# K/V LDS-DMA issue moved from the QK/PV boundary into early QK MFMA gaps (after QK MFMA 2,3,4 / 2,3); on top of v18
# speedup vs baseline: 1.0045x; 1.0045x over previous
.LBB0_863:
	v_mfma_f32_32x32x16_bf16 v[112:127], v[100:103], v[218:221], 0
	v_lshl_add_u32 v206, s89, 1, v168
	ds_read_b64_tr_b16 v[194:195], v206 offset:24576
	ds_read_b64_tr_b16 v[196:197], v206 offset:25088
	v_add_f32_e32 v108, v80, v81
	v_add_f32_e32 v108, v82, v108
	v_add_f32_e32 v108, v83, v108
	v_add_f32_e32 v108, v84, v108
	v_add_f32_e32 v108, v85, v108
	v_cvt_pk_bf16_f32 v156, v80, v81
	v_cvt_pk_bf16_f32 v157, v82, v83
	ds_read_b64_tr_b16 v[80:81], v206 offset:28672
	ds_read_b64_tr_b16 v[82:83], v206 offset:29184
	v_add_f32_e32 v104, v86, v108
	v_add_f32_e32 v104, v87, v104
	v_add_f32_e32 v104, v88, v104
	v_add_f32_e32 v144, v89, v104
	v_mfma_f32_32x32x16_bf16 v[96:111], v[96:99], v[218:221], 0
	s_add_i32 s88, s87, s35
	v_lshl_add_u64 v[238:239], v[180:181], 0, s[54:55]
	s_mov_b32 s89, m0
	s_mov_b32 m0, s88
	s_nop 0
	global_load_lds_dwordx4 v[238:239], off
	s_mov_b32 m0, s89
	v_cvt_pk_bf16_f32 v158, v84, v85
	v_cvt_pk_bf16_f32 v159, v86, v87
	ds_read_b64_tr_b16 v[84:85], v206 offset:25600
	ds_read_b64_tr_b16 v[86:87], v206 offset:26112
	v_add_f32_e32 v144, v90, v144
	v_add_f32_e32 v144, v91, v144
	v_add_f32_e32 v144, v92, v144
	v_add_f32_e32 v144, v93, v144
	v_cvt_pk_bf16_f32 v152, v88, v89
	v_cvt_pk_bf16_f32 v153, v90, v91
	v_mfma_f32_32x32x16_bf16 v[112:127], v[164:167], v[222:225], v[112:127]
	s_lshl_b32 s88, s86, 1
	v_lshl_add_u64 v[238:239], v[178:179], 0, s[54:55]
	s_add_i32 s88, s88, s16
	s_mov_b32 s89, m0
	s_mov_b32 m0, s88
	s_nop 0
	global_load_lds_dwordx4 v[238:239], off
	s_mov_b32 m0, s89
	ds_read_b64_tr_b16 v[88:89], v206 offset:29696
	ds_read_b64_tr_b16 v[90:91], v206 offset:30208
	v_add_f32_e32 v144, v94, v144
	v_add_f32_e32 v144, v95, v144
	v_add_f32_e32 v144, v64, v144
	v_add_f32_e32 v144, v65, v144
	v_mfma_f32_32x32x16_bf16 v[96:111], v[160:163], v[222:225], v[96:111]
	v_lshl_add_u64 v[238:239], v[176:177], 0, s[54:55]
	s_addk_i32 s88, 0x2000
	s_mov_b32 s89, m0
	s_mov_b32 m0, s88
	s_nop 0
	global_load_lds_dwordx4 v[238:239], off
	s_mov_b32 m0, s89
	v_cvt_pk_bf16_f32 v154, v92, v93
	v_cvt_pk_bf16_f32 v155, v94, v95
	ds_read_b64_tr_b16 v[92:93], v206 offset:26624
	ds_read_b64_tr_b16 v[94:95], v206 offset:27136
	v_add_f32_e32 v144, v66, v144
	v_add_f32_e32 v144, v67, v144
	v_add_f32_e32 v144, v68, v144
	v_add_f32_e32 v144, v69, v144
	v_cvt_pk_bf16_f32 v148, v64, v65
	v_cvt_pk_bf16_f32 v149, v66, v67
	v_mfma_f32_32x32x16_bf16 v[112:127], v[140:143], v[226:229], v[112:127]
	ds_read_b64_tr_b16 v[198:199], v206 offset:30720
	ds_read_b64_tr_b16 v[200:201], v206 offset:31232
	v_add_f32_e32 v140, v70, v144
	v_add_f32_e32 v140, v71, v140
	v_add_f32_e32 v140, v72, v140
	v_add_f32_e32 v140, v73, v140
	v_mfma_f32_32x32x16_bf16 v[96:111], v[136:139], v[226:229], v[96:111]
	v_cvt_pk_bf16_f32 v150, v68, v69
	v_cvt_pk_bf16_f32 v151, v70, v71
	ds_read_b64_tr_b16 v[202:203], v206 offset:27648
	ds_read_b64_tr_b16 v[204:205], v206 offset:28160
	v_add_f32_e32 v68, v74, v140
	v_add_f32_e32 v68, v75, v68
	v_add_f32_e32 v68, v76, v68
	v_add_f32_e32 v68, v77, v68
	v_cvt_pk_bf16_f32 v144, v72, v73
	v_cvt_pk_bf16_f32 v145, v74, v75
	v_mfma_f32_32x32x16_bf16 v[112:127], v[132:135], v[230:233], v[112:127]
	ds_read_b64_tr_b16 v[72:73], v206 offset:31744
	ds_read_b64_tr_b16 v[74:75], v206 offset:32256
	v_add_f32_e32 v68, v78, v68
	v_add_f32_e32 v68, v79, v68
	v_add_f32_e32 v68, 0, v68
	v_cvt_pk_bf16_f32 v146, v76, v77
	v_mfma_f32_32x32x16_bf16 v[96:111], v[128:131], v[230:233], v[96:111]
	v_cvt_pk_bf16_f32 v147, v78, v79
	v_add_f32_e32 v193, v193, v68
	s_waitcnt lgkmcnt(12)
	v_mfma_f32_32x32x16_bf16 v[48:63], v[156:159], v[194:197], v[48:63]
	ds_read_b64_tr_b16 v[76:77], v206 offset:32768
	ds_read_b64_tr_b16 v[78:79], v206 offset:33280
	v_exp_f32_e32 v112, v112
	v_exp_f32_e32 v113, v113
	v_mfma_f32_32x32x16_bf16 v[32:47], v[156:159], v[80:83], v[32:47]
	ds_read_b64_tr_b16 v[194:195], v206 offset:36864
	ds_read_b64_tr_b16 v[196:197], v206 offset:37376
	v_exp_f32_e32 v114, v114
	v_exp_f32_e32 v115, v115
	v_add_u32_e32 v242, s86, v234
	v_add_u32_e32 v243, s86, v235
	v_add_u32_e32 v244, s86, v236
	v_add_u32_e32 v245, s86, v237
	ds_read_b128 v[68:71], v242
	ds_read_b128 v[64:67], v242 offset:4096
	s_waitcnt lgkmcnt(14)
	v_mfma_f32_32x32x16_bf16 v[48:63], v[152:155], v[84:87], v[48:63]
	ds_read_b64_tr_b16 v[80:81], v206 offset:33792
	ds_read_b64_tr_b16 v[82:83], v206 offset:34304
	v_exp_f32_e32 v116, v116
	v_exp_f32_e32 v117, v117
	ds_read_b128 v[164:167], v243
	ds_read_b128 v[140:143], v243 offset:4096
	v_mfma_f32_32x32x16_bf16 v[32:47], v[152:155], v[88:91], v[32:47]
	ds_read_b64_tr_b16 v[84:85], v206 offset:37888
	ds_read_b64_tr_b16 v[86:87], v206 offset:38400
	v_exp_f32_e32 v118, v118
	v_exp_f32_e32 v119, v119
	ds_read_b128 v[160:163], v244
	ds_read_b128 v[132:135], v244 offset:4096
	s_waitcnt lgkmcnt(14)
	v_mfma_f32_32x32x16_bf16 v[48:63], v[148:151], v[92:95], v[48:63]
	ds_read_b64_tr_b16 v[88:89], v206 offset:34816
	ds_read_b64_tr_b16 v[90:91], v206 offset:35328
	v_exp_f32_e32 v120, v120
	v_exp_f32_e32 v121, v121
	ds_read_b128 v[136:139], v245
	ds_read_b128 v[128:131], v245 offset:4096
	v_mfma_f32_32x32x16_bf16 v[32:47], v[148:151], v[198:201], v[32:47]
	ds_read_b64_tr_b16 v[92:93], v206 offset:38912
	ds_read_b64_tr_b16 v[94:95], v206 offset:39424
	v_exp_f32_e32 v122, v122
	v_exp_f32_e32 v123, v123
	s_waitcnt lgkmcnt(14)
	v_mfma_f32_32x32x16_bf16 v[48:63], v[144:147], v[202:205], v[48:63]
	ds_read_b64_tr_b16 v[198:199], v206 offset:35840
	ds_read_b64_tr_b16 v[200:201], v206 offset:36352
	v_exp_f32_e32 v124, v124
	v_exp_f32_e32 v125, v125
	v_mfma_f32_32x32x16_bf16 v[32:47], v[144:147], v[72:75], v[32:47]
	ds_read_b64_tr_b16 v[202:203], v206 offset:39936
	ds_read_b64_tr_b16 v[204:205], v206 offset:40448
	v_exp_f32_e32 v126, v126
	v_exp_f32_e32 v127, v127
	s_waitcnt lgkmcnt(14)
	v_mfma_f32_32x32x16_bf16 v[16:31], v[156:159], v[76:79], v[16:31]
	v_exp_f32_e32 v96, v96
	v_exp_f32_e32 v97, v97
	v_mfma_f32_32x32x16_bf16 v[0:15], v[156:159], v[194:197], v[0:15]
	v_exp_f32_e32 v98, v98
	v_exp_f32_e32 v99, v99
	v_mfma_f32_32x32x16_bf16 v[16:31], v[152:155], v[80:83], v[16:31]
	v_exp_f32_e32 v100, v100
	v_exp_f32_e32 v101, v101
	s_waitcnt lgkmcnt(12)
	v_mfma_f32_32x32x16_bf16 v[0:15], v[152:155], v[84:87], v[0:15]
	v_exp_f32_e32 v102, v102
	v_exp_f32_e32 v103, v103
	s_waitcnt lgkmcnt(8)
	v_mfma_f32_32x32x16_bf16 v[16:31], v[148:151], v[88:91], v[16:31]
	v_exp_f32_e32 v104, v104
	v_exp_f32_e32 v105, v105
	s_waitcnt lgkmcnt(4)
	v_mfma_f32_32x32x16_bf16 v[0:15], v[148:151], v[92:95], v[0:15]
	v_exp_f32_e32 v106, v106
	v_exp_f32_e32 v107, v107
	s_waitcnt lgkmcnt(2)
	v_mfma_f32_32x32x16_bf16 v[16:31], v[144:147], v[198:201], v[16:31]
	v_exp_f32_e32 v108, v108
	v_exp_f32_e32 v109, v109
	s_waitcnt lgkmcnt(0)
	v_mfma_f32_32x32x16_bf16 v[0:15], v[144:147], v[202:205], v[0:15]
	v_exp_f32_e32 v110, v110
	v_exp_f32_e32 v111, v111
	s_waitcnt vmcnt(3) lgkmcnt(0)
	s_barrier
	v_mfma_f32_32x32x16_bf16 v[80:95], v[68:71], v[218:221], 0
	s_add_i32 s88, s86, 0x2000
	s_cmpk_lg_i32 s86, 0x4000
	s_cselect_b32 s88, s88, 0
	v_lshl_add_u32 v206, s87, 1, v168
	ds_read_b64_tr_b16 v[194:195], v206 offset:24576
	ds_read_b64_tr_b16 v[196:197], v206 offset:25088
	v_add_f32_e32 v76, v112, v113
	v_add_f32_e32 v76, v114, v76
	v_add_f32_e32 v76, v115, v76
	v_add_f32_e32 v76, v116, v76
	v_add_f32_e32 v76, v117, v76
	v_cvt_pk_bf16_f32 v156, v112, v113
	v_cvt_pk_bf16_f32 v157, v114, v115
	ds_read_b64_tr_b16 v[112:113], v206 offset:28672
	ds_read_b64_tr_b16 v[114:115], v206 offset:29184
	v_add_f32_e32 v72, v118, v76
	v_add_f32_e32 v72, v119, v72
	v_add_f32_e32 v72, v120, v72
	v_add_f32_e32 v144, v121, v72
	v_mfma_f32_32x32x16_bf16 v[64:79], v[64:67], v[218:221], 0
	s_add_i32 s87, s86, s35
	s_mov_b32 s89, m0
	s_mov_b32 m0, s87
	s_nop 0
	global_load_lds_dwordx4 v[180:181], off
	s_mov_b32 m0, s89
	v_cvt_pk_bf16_f32 v158, v116, v117
	v_cvt_pk_bf16_f32 v159, v118, v119
	ds_read_b64_tr_b16 v[116:117], v206 offset:25600
	ds_read_b64_tr_b16 v[118:119], v206 offset:26112
	v_add_f32_e32 v144, v122, v144
	v_add_f32_e32 v144, v123, v144
	v_add_f32_e32 v144, v124, v144
	v_add_f32_e32 v144, v125, v144
	v_mfma_f32_32x32x16_bf16 v[80:95], v[164:167], v[222:225], v[80:95]
	s_lshl_b32 s87, s88, 1
	s_add_i32 s87, s87, s16
	s_mov_b32 s89, m0
	s_mov_b32 m0, s87
	s_nop 0
	global_load_lds_dwordx4 v[178:179], off
	s_mov_b32 m0, s89
	v_cvt_pk_bf16_f32 v152, v120, v121
	v_cvt_pk_bf16_f32 v153, v122, v123
	ds_read_b64_tr_b16 v[120:121], v206 offset:29696
	ds_read_b64_tr_b16 v[122:123], v206 offset:30208
	v_add_f32_e32 v144, v126, v144
	v_add_f32_e32 v144, v127, v144
	v_add_f32_e32 v144, v96, v144
	v_add_f32_e32 v144, v97, v144
	v_mfma_f32_32x32x16_bf16 v[64:79], v[140:143], v[222:225], v[64:79]
	s_addk_i32 s87, 0x2000
	s_mov_b32 s89, m0
	s_mov_b32 m0, s87
	s_nop 0
	global_load_lds_dwordx4 v[176:177], off
	s_mov_b32 m0, s89
	v_cvt_pk_bf16_f32 v154, v124, v125
	v_cvt_pk_bf16_f32 v155, v126, v127
	ds_read_b64_tr_b16 v[124:125], v206 offset:26624
	ds_read_b64_tr_b16 v[126:127], v206 offset:27136
	v_add_f32_e32 v144, v98, v144
	v_add_f32_e32 v144, v99, v144
	v_add_f32_e32 v144, v100, v144
	v_add_f32_e32 v144, v101, v144
	v_mfma_f32_32x32x16_bf16 v[80:95], v[160:163], v[226:229], v[80:95]
	v_cvt_pk_bf16_f32 v148, v96, v97
	v_cvt_pk_bf16_f32 v149, v98, v99
	ds_read_b64_tr_b16 v[198:199], v206 offset:30720
	ds_read_b64_tr_b16 v[200:201], v206 offset:31232
	v_add_f32_e32 v140, v102, v144
	v_add_f32_e32 v140, v103, v140
	v_add_f32_e32 v140, v104, v140
	v_add_f32_e32 v140, v105, v140
	v_mfma_f32_32x32x16_bf16 v[64:79], v[132:135], v[226:229], v[64:79]
	v_cvt_pk_bf16_f32 v150, v100, v101
	v_cvt_pk_bf16_f32 v151, v102, v103
	ds_read_b64_tr_b16 v[202:203], v206 offset:27648
	ds_read_b64_tr_b16 v[204:205], v206 offset:28160
	v_add_f32_e32 v100, v106, v140
	v_add_f32_e32 v100, v107, v100
	v_add_f32_e32 v100, v108, v100
	v_add_f32_e32 v100, v109, v100
	v_mfma_f32_32x32x16_bf16 v[80:95], v[136:139], v[230:233], v[80:95]
	v_cvt_pk_bf16_f32 v144, v104, v105
	v_cvt_pk_bf16_f32 v145, v106, v107
	ds_read_b64_tr_b16 v[104:105], v206 offset:31744
	ds_read_b64_tr_b16 v[106:107], v206 offset:32256
	v_add_f32_e32 v100, v110, v100
	v_add_f32_e32 v100, v111, v100
	v_add_f32_e32 v100, 0, v100
	v_cvt_pk_bf16_f32 v146, v108, v109
	v_mfma_f32_32x32x16_bf16 v[64:79], v[128:131], v[230:233], v[64:79]
	v_cvt_pk_bf16_f32 v147, v110, v111
	v_add_f32_e32 v193, v193, v100
	s_waitcnt lgkmcnt(12)
	v_mfma_f32_32x32x16_bf16 v[48:63], v[156:159], v[194:197], v[48:63]
	ds_read_b64_tr_b16 v[108:109], v206 offset:32768
	ds_read_b64_tr_b16 v[110:111], v206 offset:33280
	v_exp_f32_e32 v80, v80
	v_exp_f32_e32 v81, v81
	v_mfma_f32_32x32x16_bf16 v[32:47], v[156:159], v[112:115], v[32:47]
	ds_read_b64_tr_b16 v[194:195], v206 offset:36864
	ds_read_b64_tr_b16 v[196:197], v206 offset:37376
	v_exp_f32_e32 v82, v82
	v_exp_f32_e32 v83, v83
	v_add_u32_e32 v242, s88, v234
	v_add_u32_e32 v243, s88, v235
	v_add_u32_e32 v244, s88, v236
	v_add_u32_e32 v245, s88, v237
	ds_read_b128 v[100:103], v242
	ds_read_b128 v[96:99], v242 offset:4096
	s_waitcnt lgkmcnt(14)
	v_mfma_f32_32x32x16_bf16 v[48:63], v[152:155], v[116:119], v[48:63]
	ds_read_b64_tr_b16 v[112:113], v206 offset:33792
	ds_read_b64_tr_b16 v[114:115], v206 offset:34304
	v_exp_f32_e32 v84, v84
	v_exp_f32_e32 v85, v85
	ds_read_b128 v[164:167], v243
	ds_read_b128 v[160:163], v243 offset:4096
	v_mfma_f32_32x32x16_bf16 v[32:47], v[152:155], v[120:123], v[32:47]
	ds_read_b64_tr_b16 v[116:117], v206 offset:37888
	ds_read_b64_tr_b16 v[118:119], v206 offset:38400
	v_exp_f32_e32 v86, v86
	v_exp_f32_e32 v87, v87
	ds_read_b128 v[140:143], v244
	ds_read_b128 v[136:139], v244 offset:4096
	s_waitcnt lgkmcnt(14)
	v_mfma_f32_32x32x16_bf16 v[48:63], v[148:151], v[124:127], v[48:63]
	ds_read_b64_tr_b16 v[120:121], v206 offset:34816
	ds_read_b64_tr_b16 v[122:123], v206 offset:35328
	v_exp_f32_e32 v88, v88
	v_exp_f32_e32 v89, v89
	ds_read_b128 v[132:135], v245
	ds_read_b128 v[128:131], v245 offset:4096
	v_mfma_f32_32x32x16_bf16 v[32:47], v[148:151], v[198:201], v[32:47]
	ds_read_b64_tr_b16 v[124:125], v206 offset:38912
	ds_read_b64_tr_b16 v[126:127], v206 offset:39424
	v_exp_f32_e32 v90, v90
	v_exp_f32_e32 v91, v91
	s_waitcnt lgkmcnt(14)
	v_mfma_f32_32x32x16_bf16 v[48:63], v[144:147], v[202:205], v[48:63]
	ds_read_b64_tr_b16 v[198:199], v206 offset:35840
	ds_read_b64_tr_b16 v[200:201], v206 offset:36352
	v_exp_f32_e32 v92, v92
	v_exp_f32_e32 v93, v93
	v_mfma_f32_32x32x16_bf16 v[32:47], v[144:147], v[104:107], v[32:47]
	ds_read_b64_tr_b16 v[202:203], v206 offset:39936
	ds_read_b64_tr_b16 v[204:205], v206 offset:40448
	v_exp_f32_e32 v94, v94
	v_exp_f32_e32 v95, v95
	s_waitcnt lgkmcnt(14)
	v_mfma_f32_32x32x16_bf16 v[16:31], v[156:159], v[108:111], v[16:31]
	v_exp_f32_e32 v64, v64
	v_exp_f32_e32 v65, v65
	v_mfma_f32_32x32x16_bf16 v[0:15], v[156:159], v[194:197], v[0:15]
	v_exp_f32_e32 v66, v66
	v_exp_f32_e32 v67, v67
	v_mfma_f32_32x32x16_bf16 v[16:31], v[152:155], v[112:115], v[16:31]
	v_exp_f32_e32 v68, v68
	v_exp_f32_e32 v69, v69
	s_waitcnt lgkmcnt(12)
	v_mfma_f32_32x32x16_bf16 v[0:15], v[152:155], v[116:119], v[0:15]
	v_exp_f32_e32 v70, v70
	v_exp_f32_e32 v71, v71
	s_waitcnt lgkmcnt(8)
	v_mfma_f32_32x32x16_bf16 v[16:31], v[148:151], v[120:123], v[16:31]
	v_exp_f32_e32 v72, v72
	v_exp_f32_e32 v73, v73
	s_waitcnt lgkmcnt(4)
	v_mfma_f32_32x32x16_bf16 v[0:15], v[148:151], v[124:127], v[0:15]
	v_exp_f32_e32 v74, v74
	v_exp_f32_e32 v75, v75
	s_waitcnt lgkmcnt(2)
	v_mfma_f32_32x32x16_bf16 v[16:31], v[144:147], v[198:201], v[16:31]
	v_exp_f32_e32 v76, v76
	v_exp_f32_e32 v77, v77
	s_waitcnt lgkmcnt(0)
	v_mfma_f32_32x32x16_bf16 v[0:15], v[144:147], v[202:205], v[0:15]
	v_exp_f32_e32 v78, v78
	v_exp_f32_e32 v79, v79
	s_add_i32 s90, s88, 0x2000
	s_waitcnt vmcnt(3) lgkmcnt(0)
	s_barrier
; #define WAIT_BAR(N) asm volatile("s_waitcnt vmcnt(" #N ") lgkmcnt(0)\n\ts_barrier":::"memory")
;   #define RESC() do{ if(!NOMAX&&resc){ asm volatile("s_waitcnt lgkmcnt(0)":::"memory"); \
;       _Pragma("unroll") for(int d_=0;d_<2*VM;++d_) _Pragma("unroll") for(int r=0;r<16;++r)o[d_][r]*=wsf[crow(r,hi)]; } }while(0)
;   #define ROT() do{sl_prev=sl_cur;sl_cur=sl_next;sl_next=(sl_next==(NSLOT-1)*SLOTB)?0:sl_next+SLOTB;}while(0)
;   #define ENDW(tt) do{ if((tt)+3<NT){ if constexpr(VM==2){WAIT_BAR(3);}else{WAIT_BAR(2);} } else if((tt)+2<NT){ if constexpr(VM==2){WAIT_BAR(2);}else{WAIT_BAR(1);} } else {WAIT_BAR(0);} }while(0)
; template<int THRL,int VM,bool NOMAX> __device__ __forceinline__ void attn_unit(const bf16*Qb,const bf16*__restrict__ Kh,const bf16*__restrict__ Vh,bf16*Ob,const int NT,const int sp,float*wscr,char*shm){
;     ...
;   for(;t+5<NT;t+=2){
;     STEP(pB0,pB1,pA0,pA1,t,true,true,true);     if constexpr(VM==2){WAIT_BAR(3);}else{WAIT_BAR(2);} RESC(); ROT();
;     STEP(pA0,pA1,pB0,pB1,t+1,true,true,true);   if constexpr(VM==2){WAIT_BAR(3);}else{WAIT_BAR(2);} RESC(); ROT();
;   }
;     ...
;   for(;t+1<NT;t+=2){
;     STEP(pB0,pB1,pA0,pA1,t,(t+3<NT),(t+1<NT),(t+1<NT));       ENDW(t);   RESC(); ROT();
	s_cmpk_lg_i32 s88, 0x4000
	s_mov_b32 s89, s86
	s_cselect_b32 s86, s90, 0
	s_add_i32 s85, s85, 2
	v_lshl_add_u64 v[176:177], v[176:177], 0, s[56:57]
	v_lshl_add_u64 v[178:179], v[178:179], 0, s[56:57]
	v_lshl_add_u64 v[180:181], v[180:181], 0, s[56:57]
	s_mov_b32 s87, s88
	s_cmpk_lt_u32 s85, 0x79
	s_cbranch_scc1 .LBB0_863
	s_and_b32 s34, s34, 0x3fffffc0
	s_lshl_b32 s34, s34, 2
	s_add_i32 s34, s34, 0
	s_add_i32 s34, s34, 0x12000
	s_cmp_lg_u32 0, -1
	s_cselect_b32 s85, 0, 0
	s_add_i32 s86, s85, 0x6000
	v_add_u32_e32 v104, s86, v191
	v_add3_u32 v176, v104, v190, v192
	v_add_u32_e32 v177, 0x6000, v168
	ds_read_b64_tr_b16 v[178:179], v168 offset:57344
	ds_read_b64_tr_b16 v[180:181], v168 offset:57856
	v_add_f32_e32 v108, v80, v81
	ds_read_b128 v[104:107], v188
	v_add_f32_e32 v108, v82, v108
	v_add_f32_e32 v108, v83, v108
	v_add_f32_e32 v108, v84, v108
	v_add_f32_e32 v108, v85, v108
	v_cvt_pk_bf16_f32 v156, v80, v81
	v_cvt_pk_bf16_f32 v157, v82, v83
	s_waitcnt lgkmcnt(0)
	v_mfma_f32_32x32x16_bf16 v[112:127], v[100:103], v[104:107], 0
	ds_read_b64_tr_b16 v[80:81], v168 offset:61440
	ds_read_b64_tr_b16 v[82:83], v168 offset:61952
	ds_read_b128 v[100:103], v188
	v_add_f32_e32 v104, v86, v108
	v_add_f32_e32 v104, v87, v104
	v_add_f32_e32 v104, v88, v104
	v_add_f32_e32 v144, v89, v104
	v_cvt_pk_bf16_f32 v158, v84, v85
	v_cvt_pk_bf16_f32 v159, v86, v87
	s_waitcnt lgkmcnt(0)
	v_mfma_f32_32x32x16_bf16 v[96:111], v[96:99], v[100:103], 0
	ds_read_b64_tr_b16 v[84:85], v168 offset:58368
	ds_read_b64_tr_b16 v[86:87], v168 offset:58880
	ds_read_b128 v[194:197], v188 offset:1024
	v_add_f32_e32 v144, v90, v144
	v_add_f32_e32 v144, v91, v144
	v_add_f32_e32 v144, v92, v144
	v_add_f32_e32 v144, v93, v144
	v_cvt_pk_bf16_f32 v152, v88, v89
	v_cvt_pk_bf16_f32 v153, v90, v91
	s_waitcnt lgkmcnt(0)
	v_mfma_f32_32x32x16_bf16 v[112:127], v[164:167], v[194:197], v[112:127]
	ds_read_b64_tr_b16 v[88:89], v168 offset:62464
	ds_read_b64_tr_b16 v[90:91], v168 offset:62976
	ds_read_b128 v[164:167], v188 offset:1024
	v_add_f32_e32 v144, v94, v144
	v_add_f32_e32 v144, v95, v144
	v_add_f32_e32 v144, v64, v144
	v_add_f32_e32 v144, v65, v144
	v_cvt_pk_bf16_f32 v154, v92, v93
	v_cvt_pk_bf16_f32 v155, v94, v95
	s_waitcnt lgkmcnt(0)
	v_mfma_f32_32x32x16_bf16 v[96:111], v[160:163], v[164:167], v[96:111]
	ds_read_b64_tr_b16 v[194:195], v168 offset:59392
	ds_read_b64_tr_b16 v[196:197], v168 offset:59904
	ds_read_b128 v[92:95], v188 offset:2048
	v_add_f32_e32 v144, v66, v144
	v_add_f32_e32 v144, v67, v144
	v_add_f32_e32 v144, v68, v144
	v_add_f32_e32 v144, v69, v144
	v_cvt_pk_bf16_f32 v148, v64, v65
	v_cvt_pk_bf16_f32 v149, v66, v67
	s_waitcnt lgkmcnt(0)
	v_mfma_f32_32x32x16_bf16 v[112:127], v[140:143], v[92:95], v[112:127]
	ds_read_b64_tr_b16 v[140:141], v168 offset:63488
	ds_read_b64_tr_b16 v[142:143], v168 offset:64000
	ds_read_b128 v[64:67], v188 offset:2048
	v_add_f32_e32 v92, v70, v144
	v_add_f32_e32 v92, v71, v92
	v_add_f32_e32 v92, v72, v92
	v_add_f32_e32 v92, v73, v92
	v_cvt_pk_bf16_f32 v150, v68, v69
	v_cvt_pk_bf16_f32 v151, v70, v71
	s_waitcnt lgkmcnt(0)
	v_mfma_f32_32x32x16_bf16 v[96:111], v[136:139], v[64:67], v[96:111]
	ds_read_b64_tr_b16 v[136:137], v168 offset:60416
	ds_read_b64_tr_b16 v[138:139], v168 offset:60928
	ds_read_b128 v[64:67], v188 offset:3072
	v_add_f32_e32 v68, v74, v92
	v_add_f32_e32 v68, v75, v68
	v_add_f32_e32 v68, v76, v68
	v_add_f32_e32 v68, v77, v68
	v_cvt_pk_bf16_f32 v144, v72, v73
	v_cvt_pk_bf16_f32 v145, v74, v75
	s_waitcnt lgkmcnt(0)
	v_mfma_f32_32x32x16_bf16 v[112:127], v[132:135], v[64:67], v[112:127]
	ds_read_b64_tr_b16 v[72:73], v168 offset:64512
	ds_read_b64_tr_b16 v[74:75], v168 offset:65024
	ds_read_b128 v[64:67], v188 offset:3072
	v_add_f32_e32 v68, v78, v68
	v_add_f32_e32 v68, v79, v68
	v_add_f32_e32 v68, 0, v68
	v_cvt_pk_bf16_f32 v146, v76, v77
	v_cvt_pk_bf16_f32 v147, v78, v79
	s_waitcnt lgkmcnt(0)
	v_mfma_f32_32x32x16_bf16 v[96:111], v[128:131], v[64:67], v[96:111]
	v_lshl_add_u64 v[64:65], v[174:175], 0, s[58:59]
	s_mov_b32 s86, m0
	s_mov_b32 m0, s35
	s_nop 0
	global_load_lds_dwordx4 v[64:65], off
	s_mov_b32 m0, s86
	s_add_i32 s85, s85, s17
	v_lshl_add_u64 v[64:65], v[170:171], 0, s[60:61]
	s_add_i32 s17, s85, 0xa000
	s_mov_b32 s35, m0
	s_mov_b32 m0, s17
	s_nop 0
	global_load_lds_dwordx4 v[64:65], off
	s_mov_b32 m0, s35
	v_lshl_add_u64 v[64:65], v[172:173], 0, s[60:61]
	s_add_i32 s35, s17, 0x2000
	s_mov_b32 s86, m0
	s_mov_b32 m0, s35
	s_nop 0
	global_load_lds_dwordx4 v[64:65], off
	s_mov_b32 m0, s86
	v_add_f32_e32 v198, v193, v68
	v_mfma_f32_32x32x16_bf16 v[48:63], v[156:159], v[178:181], v[48:63]
	ds_read_b64_tr_b16 v[76:77], v177 offset:40960
	ds_read_b64_tr_b16 v[78:79], v177 offset:41472
	v_exp_f32_e32 v112, v112
	v_exp_f32_e32 v113, v113
	v_mfma_f32_32x32x16_bf16 v[32:47], v[156:159], v[80:83], v[32:47]
	ds_read_b64_tr_b16 v[128:129], v177 offset:45056
	ds_read_b64_tr_b16 v[130:131], v177 offset:45568
	v_exp_f32_e32 v114, v114
	v_exp_f32_e32 v115, v115
	ds_read_b128 v[68:71], v234 offset:8192
	ds_read_b128 v[64:67], v234 offset:12288
	v_mfma_f32_32x32x16_bf16 v[48:63], v[152:155], v[84:87], v[48:63]
	ds_read_b64_tr_b16 v[132:133], v177 offset:41984
	ds_read_b64_tr_b16 v[134:135], v177 offset:42496
	v_exp_f32_e32 v116, v116
	v_exp_f32_e32 v117, v117
	ds_read_b128 v[164:167], v235 offset:8192
	ds_read_b128 v[92:95], v235 offset:12288
	v_mfma_f32_32x32x16_bf16 v[32:47], v[152:155], v[88:91], v[32:47]
	ds_read_b64_tr_b16 v[178:179], v177 offset:46080
	ds_read_b64_tr_b16 v[180:181], v177 offset:46592
	v_exp_f32_e32 v118, v118
	v_exp_f32_e32 v119, v119
	ds_read_b128 v[160:163], v236 offset:8192
	ds_read_b128 v[84:87], v236 offset:12288
	v_mfma_f32_32x32x16_bf16 v[48:63], v[148:151], v[194:197], v[48:63]
	ds_read_b64_tr_b16 v[190:191], v177 offset:43008
	ds_read_b64_tr_b16 v[192:193], v177 offset:43520
	v_exp_f32_e32 v120, v120
	v_exp_f32_e32 v121, v121
	ds_read_b128 v[88:91], v237 offset:8192
	ds_read_b128 v[80:83], v237 offset:12288
	v_mfma_f32_32x32x16_bf16 v[32:47], v[148:151], v[140:143], v[32:47]
	ds_read_b64_tr_b16 v[194:195], v177 offset:47104
	ds_read_b64_tr_b16 v[196:197], v177 offset:47616
	v_exp_f32_e32 v122, v122
	v_exp_f32_e32 v123, v123
	v_mfma_f32_32x32x16_bf16 v[48:63], v[144:147], v[136:139], v[48:63]
	ds_read_b64_tr_b16 v[140:141], v177 offset:44032
	ds_read_b64_tr_b16 v[142:143], v177 offset:44544
	v_exp_f32_e32 v124, v124
	v_exp_f32_e32 v125, v125
	v_mfma_f32_32x32x16_bf16 v[32:47], v[144:147], v[72:75], v[32:47]
	ds_read_b64_tr_b16 v[136:137], v177 offset:48128
	ds_read_b64_tr_b16 v[138:139], v177 offset:48640
	v_exp_f32_e32 v126, v126
	v_exp_f32_e32 v127, v127
	s_waitcnt lgkmcnt(14)
	v_mfma_f32_32x32x16_bf16 v[16:31], v[156:159], v[76:79], v[16:31]
	v_exp_f32_e32 v96, v96
	v_exp_f32_e32 v97, v97
	v_mfma_f32_32x32x16_bf16 v[0:15], v[156:159], v[128:131], v[0:15]
	v_exp_f32_e32 v98, v98
	v_exp_f32_e32 v99, v99
	v_mfma_f32_32x32x16_bf16 v[16:31], v[152:155], v[132:135], v[16:31]
	v_exp_f32_e32 v100, v100
	v_exp_f32_e32 v101, v101
	s_waitcnt lgkmcnt(12)
	v_mfma_f32_32x32x16_bf16 v[0:15], v[152:155], v[178:181], v[0:15]
	v_exp_f32_e32 v102, v102
	v_exp_f32_e32 v103, v103
	s_waitcnt lgkmcnt(8)
	v_mfma_f32_32x32x16_bf16 v[16:31], v[148:151], v[190:193], v[16:31]
	v_exp_f32_e32 v104, v104
	v_exp_f32_e32 v105, v105
	s_waitcnt lgkmcnt(4)
	v_mfma_f32_32x32x16_bf16 v[0:15], v[148:151], v[194:197], v[0:15]
	v_exp_f32_e32 v106, v106
	v_exp_f32_e32 v107, v107
	s_waitcnt lgkmcnt(2)
	v_mfma_f32_32x32x16_bf16 v[16:31], v[144:147], v[140:143], v[16:31]
	v_exp_f32_e32 v108, v108
	v_exp_f32_e32 v109, v109
	s_waitcnt lgkmcnt(0)
	v_mfma_f32_32x32x16_bf16 v[0:15], v[144:147], v[136:139], v[0:15]
	v_exp_f32_e32 v110, v110
	v_exp_f32_e32 v111, v111
	s_waitcnt vmcnt(3) lgkmcnt(0)
	s_barrier
	ds_read_b64_tr_b16 v[178:179], v168 offset:24576
	ds_read_b64_tr_b16 v[180:181], v168 offset:25088
	v_add_f32_e32 v76, v112, v113
	ds_read_b128 v[72:75], v188
	v_add_f32_e32 v76, v114, v76
	v_add_f32_e32 v76, v115, v76
	v_add_f32_e32 v76, v116, v76
	v_add_f32_e32 v76, v117, v76
	v_cvt_pk_bf16_f32 v156, v112, v113
	v_cvt_pk_bf16_f32 v157, v114, v115
	s_waitcnt lgkmcnt(0)
	v_mfma_f32_32x32x16_bf16 v[128:143], v[68:71], v[72:75], 0
	ds_read_b64_tr_b16 v[112:113], v168 offset:28672
	ds_read_b64_tr_b16 v[114:115], v168 offset:29184
	ds_read_b128 v[68:71], v188
	v_add_f32_e32 v72, v118, v76
	v_add_f32_e32 v72, v119, v72
	v_add_f32_e32 v72, v120, v72
	v_add_f32_e32 v144, v121, v72
	s_waitcnt lgkmcnt(0)
	v_mfma_f32_32x32x16_bf16 v[64:79], v[64:67], v[68:71], 0
	v_cvt_pk_bf16_f32 v158, v116, v117
	v_cvt_pk_bf16_f32 v159, v118, v119
	ds_read_b64_tr_b16 v[116:117], v168 offset:25600
	ds_read_b64_tr_b16 v[118:119], v168 offset:26112
	ds_read_b128 v[190:193], v188 offset:1024
	v_add_f32_e32 v144, v122, v144
	v_add_f32_e32 v144, v123, v144
	v_add_f32_e32 v144, v124, v144
	v_add_f32_e32 v144, v125, v144
	v_cvt_pk_bf16_f32 v152, v120, v121
	v_cvt_pk_bf16_f32 v153, v122, v123
	s_waitcnt lgkmcnt(0)
	v_mfma_f32_32x32x16_bf16 v[128:143], v[164:167], v[190:193], v[128:143]
	ds_read_b64_tr_b16 v[120:121], v168 offset:29696
	ds_read_b64_tr_b16 v[122:123], v168 offset:30208
	ds_read_b128 v[164:167], v188 offset:1024
	v_add_f32_e32 v144, v126, v144
	v_add_f32_e32 v144, v127, v144
	v_add_f32_e32 v144, v96, v144
	v_add_f32_e32 v144, v97, v144
	s_waitcnt lgkmcnt(0)
	v_mfma_f32_32x32x16_bf16 v[64:79], v[92:95], v[164:167], v[64:79]
	v_cvt_pk_bf16_f32 v154, v124, v125
	v_cvt_pk_bf16_f32 v155, v126, v127
	ds_read_b64_tr_b16 v[92:93], v168 offset:26624
	ds_read_b64_tr_b16 v[94:95], v168 offset:27136
	ds_read_b128 v[124:127], v188 offset:2048
	v_add_f32_e32 v144, v98, v144
	v_add_f32_e32 v144, v99, v144
	v_add_f32_e32 v144, v100, v144
	v_add_f32_e32 v144, v101, v144
	v_cvt_pk_bf16_f32 v148, v96, v97
	v_cvt_pk_bf16_f32 v149, v98, v99
	s_waitcnt lgkmcnt(0)
	v_mfma_f32_32x32x16_bf16 v[128:143], v[160:163], v[124:127], v[128:143]
	ds_read_b64_tr_b16 v[96:97], v168 offset:30720
	ds_read_b64_tr_b16 v[98:99], v168 offset:31232
	ds_read_b128 v[124:127], v188 offset:2048
	v_add_f32_e32 v144, v102, v144
	v_add_f32_e32 v144, v103, v144
	v_add_f32_e32 v144, v104, v144
	v_add_f32_e32 v144, v105, v144
	s_waitcnt lgkmcnt(0)
	v_mfma_f32_32x32x16_bf16 v[64:79], v[84:87], v[124:127], v[64:79]
	v_cvt_pk_bf16_f32 v150, v100, v101
	v_cvt_pk_bf16_f32 v151, v102, v103
	ds_read_b64_tr_b16 v[100:101], v168 offset:27648
	ds_read_b64_tr_b16 v[102:103], v168 offset:28160
	ds_read_b128 v[84:87], v188 offset:3072
	v_add_f32_e32 v124, v106, v144
	v_add_f32_e32 v124, v107, v124
	v_add_f32_e32 v124, v108, v124
	v_add_f32_e32 v124, v109, v124
	v_cvt_pk_bf16_f32 v144, v104, v105
	v_cvt_pk_bf16_f32 v145, v106, v107
	s_waitcnt lgkmcnt(0)
	v_mfma_f32_32x32x16_bf16 v[128:143], v[88:91], v[84:87], v[128:143]
	ds_read_b64_tr_b16 v[88:89], v168 offset:31744
	ds_read_b64_tr_b16 v[90:91], v168 offset:32256
	ds_read_b128 v[84:87], v188 offset:3072
	v_add_f32_e32 v104, v110, v124
	v_add_f32_e32 v104, v111, v104
	v_add_f32_e32 v104, 0, v104
	v_cvt_pk_bf16_f32 v146, v108, v109
	s_waitcnt lgkmcnt(0)
	v_mfma_f32_32x32x16_bf16 v[64:79], v[80:83], v[84:87], v[64:79]
	v_cvt_pk_bf16_f32 v147, v110, v111
	v_lshl_add_u64 v[80:81], v[174:175], 0, s[62:63]
	s_add_i32 s86, s85, 0x2000
	s_mov_b32 s87, m0
	s_mov_b32 m0, s86
	s_nop 0
	global_load_lds_dwordx4 v[80:81], off
	s_mov_b32 m0, s87
	v_lshl_add_u64 v[80:81], v[170:171], 0, s[64:65]
	s_add_i32 s86, s85, 0xe000
	s_mov_b32 s87, m0
	s_mov_b32 m0, s86
	s_nop 0
	global_load_lds_dwordx4 v[80:81], off
	s_mov_b32 m0, s87
	v_lshl_add_u64 v[80:81], v[172:173], 0, s[64:65]
	s_add_i32 s85, s85, 0x10000
	s_mov_b32 s86, m0
	s_mov_b32 m0, s85
	s_nop 0
	global_load_lds_dwordx4 v[80:81], off
	s_mov_b32 m0, s86
	v_add_f32_e32 v198, v198, v104
	v_mfma_f32_32x32x16_bf16 v[48:63], v[156:159], v[178:181], v[48:63]
	ds_read_b64_tr_b16 v[104:105], v168 offset:32768
	ds_read_b64_tr_b16 v[106:107], v168 offset:33280
	v_exp_f32_e32 v128, v128
	v_exp_f32_e32 v129, v129
	v_mfma_f32_32x32x16_bf16 v[32:47], v[156:159], v[112:115], v[32:47]
	ds_read_b64_tr_b16 v[108:109], v168 offset:36864
	ds_read_b64_tr_b16 v[110:111], v168 offset:37376
	v_exp_f32_e32 v130, v130
	v_exp_f32_e32 v131, v131
	ds_read_b128 v[84:87], v234 offset:16384
	ds_read_b128 v[80:83], v234 offset:20480
	v_mfma_f32_32x32x16_bf16 v[48:63], v[152:155], v[116:119], v[48:63]
	ds_read_b64_tr_b16 v[178:179], v168 offset:33792
	ds_read_b64_tr_b16 v[180:181], v168 offset:34304
	v_exp_f32_e32 v132, v132
	v_exp_f32_e32 v133, v133
	ds_read_b128 v[164:167], v235 offset:16384
	ds_read_b128 v[124:127], v235 offset:20480
	v_mfma_f32_32x32x16_bf16 v[32:47], v[152:155], v[120:123], v[32:47]
	ds_read_b64_tr_b16 v[190:191], v168 offset:37888
	ds_read_b64_tr_b16 v[192:193], v168 offset:38400
	v_exp_f32_e32 v134, v134
	v_exp_f32_e32 v135, v135
	ds_read_b128 v[160:163], v236 offset:16384
	ds_read_b128 v[116:119], v236 offset:20480
	v_mfma_f32_32x32x16_bf16 v[48:63], v[148:151], v[92:95], v[48:63]
	ds_read_b64_tr_b16 v[194:195], v168 offset:34816
	ds_read_b64_tr_b16 v[196:197], v168 offset:35328
	v_exp_f32_e32 v136, v136
	v_exp_f32_e32 v137, v137
	ds_read_b128 v[120:123], v237 offset:16384
	ds_read_b128 v[112:115], v237 offset:20480
	v_mfma_f32_32x32x16_bf16 v[32:47], v[148:151], v[96:99], v[32:47]
	ds_read_b64_tr_b16 v[92:93], v168 offset:38912
	ds_read_b64_tr_b16 v[94:95], v168 offset:39424
	v_exp_f32_e32 v138, v138
	v_exp_f32_e32 v139, v139
	v_mfma_f32_32x32x16_bf16 v[48:63], v[144:147], v[100:103], v[48:63]
	ds_read_b64_tr_b16 v[96:97], v168 offset:35840
	ds_read_b64_tr_b16 v[98:99], v168 offset:36352
	v_exp_f32_e32 v140, v140
	v_exp_f32_e32 v141, v141
	v_mfma_f32_32x32x16_bf16 v[32:47], v[144:147], v[88:91], v[32:47]
	ds_read_b64_tr_b16 v[100:101], v168 offset:39936
	ds_read_b64_tr_b16 v[102:103], v168 offset:40448
	v_exp_f32_e32 v142, v142
	v_exp_f32_e32 v143, v143
	s_waitcnt lgkmcnt(14)
	v_mfma_f32_32x32x16_bf16 v[16:31], v[156:159], v[104:107], v[16:31]
	v_exp_f32_e32 v64, v64
	v_exp_f32_e32 v65, v65
	v_mfma_f32_32x32x16_bf16 v[0:15], v[156:159], v[108:111], v[0:15]
	v_exp_f32_e32 v66, v66
	v_exp_f32_e32 v67, v67
	v_mfma_f32_32x32x16_bf16 v[16:31], v[152:155], v[178:181], v[16:31]
	v_exp_f32_e32 v68, v68
	v_exp_f32_e32 v69, v69
	s_waitcnt lgkmcnt(12)
	v_mfma_f32_32x32x16_bf16 v[0:15], v[152:155], v[190:193], v[0:15]
	v_exp_f32_e32 v70, v70
	v_exp_f32_e32 v71, v71
	s_waitcnt lgkmcnt(8)
	v_mfma_f32_32x32x16_bf16 v[16:31], v[148:151], v[194:197], v[16:31]
	v_exp_f32_e32 v72, v72
	v_exp_f32_e32 v73, v73
	s_waitcnt lgkmcnt(4)
	v_mfma_f32_32x32x16_bf16 v[0:15], v[148:151], v[92:95], v[0:15]
	v_exp_f32_e32 v74, v74
	v_exp_f32_e32 v75, v75
	s_waitcnt lgkmcnt(2)
	v_mfma_f32_32x32x16_bf16 v[16:31], v[144:147], v[96:99], v[16:31]
	v_exp_f32_e32 v76, v76
	v_exp_f32_e32 v77, v77
	s_waitcnt lgkmcnt(0)
	v_mfma_f32_32x32x16_bf16 v[0:15], v[144:147], v[100:103], v[0:15]
	v_exp_f32_e32 v78, v78
	v_exp_f32_e32 v79, v79
	s_waitcnt vmcnt(3) lgkmcnt(0)
	s_barrier
	ds_read_b64_tr_b16 v[178:179], v168 offset:40960
	ds_read_b64_tr_b16 v[180:181], v168 offset:41472
	v_add_f32_e32 v92, v128, v129
	ds_read_b128 v[88:91], v188
	v_add_f32_e32 v92, v130, v92
	v_add_f32_e32 v92, v131, v92
	v_add_f32_e32 v92, v132, v92
	v_add_f32_e32 v92, v133, v92
	v_cvt_pk_bf16_f32 v156, v128, v129
	v_cvt_pk_bf16_f32 v157, v130, v131
	s_waitcnt lgkmcnt(0)
	v_mfma_f32_32x32x16_bf16 v[96:111], v[84:87], v[88:91], 0
	ds_read_b64_tr_b16 v[128:129], v168 offset:45056
	ds_read_b64_tr_b16 v[130:131], v168 offset:45568
	ds_read_b128 v[84:87], v188
	v_add_f32_e32 v88, v134, v92
	v_add_f32_e32 v88, v135, v88
	v_add_f32_e32 v88, v136, v88
	v_add_f32_e32 v144, v137, v88
	v_cvt_pk_bf16_f32 v158, v132, v133
	v_cvt_pk_bf16_f32 v159, v134, v135
	s_waitcnt lgkmcnt(0)
	v_mfma_f32_32x32x16_bf16 v[80:95], v[80:83], v[84:87], 0
	ds_read_b64_tr_b16 v[132:133], v168 offset:41984
	ds_read_b64_tr_b16 v[134:135], v168 offset:42496
	ds_read_b128 v[190:193], v188 offset:1024
	v_add_f32_e32 v144, v138, v144
	v_add_f32_e32 v144, v139, v144
	v_add_f32_e32 v144, v140, v144
	v_add_f32_e32 v144, v141, v144
	v_cvt_pk_bf16_f32 v152, v136, v137
	v_cvt_pk_bf16_f32 v153, v138, v139
	s_waitcnt lgkmcnt(0)
	v_mfma_f32_32x32x16_bf16 v[96:111], v[164:167], v[190:193], v[96:111]
	ds_read_b64_tr_b16 v[136:137], v168 offset:46080
	ds_read_b64_tr_b16 v[138:139], v168 offset:46592
	ds_read_b128 v[164:167], v188 offset:1024
	v_add_f32_e32 v144, v142, v144
	v_add_f32_e32 v144, v143, v144
	v_add_f32_e32 v144, v64, v144
	v_add_f32_e32 v144, v65, v144
	v_cvt_pk_bf16_f32 v154, v140, v141
	v_cvt_pk_bf16_f32 v155, v142, v143
	s_waitcnt lgkmcnt(0)
	v_mfma_f32_32x32x16_bf16 v[80:95], v[124:127], v[164:167], v[80:95]
	ds_read_b64_tr_b16 v[124:125], v168 offset:43008
	ds_read_b64_tr_b16 v[126:127], v168 offset:43520
	ds_read_b128 v[140:143], v188 offset:2048
	v_add_f32_e32 v144, v66, v144
	v_add_f32_e32 v144, v67, v144
	v_add_f32_e32 v144, v68, v144
	v_add_f32_e32 v144, v69, v144
	v_cvt_pk_bf16_f32 v148, v64, v65
	v_cvt_pk_bf16_f32 v149, v66, v67
	s_waitcnt lgkmcnt(0)
	v_mfma_f32_32x32x16_bf16 v[96:111], v[160:163], v[140:143], v[96:111]
	ds_read_b64_tr_b16 v[190:191], v168 offset:47104
	ds_read_b64_tr_b16 v[192:193], v168 offset:47616
	ds_read_b128 v[64:67], v188 offset:2048
	v_add_f32_e32 v140, v70, v144
	v_add_f32_e32 v140, v71, v140
	v_add_f32_e32 v140, v72, v140
	v_add_f32_e32 v140, v73, v140
	v_cvt_pk_bf16_f32 v150, v68, v69
	v_cvt_pk_bf16_f32 v151, v70, v71
	s_waitcnt lgkmcnt(0)
	v_mfma_f32_32x32x16_bf16 v[80:95], v[116:119], v[64:67], v[80:95]
	ds_read_b64_tr_b16 v[116:117], v168 offset:44032
	ds_read_b64_tr_b16 v[118:119], v168 offset:44544
	ds_read_b128 v[64:67], v188 offset:3072
	v_add_f32_e32 v68, v74, v140
	v_add_f32_e32 v68, v75, v68
	v_add_f32_e32 v68, v76, v68
	v_add_f32_e32 v68, v77, v68
	v_cvt_pk_bf16_f32 v144, v72, v73
	v_cvt_pk_bf16_f32 v145, v74, v75
	s_waitcnt lgkmcnt(0)
	v_mfma_f32_32x32x16_bf16 v[96:111], v[120:123], v[64:67], v[96:111]
	ds_read_b64_tr_b16 v[72:73], v168 offset:48128
	ds_read_b64_tr_b16 v[74:75], v168 offset:48640
	ds_read_b128 v[64:67], v188 offset:3072
	v_add_f32_e32 v68, v78, v68
	v_add_f32_e32 v68, v79, v68
	v_add_f32_e32 v68, 0, v68
	v_cvt_pk_bf16_f32 v146, v76, v77
	v_cvt_pk_bf16_f32 v147, v78, v79
	s_waitcnt lgkmcnt(0)
	v_mfma_f32_32x32x16_bf16 v[80:95], v[112:115], v[64:67], v[80:95]
	v_lshl_add_u64 v[64:65], v[170:171], 0, s[58:59]
	s_mov_b32 s85, m0
	s_mov_b32 m0, s16
	s_nop 0
	global_load_lds_dwordx4 v[64:65], off
	s_mov_b32 m0, s85
	v_lshl_add_u64 v[64:65], v[172:173], 0, s[58:59]
	s_addk_i32 s16, 0x2000
	s_mov_b32 s85, m0
	s_mov_b32 m0, s16
	s_nop 0
	global_load_lds_dwordx4 v[64:65], off
	s_mov_b32 m0, s85
	v_add_f32_e32 v174, v198, v68
	v_mfma_f32_32x32x16_bf16 v[48:63], v[156:159], v[178:181], v[48:63]
	ds_read_b64_tr_b16 v[76:77], v168 offset:49152
	ds_read_b64_tr_b16 v[78:79], v168 offset:49664
	v_exp_f32_e32 v96, v96
	v_exp_f32_e32 v97, v97
	v_mfma_f32_32x32x16_bf16 v[32:47], v[156:159], v[128:131], v[32:47]
	ds_read_b64_tr_b16 v[112:113], v168 offset:53248
	ds_read_b64_tr_b16 v[114:115], v168 offset:53760
	v_exp_f32_e32 v98, v98
	v_exp_f32_e32 v99, v99
	ds_read_b128 v[68:71], v234
	ds_read_b128 v[64:67], v234 offset:4096
	v_mfma_f32_32x32x16_bf16 v[48:63], v[152:155], v[132:135], v[48:63]
	ds_read_b64_tr_b16 v[120:121], v168 offset:50176
	ds_read_b64_tr_b16 v[122:123], v168 offset:50688
	v_exp_f32_e32 v100, v100
	v_exp_f32_e32 v101, v101
	ds_read_b128 v[164:167], v235
	ds_read_b128 v[140:143], v235 offset:4096
	v_mfma_f32_32x32x16_bf16 v[32:47], v[152:155], v[136:139], v[32:47]
	ds_read_b64_tr_b16 v[178:179], v168 offset:54272
	ds_read_b64_tr_b16 v[180:181], v168 offset:54784
	v_exp_f32_e32 v102, v102
	v_exp_f32_e32 v103, v103
	ds_read_b128 v[160:163], v236
	ds_read_b128 v[132:135], v236 offset:4096
	v_mfma_f32_32x32x16_bf16 v[48:63], v[148:151], v[124:127], v[48:63]
	ds_read_b64_tr_b16 v[194:195], v168 offset:51200
	ds_read_b64_tr_b16 v[196:197], v168 offset:51712
	v_exp_f32_e32 v104, v104
	v_exp_f32_e32 v105, v105
	ds_read_b128 v[136:139], v237
	ds_read_b128 v[128:131], v237 offset:4096
	v_mfma_f32_32x32x16_bf16 v[32:47], v[148:151], v[190:193], v[32:47]
	ds_read_b64_tr_b16 v[124:125], v168 offset:55296
	ds_read_b64_tr_b16 v[126:127], v168 offset:55808
	v_exp_f32_e32 v106, v106
	v_exp_f32_e32 v107, v107
	v_mfma_f32_32x32x16_bf16 v[48:63], v[144:147], v[116:119], v[48:63]
	ds_read_b64_tr_b16 v[190:191], v168 offset:52224
	ds_read_b64_tr_b16 v[192:193], v168 offset:52736
	v_exp_f32_e32 v108, v108
	v_exp_f32_e32 v109, v109
	v_mfma_f32_32x32x16_bf16 v[32:47], v[144:147], v[72:75], v[32:47]
	ds_read_b64_tr_b16 v[116:117], v168 offset:56320
	ds_read_b64_tr_b16 v[118:119], v168 offset:56832
	v_exp_f32_e32 v110, v110
	v_exp_f32_e32 v111, v111
	s_waitcnt lgkmcnt(14)
	v_mfma_f32_32x32x16_bf16 v[16:31], v[156:159], v[76:79], v[16:31]
	v_exp_f32_e32 v80, v80
	v_exp_f32_e32 v81, v81
	v_mfma_f32_32x32x16_bf16 v[0:15], v[156:159], v[112:115], v[0:15]
	v_exp_f32_e32 v82, v82
	v_exp_f32_e32 v83, v83
	v_mfma_f32_32x32x16_bf16 v[16:31], v[152:155], v[120:123], v[16:31]
	v_exp_f32_e32 v84, v84
	v_exp_f32_e32 v85, v85
	s_waitcnt lgkmcnt(12)
	v_mfma_f32_32x32x16_bf16 v[0:15], v[152:155], v[178:181], v[0:15]
	v_exp_f32_e32 v86, v86
	v_exp_f32_e32 v87, v87
	s_waitcnt lgkmcnt(8)
	v_mfma_f32_32x32x16_bf16 v[16:31], v[148:151], v[194:197], v[16:31]
	v_exp_f32_e32 v88, v88
	v_exp_f32_e32 v89, v89
	s_waitcnt lgkmcnt(4)
	v_mfma_f32_32x32x16_bf16 v[0:15], v[148:151], v[124:127], v[0:15]
	v_exp_f32_e32 v90, v90
	v_exp_f32_e32 v91, v91
	s_waitcnt lgkmcnt(2)
	v_mfma_f32_32x32x16_bf16 v[16:31], v[144:147], v[190:193], v[16:31]
	v_exp_f32_e32 v92, v92
	v_exp_f32_e32 v93, v93
	s_waitcnt lgkmcnt(0)
	v_mfma_f32_32x32x16_bf16 v[0:15], v[144:147], v[116:119], v[0:15]
	v_exp_f32_e32 v94, v94
	v_exp_f32_e32 v95, v95
	s_waitcnt vmcnt(2) lgkmcnt(0)
	s_barrier
	ds_read_b64_tr_b16 v[178:179], v168 offset:57344
	ds_read_b64_tr_b16 v[180:181], v168 offset:57856
	v_add_f32_e32 v76, v96, v97
	ds_read_b128 v[72:75], v188
	v_add_f32_e32 v76, v98, v76
	v_add_f32_e32 v76, v99, v76
	v_add_f32_e32 v76, v100, v76
	v_add_f32_e32 v76, v101, v76
	v_cvt_pk_bf16_f32 v156, v96, v97
	v_cvt_pk_bf16_f32 v157, v98, v99
	s_waitcnt lgkmcnt(0)
	v_mfma_f32_32x32x16_bf16 v[112:127], v[68:71], v[72:75], 0
	ds_read_b64_tr_b16 v[96:97], v168 offset:61440
	ds_read_b64_tr_b16 v[98:99], v168 offset:61952
	ds_read_b128 v[68:71], v188
	v_add_f32_e32 v72, v102, v76
	v_add_f32_e32 v72, v103, v72
	v_add_f32_e32 v72, v104, v72
	v_add_f32_e32 v144, v105, v72
	s_waitcnt lgkmcnt(0)
	v_mfma_f32_32x32x16_bf16 v[64:79], v[64:67], v[68:71], 0
	v_cvt_pk_bf16_f32 v158, v100, v101
	v_cvt_pk_bf16_f32 v159, v102, v103
	ds_read_b64_tr_b16 v[100:101], v168 offset:58368
	ds_read_b64_tr_b16 v[102:103], v168 offset:58880
	ds_read_b128 v[190:193], v188 offset:1024
	v_add_f32_e32 v144, v106, v144
	v_add_f32_e32 v144, v107, v144
	v_add_f32_e32 v144, v108, v144
	v_add_f32_e32 v144, v109, v144
	v_cvt_pk_bf16_f32 v152, v104, v105
	v_cvt_pk_bf16_f32 v153, v106, v107
	s_waitcnt lgkmcnt(0)
	v_mfma_f32_32x32x16_bf16 v[112:127], v[164:167], v[190:193], v[112:127]
	ds_read_b64_tr_b16 v[104:105], v168 offset:62464
	ds_read_b64_tr_b16 v[106:107], v168 offset:62976
	ds_read_b128 v[164:167], v188 offset:1024
	v_add_f32_e32 v144, v110, v144
	v_add_f32_e32 v144, v111, v144
	v_add_f32_e32 v144, v80, v144
	v_add_f32_e32 v144, v81, v144
	s_waitcnt lgkmcnt(0)
	v_mfma_f32_32x32x16_bf16 v[64:79], v[140:143], v[164:167], v[64:79]
	v_cvt_pk_bf16_f32 v154, v108, v109
	v_cvt_pk_bf16_f32 v155, v110, v111
	ds_read_b64_tr_b16 v[108:109], v168 offset:59392
	ds_read_b64_tr_b16 v[110:111], v168 offset:59904
	ds_read_b128 v[140:143], v188 offset:2048
	v_add_f32_e32 v144, v82, v144
	v_add_f32_e32 v144, v83, v144
	v_add_f32_e32 v144, v84, v144
	v_add_f32_e32 v144, v85, v144
	v_cvt_pk_bf16_f32 v148, v80, v81
	v_cvt_pk_bf16_f32 v149, v82, v83
	s_waitcnt lgkmcnt(0)
	v_mfma_f32_32x32x16_bf16 v[112:127], v[160:163], v[140:143], v[112:127]
	ds_read_b64_tr_b16 v[190:191], v168 offset:63488
	ds_read_b64_tr_b16 v[192:193], v168 offset:64000
	ds_read_b128 v[80:83], v188 offset:2048
	v_add_f32_e32 v140, v86, v144
	v_add_f32_e32 v140, v87, v140
	v_add_f32_e32 v140, v88, v140
	v_add_f32_e32 v140, v89, v140
	s_waitcnt lgkmcnt(0)
	v_mfma_f32_32x32x16_bf16 v[64:79], v[132:135], v[80:83], v[64:79]
	v_cvt_pk_bf16_f32 v150, v84, v85
	v_cvt_pk_bf16_f32 v151, v86, v87
	ds_read_b64_tr_b16 v[84:85], v168 offset:60416
	ds_read_b64_tr_b16 v[86:87], v168 offset:60928
	ds_read_b128 v[80:83], v188 offset:3072
	v_add_f32_e32 v132, v90, v140
	v_add_f32_e32 v132, v91, v132
	v_add_f32_e32 v132, v92, v132
	v_add_f32_e32 v132, v93, v132
	v_cvt_pk_bf16_f32 v144, v88, v89
	v_cvt_pk_bf16_f32 v145, v90, v91
	s_waitcnt lgkmcnt(0)
	v_mfma_f32_32x32x16_bf16 v[112:127], v[136:139], v[80:83], v[112:127]
	ds_read_b64_tr_b16 v[88:89], v168 offset:64512
	ds_read_b64_tr_b16 v[90:91], v168 offset:65024
	ds_read_b128 v[80:83], v188 offset:3072
	v_add_f32_e32 v132, v94, v132
	v_add_f32_e32 v132, v95, v132
	v_add_f32_e32 v132, 0, v132
	v_cvt_pk_bf16_f32 v146, v92, v93
	s_waitcnt lgkmcnt(0)
	v_mfma_f32_32x32x16_bf16 v[64:79], v[128:131], v[80:83], v[64:79]
	v_cvt_pk_bf16_f32 v147, v94, v95
	v_lshl_add_u64 v[80:81], v[170:171], 0, s[62:63]
	s_mov_b32 s16, m0
	s_mov_b32 m0, s17
	s_nop 0
	global_load_lds_dwordx4 v[80:81], off
	s_mov_b32 m0, s16
	v_lshl_add_u64 v[80:81], v[172:173], 0, s[62:63]
	s_mov_b32 s16, m0
	s_mov_b32 m0, s35
	s_nop 0
	global_load_lds_dwordx4 v[80:81], off
	s_mov_b32 m0, s16
	v_add_f32_e32 v174, v174, v132
	v_mfma_f32_32x32x16_bf16 v[48:63], v[156:159], v[178:181], v[48:63]
	ds_read_b64_tr_b16 v[92:93], v177 offset:40960
	ds_read_b64_tr_b16 v[94:95], v177 offset:41472
	v_exp_f32_e32 v112, v112
	v_exp_f32_e32 v113, v113
	v_mfma_f32_32x32x16_bf16 v[32:47], v[156:159], v[96:99], v[32:47]
	ds_read_b64_tr_b16 v[170:171], v177 offset:45056
	ds_read_b64_tr_b16 v[172:173], v177 offset:45568
	v_exp_f32_e32 v114, v114
	v_exp_f32_e32 v115, v115
	ds_read_b128 v[80:83], v234 offset:8192
	ds_read_b128 v[96:99], v234 offset:12288
	v_mfma_f32_32x32x16_bf16 v[48:63], v[152:155], v[100:103], v[48:63]
	ds_read_b64_tr_b16 v[178:179], v177 offset:41984
	ds_read_b64_tr_b16 v[180:181], v177 offset:42496
	v_exp_f32_e32 v116, v116
	v_exp_f32_e32 v117, v117
	ds_read_b128 v[164:167], v235 offset:8192
	ds_read_b128 v[140:143], v235 offset:12288
	v_mfma_f32_32x32x16_bf16 v[32:47], v[152:155], v[104:107], v[32:47]
	ds_read_b64_tr_b16 v[100:101], v177 offset:46080
	ds_read_b64_tr_b16 v[102:103], v177 offset:46592
	v_exp_f32_e32 v118, v118
	v_exp_f32_e32 v119, v119
	ds_read_b128 v[160:163], v236 offset:8192
	ds_read_b128 v[132:135], v236 offset:12288
	v_mfma_f32_32x32x16_bf16 v[48:63], v[148:151], v[108:111], v[48:63]
	ds_read_b64_tr_b16 v[104:105], v177 offset:43008
	ds_read_b64_tr_b16 v[106:107], v177 offset:43520
	v_exp_f32_e32 v120, v120
	v_exp_f32_e32 v121, v121
	ds_read_b128 v[136:139], v237 offset:8192
	ds_read_b128 v[128:131], v237 offset:12288
	v_mfma_f32_32x32x16_bf16 v[32:47], v[148:151], v[190:193], v[32:47]
	ds_read_b64_tr_b16 v[108:109], v177 offset:47104
	ds_read_b64_tr_b16 v[110:111], v177 offset:47616
	v_exp_f32_e32 v122, v122
	v_exp_f32_e32 v123, v123
	v_mfma_f32_32x32x16_bf16 v[48:63], v[144:147], v[84:87], v[48:63]
	ds_read_b64_tr_b16 v[190:191], v177 offset:44032
	ds_read_b64_tr_b16 v[192:193], v177 offset:44544
	v_exp_f32_e32 v124, v124
	v_exp_f32_e32 v125, v125
	v_mfma_f32_32x32x16_bf16 v[32:47], v[144:147], v[88:91], v[32:47]
	ds_read_b64_tr_b16 v[84:85], v177 offset:48128
	ds_read_b64_tr_b16 v[86:87], v177 offset:48640
	v_exp_f32_e32 v126, v126
	v_exp_f32_e32 v127, v127
	s_waitcnt lgkmcnt(14)
	v_mfma_f32_32x32x16_bf16 v[16:31], v[156:159], v[92:95], v[16:31]
	v_exp_f32_e32 v64, v64
	v_exp_f32_e32 v65, v65
	v_mfma_f32_32x32x16_bf16 v[0:15], v[156:159], v[170:173], v[0:15]
	v_exp_f32_e32 v66, v66
	v_exp_f32_e32 v67, v67
	v_mfma_f32_32x32x16_bf16 v[16:31], v[152:155], v[178:181], v[16:31]
	v_exp_f32_e32 v68, v68
	v_exp_f32_e32 v69, v69
	s_waitcnt lgkmcnt(12)
	v_mfma_f32_32x32x16_bf16 v[0:15], v[152:155], v[100:103], v[0:15]
	v_exp_f32_e32 v70, v70
	v_exp_f32_e32 v71, v71
	s_waitcnt lgkmcnt(8)
	v_mfma_f32_32x32x16_bf16 v[16:31], v[148:151], v[104:107], v[16:31]
	v_exp_f32_e32 v72, v72
	v_exp_f32_e32 v73, v73
	s_waitcnt lgkmcnt(4)
	v_mfma_f32_32x32x16_bf16 v[0:15], v[148:151], v[108:111], v[0:15]
	v_exp_f32_e32 v74, v74
	v_exp_f32_e32 v75, v75
	s_waitcnt lgkmcnt(2)
	v_mfma_f32_32x32x16_bf16 v[16:31], v[144:147], v[190:193], v[16:31]
	v_exp_f32_e32 v76, v76
	v_exp_f32_e32 v77, v77
	s_waitcnt lgkmcnt(0)
	v_mfma_f32_32x32x16_bf16 v[0:15], v[144:147], v[84:87], v[0:15]
	v_exp_f32_e32 v78, v78
	v_exp_f32_e32 v79, v79
	s_waitcnt vmcnt(0) lgkmcnt(0)
	s_barrier
	ds_read_b64_tr_b16 v[170:171], v168 offset:24576
	ds_read_b64_tr_b16 v[172:173], v168 offset:25088
	v_add_f32_e32 v88, v112, v113
	ds_read_b128 v[84:87], v188
	v_add_f32_e32 v88, v114, v88
	v_add_f32_e32 v88, v115, v88
	v_add_f32_e32 v88, v116, v88
	v_add_f32_e32 v104, v117, v88
	v_cvt_pk_bf16_f32 v156, v112, v113
	v_cvt_pk_bf16_f32 v157, v114, v115
	s_waitcnt lgkmcnt(0)
	v_mfma_f32_32x32x16_bf16 v[80:95], v[80:83], v[84:87], 0
	ds_read_b64_tr_b16 v[112:113], v168 offset:28672
	ds_read_b64_tr_b16 v[114:115], v168 offset:29184
	ds_read_b128 v[100:103], v188
	v_add_f32_e32 v104, v118, v104
	v_add_f32_e32 v104, v119, v104
	v_add_f32_e32 v104, v120, v104
	v_add_f32_e32 v144, v121, v104
	v_cvt_pk_bf16_f32 v158, v116, v117
	v_cvt_pk_bf16_f32 v159, v118, v119
	s_waitcnt lgkmcnt(0)
	v_mfma_f32_32x32x16_bf16 v[96:111], v[96:99], v[100:103], 0
	ds_read_b64_tr_b16 v[116:117], v168 offset:25600
	ds_read_b64_tr_b16 v[118:119], v168 offset:26112
	ds_read_b128 v[178:181], v188 offset:1024
	v_add_f32_e32 v144, v122, v144
	v_add_f32_e32 v144, v123, v144
	v_add_f32_e32 v144, v124, v144
	v_add_f32_e32 v144, v125, v144
	v_cvt_pk_bf16_f32 v152, v120, v121
	v_cvt_pk_bf16_f32 v153, v122, v123
	s_waitcnt lgkmcnt(0)
	v_mfma_f32_32x32x16_bf16 v[80:95], v[164:167], v[178:181], v[80:95]
	ds_read_b64_tr_b16 v[120:121], v168 offset:29696
	ds_read_b64_tr_b16 v[122:123], v168 offset:30208
	ds_read_b128 v[164:167], v188 offset:1024
	v_add_f32_e32 v144, v126, v144
	v_add_f32_e32 v144, v127, v144
	v_add_f32_e32 v144, v64, v144
	v_add_f32_e32 v144, v65, v144
	v_cvt_pk_bf16_f32 v154, v124, v125
	v_cvt_pk_bf16_f32 v155, v126, v127
	s_waitcnt lgkmcnt(0)
	v_mfma_f32_32x32x16_bf16 v[96:111], v[140:143], v[164:167], v[96:111]
	ds_read_b64_tr_b16 v[124:125], v168 offset:26624
	ds_read_b64_tr_b16 v[126:127], v168 offset:27136
	ds_read_b128 v[140:143], v188 offset:2048
	v_add_f32_e32 v144, v66, v144
	v_add_f32_e32 v144, v67, v144
	v_add_f32_e32 v144, v68, v144
	v_add_f32_e32 v144, v69, v144
	v_cvt_pk_bf16_f32 v148, v64, v65
	v_cvt_pk_bf16_f32 v149, v66, v67
	s_waitcnt lgkmcnt(0)
	v_mfma_f32_32x32x16_bf16 v[80:95], v[160:163], v[140:143], v[80:95]
	ds_read_b64_tr_b16 v[64:65], v168 offset:30720
	ds_read_b64_tr_b16 v[66:67], v168 offset:31232
	ds_read_b128 v[140:143], v188 offset:2048
	v_add_f32_e32 v144, v70, v144
	v_add_f32_e32 v144, v71, v144
	v_add_f32_e32 v144, v72, v144
	v_add_f32_e32 v144, v73, v144
	v_cvt_pk_bf16_f32 v150, v68, v69
	v_cvt_pk_bf16_f32 v151, v70, v71
	s_waitcnt lgkmcnt(0)
	v_mfma_f32_32x32x16_bf16 v[96:111], v[132:135], v[140:143], v[96:111]
	ds_read_b64_tr_b16 v[68:69], v168 offset:27648
	ds_read_b64_tr_b16 v[70:71], v168 offset:28160
	ds_read_b128 v[132:135], v188 offset:3072
	v_add_f32_e32 v140, v74, v144
	v_add_f32_e32 v140, v75, v140
	v_add_f32_e32 v140, v76, v140
	v_add_f32_e32 v140, v77, v140
	v_cvt_pk_bf16_f32 v144, v72, v73
	v_cvt_pk_bf16_f32 v145, v74, v75
	s_waitcnt lgkmcnt(0)
	v_mfma_f32_32x32x16_bf16 v[80:95], v[136:139], v[132:135], v[80:95]
	ds_read_b64_tr_b16 v[72:73], v168 offset:31744
	ds_read_b64_tr_b16 v[74:75], v168 offset:32256
	ds_read_b128 v[132:135], v188 offset:3072
	v_add_f32_e32 v136, v78, v140
	v_add_f32_e32 v136, v79, v136
	v_add_f32_e32 v136, 0, v136
	v_cvt_pk_bf16_f32 v146, v76, v77
	v_cvt_pk_bf16_f32 v147, v78, v79
	s_waitcnt lgkmcnt(0)
	v_mfma_f32_32x32x16_bf16 v[96:111], v[128:131], v[132:135], v[96:111]
	v_mfma_f32_32x32x16_bf16 v[48:63], v[156:159], v[170:173], v[48:63]
	ds_read_b64_tr_b16 v[76:77], v168 offset:32768
	ds_read_b64_tr_b16 v[78:79], v168 offset:33280
	v_exp_f32_e32 v80, v80
	v_exp_f32_e32 v81, v81
	v_mfma_f32_32x32x16_bf16 v[32:47], v[156:159], v[112:115], v[32:47]
	ds_read_b64_tr_b16 v[128:129], v168 offset:36864
	ds_read_b64_tr_b16 v[130:131], v168 offset:37376
	v_exp_f32_e32 v82, v82
	v_exp_f32_e32 v83, v83
	v_mfma_f32_32x32x16_bf16 v[48:63], v[152:155], v[116:119], v[48:63]
	ds_read_b64_tr_b16 v[112:113], v168 offset:33792
	ds_read_b64_tr_b16 v[114:115], v168 offset:34304
	v_exp_f32_e32 v84, v84
	v_exp_f32_e32 v85, v85
	v_mfma_f32_32x32x16_bf16 v[32:47], v[152:155], v[120:123], v[32:47]
	ds_read_b64_tr_b16 v[116:117], v168 offset:37888
	ds_read_b64_tr_b16 v[118:119], v168 offset:38400
	v_exp_f32_e32 v86, v86
	v_exp_f32_e32 v87, v87
	v_mfma_f32_32x32x16_bf16 v[48:63], v[148:151], v[124:127], v[48:63]
	ds_read_b64_tr_b16 v[120:121], v168 offset:34816
	ds_read_b64_tr_b16 v[122:123], v168 offset:35328
	v_exp_f32_e32 v88, v88
	v_exp_f32_e32 v89, v89
	v_mfma_f32_32x32x16_bf16 v[32:47], v[148:151], v[64:67], v[32:47]
	ds_read_b64_tr_b16 v[124:125], v168 offset:38912
	ds_read_b64_tr_b16 v[126:127], v168 offset:39424
	v_exp_f32_e32 v90, v90
	v_exp_f32_e32 v91, v91
	v_mfma_f32_32x32x16_bf16 v[48:63], v[144:147], v[68:71], v[48:63]
	ds_read_b64_tr_b16 v[64:65], v168 offset:35840
	ds_read_b64_tr_b16 v[66:67], v168 offset:36352
	v_exp_f32_e32 v92, v92
	v_exp_f32_e32 v93, v93
	v_mfma_f32_32x32x16_bf16 v[32:47], v[144:147], v[72:75], v[32:47]
	ds_read_b64_tr_b16 v[68:69], v168 offset:39936
	ds_read_b64_tr_b16 v[70:71], v168 offset:40448
	v_exp_f32_e32 v94, v94
	v_exp_f32_e32 v95, v95
	s_waitcnt lgkmcnt(14)
	v_mfma_f32_32x32x16_bf16 v[16:31], v[156:159], v[76:79], v[16:31]
	v_exp_f32_e32 v96, v96
	v_exp_f32_e32 v97, v97
	s_waitcnt lgkmcnt(12)
; #define SBAR() __builtin_amdgcn_sched_barrier(0)
;   #define PKW(P,B) cvtpk_s(P[B],P[B+1])
; template<int THRL,int VM,bool NOMAX> __device__ __forceinline__ void attn_unit(const bf16*Qb,const bf16*__restrict__ Kh,const bf16*__restrict__ Vh,bf16*Ob,const int NT,const int sp,float*wscr,char*shm){
;     ...
;   { float sacc=pB0[0]+pB0[1]; _Pragma("unroll") for(int r=2;r<16;++r)sacc+=pB0[r]; _Pragma("unroll") for(int r=0;r<16;++r)sacc+=pB1[r]; l_reg+=sacc;
;     pw0=(u32x4){PKW(pB0,0),PKW(pB0,2),PKW(pB0,4),PKW(pB0,6)};pw1=(u32x4){PKW(pB0,8),PKW(pB0,10),PKW(pB0,12),PKW(pB0,14)};pw2=(u32x4){PKW(pB1,0),PKW(pB1,2),PKW(pB1,4),PKW(pB1,6)};pw3=(u32x4){PKW(pB1,8),PKW(pB1,10),PKW(pB1,12),PKW(pB1,14)};
;     SBAR(); pv(o,vb0+VM*sl_cur,PAF(0),PAF(1),PAF(2),PAF(3)); if constexpr(VM==2) pv(o+2,vb0+VM*sl_cur+8192,PAF(0),PAF(1),PAF(2),PAF(3)); }
;     ...
;   {auto rr=__builtin_amdgcn_permlane32_swap(__float_as_uint(l_reg),__float_as_uint(l_reg),false,false);l_reg=__uint_as_float(rr[0])+__uint_as_float(rr[1]);}
;   if(hi==0)wsf[32+r32]=l_reg;asm volatile("s_waitcnt lgkmcnt(0)":::"memory");
	v_mfma_f32_32x32x16_bf16 v[0:15], v[156:159], v[128:131], v[0:15]
	v_exp_f32_e32 v98, v98
	v_exp_f32_e32 v99, v99
	s_waitcnt lgkmcnt(10)
	v_mfma_f32_32x32x16_bf16 v[16:31], v[152:155], v[112:115], v[16:31]
	v_exp_f32_e32 v100, v100
	v_exp_f32_e32 v101, v101
	s_waitcnt lgkmcnt(8)
	v_mfma_f32_32x32x16_bf16 v[0:15], v[152:155], v[116:119], v[0:15]
	v_exp_f32_e32 v102, v102
	v_exp_f32_e32 v103, v103
	s_waitcnt lgkmcnt(6)
	v_mfma_f32_32x32x16_bf16 v[16:31], v[148:151], v[120:123], v[16:31]
	v_exp_f32_e32 v104, v104
	v_exp_f32_e32 v105, v105
	s_waitcnt lgkmcnt(4)
	v_mfma_f32_32x32x16_bf16 v[0:15], v[148:151], v[124:127], v[0:15]
	v_exp_f32_e32 v106, v106
	v_exp_f32_e32 v107, v107
	s_waitcnt lgkmcnt(2)
	v_mfma_f32_32x32x16_bf16 v[16:31], v[144:147], v[64:67], v[16:31]
	v_exp_f32_e32 v108, v108
	v_exp_f32_e32 v109, v109
	s_waitcnt lgkmcnt(0)
	v_mfma_f32_32x32x16_bf16 v[0:15], v[144:147], v[68:71], v[0:15]
	v_exp_f32_e32 v110, v110
	v_exp_f32_e32 v111, v111
	v_add_f32_e32 v64, v80, v81
	v_add_f32_e32 v64, v82, v64
	v_add_f32_e32 v64, v83, v64
	v_add_f32_e32 v64, v84, v64
	v_add_f32_e32 v64, v85, v64
	v_add_f32_e32 v64, v86, v64
	v_add_f32_e32 v64, v87, v64
	v_add_f32_e32 v64, v88, v64
	v_add_f32_e32 v64, v89, v64
	v_add_f32_e32 v64, v90, v64
	v_add_f32_e32 v64, v91, v64
	v_add_f32_e32 v64, v92, v64
	v_add_f32_e32 v64, v93, v64
	v_add_f32_e32 v64, v94, v64
	v_add_f32_e32 v64, v95, v64
	v_add_f32_e32 v64, v64, v96
	v_add_f32_e32 v64, v97, v64
	v_add_f32_e32 v64, v98, v64
	v_add_f32_e32 v64, v99, v64
	v_add_f32_e32 v64, v100, v64
	v_add_f32_e32 v64, v101, v64
	v_add_f32_e32 v64, v102, v64
	v_add_f32_e32 v64, v103, v64
	v_add_f32_e32 v64, v104, v64
	v_add_f32_e32 v64, v105, v64
	v_add_f32_e32 v64, v106, v64
	v_add_f32_e32 v64, v107, v64
	v_add_f32_e32 v64, v108, v64
	v_add_f32_e32 v64, v109, v64
	v_add_f32_e32 v64, v110, v64
	v_add_f32_e32 v64, v111, v64
	v_add_f32_e32 v65, v174, v136
	v_add_f32_e32 v64, v65, v64
	v_cvt_pk_bf16_f32 v66, v80, v81
	v_cvt_pk_bf16_f32 v67, v82, v83
	v_cvt_pk_bf16_f32 v68, v84, v85
	v_cvt_pk_bf16_f32 v69, v86, v87
	v_cvt_pk_bf16_f32 v70, v88, v89
	v_cvt_pk_bf16_f32 v71, v90, v91
	v_cvt_pk_bf16_f32 v72, v92, v93
	v_cvt_pk_bf16_f32 v73, v94, v95
	v_cvt_pk_bf16_f32 v74, v96, v97
	v_cvt_pk_bf16_f32 v75, v98, v99
	v_cvt_pk_bf16_f32 v76, v100, v101
	v_cvt_pk_bf16_f32 v77, v102, v103
	v_cvt_pk_bf16_f32 v78, v104, v105
	v_cvt_pk_bf16_f32 v79, v106, v107
	v_cvt_pk_bf16_f32 v80, v108, v109
	v_cvt_pk_bf16_f32 v81, v110, v111
	v_add_u32_e32 v65, 0x4000, v176
	ds_read_b64_tr_b16 v[82:83],v65 offset:0
	ds_read_b64_tr_b16 v[84:85],v65 offset:512
	ds_read_b64_tr_b16 v[86:87],v65 offset:1024
	ds_read_b64_tr_b16 v[88:89],v65 offset:1536
	ds_read_b64_tr_b16 v[90:91],v65 offset:2048
	ds_read_b64_tr_b16 v[92:93],v65 offset:2560
	ds_read_b64_tr_b16 v[94:95],v65 offset:3072
	ds_read_b64_tr_b16 v[96:97],v65 offset:3584
	s_waitcnt lgkmcnt(0)
	s_nop 0
	v_mfma_f32_32x32x16_bf16 v[48:63], v[66:69], v[82:85], v[48:63]
	ds_read_b64_tr_b16 v[82:83],v65 offset:4096
	ds_read_b64_tr_b16 v[84:85],v65 offset:4608
	v_mfma_f32_32x32x16_bf16 v[48:63], v[70:73], v[86:89], v[48:63]
	ds_read_b64_tr_b16 v[86:87],v65 offset:5120
	ds_read_b64_tr_b16 v[88:89],v65 offset:5632
	v_mfma_f32_32x32x16_bf16 v[48:63], v[74:77], v[90:93], v[48:63]
	ds_read_b64_tr_b16 v[90:91],v65 offset:6144
	ds_read_b64_tr_b16 v[92:93],v65 offset:6656
	ds_read_b64_tr_b16 v[98:99],v65 offset:7168
	ds_read_b64_tr_b16 v[100:101],v65 offset:7680
	s_waitcnt lgkmcnt(0)
	v_mfma_f32_32x32x16_bf16 v[48:63], v[78:81], v[94:97], v[48:63]
	v_mfma_f32_32x32x16_bf16 v[32:47], v[66:69], v[82:85], v[32:47]
	v_add_u32_e32 v65, 0x6000, v176
	ds_read_b64_tr_b16 v[82:83],v65 offset:0
	ds_read_b64_tr_b16 v[84:85],v65 offset:512
	v_mfma_f32_32x32x16_bf16 v[32:47], v[70:73], v[86:89], v[32:47]
	ds_read_b64_tr_b16 v[86:87],v65 offset:1024
	ds_read_b64_tr_b16 v[88:89],v65 offset:1536
	v_mfma_f32_32x32x16_bf16 v[32:47], v[74:77], v[90:93], v[32:47]
	ds_read_b64_tr_b16 v[90:91],v65 offset:2048
	ds_read_b64_tr_b16 v[92:93],v65 offset:2560
	ds_read_b64_tr_b16 v[94:95],v65 offset:3072
	ds_read_b64_tr_b16 v[96:97],v65 offset:3584
	s_waitcnt lgkmcnt(0)
	v_mfma_f32_32x32x16_bf16 v[32:47], v[78:81], v[98:101], v[32:47]
	v_mfma_f32_32x32x16_bf16 v[16:31], v[66:69], v[82:85], v[16:31]
	ds_read_b64_tr_b16 v[82:83],v65 offset:4096
	ds_read_b64_tr_b16 v[84:85],v65 offset:4608
	v_mfma_f32_32x32x16_bf16 v[16:31], v[70:73], v[86:89], v[16:31]
	ds_read_b64_tr_b16 v[86:87],v65 offset:5120
	ds_read_b64_tr_b16 v[88:89],v65 offset:5632
	v_mfma_f32_32x32x16_bf16 v[16:31], v[74:77], v[90:93], v[16:31]
	ds_read_b64_tr_b16 v[90:91],v65 offset:6144
	ds_read_b64_tr_b16 v[92:93],v65 offset:6656
	ds_read_b64_tr_b16 v[98:99],v65 offset:7168
	ds_read_b64_tr_b16 v[100:101],v65 offset:7680
	s_waitcnt lgkmcnt(0)
	v_mfma_f32_32x32x16_bf16 v[16:31], v[78:81], v[94:97], v[16:31]
	v_mfma_f32_32x32x16_bf16 v[0:15], v[66:69], v[82:85], v[0:15]
	v_mov_b32_e32 v65, v64
	s_nop 1
	v_permlane32_swap_b32_e32 v64, v65
	v_cmp_gt_u32_e32 vcc, 32, v187
	v_mfma_f32_32x32x16_bf16 v[0:15], v[70:73], v[86:89], v[0:15]
	v_mfma_f32_32x32x16_bf16 v[0:15], v[74:77], v[90:93], v[0:15]
	v_mfma_f32_32x32x16_bf16 v[0:15], v[78:81], v[98:101], v[0:15]
	s_and_saveexec_b64 s[16:17], vcc
	s_cbranch_execz .LBB0_859
	v_add_f32_e32 v64, v64, v65
	v_lshl_add_u32 v65, v186, 2, s34
	ds_write_b32 v65, v64 offset:128
	s_branch .LBB0_859

.LBB0_874:
	v_mfma_f32_32x32x16_bf16 v[112:127], v[100:103], v[218:221], 0
	v_lshl_add_u32 v206, s89, 1, v188
	ds_read_b64_tr_b16 v[194:195], v206 offset:24576
	ds_read_b64_tr_b16 v[196:197], v206 offset:25088
	v_add_f32_e32 v108, v80, v81
	v_add_f32_e32 v108, v82, v108
	v_add_f32_e32 v108, v83, v108
	v_add_f32_e32 v108, v84, v108
	v_add_f32_e32 v108, v85, v108
	v_cvt_pk_bf16_f32 v156, v80, v81
	v_cvt_pk_bf16_f32 v157, v82, v83
	ds_read_b64_tr_b16 v[80:81], v206 offset:28672
	ds_read_b64_tr_b16 v[82:83], v206 offset:29184
	v_add_f32_e32 v104, v86, v108
	v_add_f32_e32 v104, v87, v104
	v_add_f32_e32 v104, v88, v104
	v_add_f32_e32 v144, v89, v104
	v_mfma_f32_32x32x16_bf16 v[96:111], v[96:99], v[218:221], 0
	s_add_i32 s88, s87, s17
	v_lshl_add_u64 v[238:239], v[180:181], 0, s[56:57]
	s_mov_b32 s89, m0
	s_mov_b32 m0, s88
	s_nop 0
	global_load_lds_dwordx4 v[238:239], off
	s_mov_b32 m0, s89
	v_cvt_pk_bf16_f32 v158, v84, v85
	v_cvt_pk_bf16_f32 v159, v86, v87
	ds_read_b64_tr_b16 v[84:85], v206 offset:25600
	ds_read_b64_tr_b16 v[86:87], v206 offset:26112
	v_add_f32_e32 v144, v90, v144
	v_add_f32_e32 v144, v91, v144
	v_add_f32_e32 v144, v92, v144
	v_add_f32_e32 v144, v93, v144
	v_cvt_pk_bf16_f32 v152, v88, v89
	v_cvt_pk_bf16_f32 v153, v90, v91
	v_mfma_f32_32x32x16_bf16 v[112:127], v[164:167], v[222:225], v[112:127]
	s_lshl_b32 s88, s86, 1
	v_lshl_add_u64 v[238:239], v[178:179], 0, s[56:57]
	s_add_i32 s88, s88, s16
	s_mov_b32 s89, m0
	s_mov_b32 m0, s88
	s_nop 0
	global_load_lds_dwordx4 v[238:239], off
	s_mov_b32 m0, s89
	ds_read_b64_tr_b16 v[88:89], v206 offset:29696
	ds_read_b64_tr_b16 v[90:91], v206 offset:30208
	v_add_f32_e32 v144, v94, v144
	v_add_f32_e32 v144, v95, v144
	v_add_f32_e32 v144, v64, v144
	v_add_f32_e32 v144, v65, v144
	v_mfma_f32_32x32x16_bf16 v[96:111], v[160:163], v[222:225], v[96:111]
	v_lshl_add_u64 v[238:239], v[176:177], 0, s[56:57]
	s_addk_i32 s88, 0x2000
	s_mov_b32 s89, m0
	s_mov_b32 m0, s88
	s_nop 0
	global_load_lds_dwordx4 v[238:239], off
	s_mov_b32 m0, s89
	v_cvt_pk_bf16_f32 v154, v92, v93
	v_cvt_pk_bf16_f32 v155, v94, v95
	ds_read_b64_tr_b16 v[92:93], v206 offset:26624
	ds_read_b64_tr_b16 v[94:95], v206 offset:27136
	v_add_f32_e32 v144, v66, v144
	v_add_f32_e32 v144, v67, v144
	v_add_f32_e32 v144, v68, v144
	v_add_f32_e32 v144, v69, v144
	v_cvt_pk_bf16_f32 v148, v64, v65
	v_cvt_pk_bf16_f32 v149, v66, v67
	v_mfma_f32_32x32x16_bf16 v[112:127], v[140:143], v[226:229], v[112:127]
	ds_read_b64_tr_b16 v[198:199], v206 offset:30720
	ds_read_b64_tr_b16 v[200:201], v206 offset:31232
	v_add_f32_e32 v140, v70, v144
	v_add_f32_e32 v140, v71, v140
	v_add_f32_e32 v140, v72, v140
	v_add_f32_e32 v140, v73, v140
	v_mfma_f32_32x32x16_bf16 v[96:111], v[136:139], v[226:229], v[96:111]
	v_cvt_pk_bf16_f32 v150, v68, v69
	v_cvt_pk_bf16_f32 v151, v70, v71
	ds_read_b64_tr_b16 v[202:203], v206 offset:27648
	ds_read_b64_tr_b16 v[204:205], v206 offset:28160
	v_add_f32_e32 v68, v74, v140
	v_add_f32_e32 v68, v75, v68
	v_add_f32_e32 v68, v76, v68
	v_add_f32_e32 v68, v77, v68
	v_cvt_pk_bf16_f32 v144, v72, v73
	v_cvt_pk_bf16_f32 v145, v74, v75
	v_mfma_f32_32x32x16_bf16 v[112:127], v[132:135], v[230:233], v[112:127]
	ds_read_b64_tr_b16 v[72:73], v206 offset:31744
	ds_read_b64_tr_b16 v[74:75], v206 offset:32256
	v_add_f32_e32 v68, v78, v68
	v_add_f32_e32 v68, v79, v68
	v_add_f32_e32 v68, 0, v68
	v_cvt_pk_bf16_f32 v146, v76, v77
	v_mfma_f32_32x32x16_bf16 v[96:111], v[128:131], v[230:233], v[96:111]
	v_cvt_pk_bf16_f32 v147, v78, v79
	v_add_f32_e32 v193, v193, v68
	s_waitcnt lgkmcnt(12)
	v_mfma_f32_32x32x16_bf16 v[48:63], v[156:159], v[194:197], v[48:63]
	ds_read_b64_tr_b16 v[76:77], v206 offset:32768
	ds_read_b64_tr_b16 v[78:79], v206 offset:33280
	v_exp_f32_e32 v112, v112
	v_exp_f32_e32 v113, v113
	v_mfma_f32_32x32x16_bf16 v[32:47], v[156:159], v[80:83], v[32:47]
	ds_read_b64_tr_b16 v[194:195], v206 offset:36864
	ds_read_b64_tr_b16 v[196:197], v206 offset:37376
	v_exp_f32_e32 v114, v114
	v_exp_f32_e32 v115, v115
	v_add_u32_e32 v242, s86, v234
	v_add_u32_e32 v243, s86, v235
	v_add_u32_e32 v244, s86, v236
	v_add_u32_e32 v245, s86, v237
	ds_read_b128 v[68:71], v242
	ds_read_b128 v[64:67], v242 offset:4096
	s_waitcnt lgkmcnt(14)
	v_mfma_f32_32x32x16_bf16 v[48:63], v[152:155], v[84:87], v[48:63]
	ds_read_b64_tr_b16 v[80:81], v206 offset:33792
	ds_read_b64_tr_b16 v[82:83], v206 offset:34304
	v_exp_f32_e32 v116, v116
	v_exp_f32_e32 v117, v117
	ds_read_b128 v[164:167], v243
	ds_read_b128 v[140:143], v243 offset:4096
	v_mfma_f32_32x32x16_bf16 v[32:47], v[152:155], v[88:91], v[32:47]
	ds_read_b64_tr_b16 v[84:85], v206 offset:37888
	ds_read_b64_tr_b16 v[86:87], v206 offset:38400
	v_exp_f32_e32 v118, v118
	v_exp_f32_e32 v119, v119
	ds_read_b128 v[160:163], v244
	ds_read_b128 v[132:135], v244 offset:4096
	s_waitcnt lgkmcnt(14)
	v_mfma_f32_32x32x16_bf16 v[48:63], v[148:151], v[92:95], v[48:63]
	ds_read_b64_tr_b16 v[88:89], v206 offset:34816
	ds_read_b64_tr_b16 v[90:91], v206 offset:35328
	v_exp_f32_e32 v120, v120
	v_exp_f32_e32 v121, v121
	ds_read_b128 v[136:139], v245
	ds_read_b128 v[128:131], v245 offset:4096
	v_mfma_f32_32x32x16_bf16 v[32:47], v[148:151], v[198:201], v[32:47]
	ds_read_b64_tr_b16 v[92:93], v206 offset:38912
	ds_read_b64_tr_b16 v[94:95], v206 offset:39424
	v_exp_f32_e32 v122, v122
	v_exp_f32_e32 v123, v123
	s_waitcnt lgkmcnt(14)
	v_mfma_f32_32x32x16_bf16 v[48:63], v[144:147], v[202:205], v[48:63]
	ds_read_b64_tr_b16 v[198:199], v206 offset:35840
	ds_read_b64_tr_b16 v[200:201], v206 offset:36352
	v_exp_f32_e32 v124, v124
	v_exp_f32_e32 v125, v125
	v_mfma_f32_32x32x16_bf16 v[32:47], v[144:147], v[72:75], v[32:47]
	ds_read_b64_tr_b16 v[202:203], v206 offset:39936
	ds_read_b64_tr_b16 v[204:205], v206 offset:40448
	v_exp_f32_e32 v126, v126
	v_exp_f32_e32 v127, v127
	s_waitcnt lgkmcnt(14)
	v_mfma_f32_32x32x16_bf16 v[16:31], v[156:159], v[76:79], v[16:31]
	v_exp_f32_e32 v96, v96
	v_exp_f32_e32 v97, v97
	v_mfma_f32_32x32x16_bf16 v[0:15], v[156:159], v[194:197], v[0:15]
	v_exp_f32_e32 v98, v98
	v_exp_f32_e32 v99, v99
	v_mfma_f32_32x32x16_bf16 v[16:31], v[152:155], v[80:83], v[16:31]
	v_exp_f32_e32 v100, v100
	v_exp_f32_e32 v101, v101
	s_waitcnt lgkmcnt(12)
	v_mfma_f32_32x32x16_bf16 v[0:15], v[152:155], v[84:87], v[0:15]
	v_exp_f32_e32 v102, v102
	v_exp_f32_e32 v103, v103
	s_waitcnt lgkmcnt(8)
	v_mfma_f32_32x32x16_bf16 v[16:31], v[148:151], v[88:91], v[16:31]
	v_exp_f32_e32 v104, v104
	v_exp_f32_e32 v105, v105
	s_waitcnt lgkmcnt(4)
	v_mfma_f32_32x32x16_bf16 v[0:15], v[148:151], v[92:95], v[0:15]
	v_exp_f32_e32 v106, v106
	v_exp_f32_e32 v107, v107
	s_waitcnt lgkmcnt(2)
	v_mfma_f32_32x32x16_bf16 v[16:31], v[144:147], v[198:201], v[16:31]
	v_exp_f32_e32 v108, v108
	v_exp_f32_e32 v109, v109
	s_waitcnt lgkmcnt(0)
	v_mfma_f32_32x32x16_bf16 v[0:15], v[144:147], v[202:205], v[0:15]
	v_exp_f32_e32 v110, v110
	v_exp_f32_e32 v111, v111
	s_waitcnt vmcnt(3) lgkmcnt(0)
	s_barrier
	v_mfma_f32_32x32x16_bf16 v[80:95], v[68:71], v[218:221], 0
	s_add_i32 s88, s86, 0x2000
	s_cmpk_lg_i32 s86, 0x4000
	s_cselect_b32 s88, s88, 0
	v_lshl_add_u32 v206, s87, 1, v188
	ds_read_b64_tr_b16 v[194:195], v206 offset:24576
	ds_read_b64_tr_b16 v[196:197], v206 offset:25088
	v_add_f32_e32 v76, v112, v113
	v_add_f32_e32 v76, v114, v76
	v_add_f32_e32 v76, v115, v76
	v_add_f32_e32 v76, v116, v76
	v_add_f32_e32 v76, v117, v76
	v_cvt_pk_bf16_f32 v156, v112, v113
	v_cvt_pk_bf16_f32 v157, v114, v115
	ds_read_b64_tr_b16 v[112:113], v206 offset:28672
	ds_read_b64_tr_b16 v[114:115], v206 offset:29184
	v_add_f32_e32 v72, v118, v76
	v_add_f32_e32 v72, v119, v72
	v_add_f32_e32 v72, v120, v72
	v_add_f32_e32 v144, v121, v72
	v_mfma_f32_32x32x16_bf16 v[64:79], v[64:67], v[218:221], 0
	s_add_i32 s87, s86, s17
	s_mov_b32 s89, m0
	s_mov_b32 m0, s87
	s_nop 0
	global_load_lds_dwordx4 v[180:181], off
	s_mov_b32 m0, s89
	v_cvt_pk_bf16_f32 v158, v116, v117
	v_cvt_pk_bf16_f32 v159, v118, v119
	ds_read_b64_tr_b16 v[116:117], v206 offset:25600
	ds_read_b64_tr_b16 v[118:119], v206 offset:26112
	v_add_f32_e32 v144, v122, v144
	v_add_f32_e32 v144, v123, v144
	v_add_f32_e32 v144, v124, v144
	v_add_f32_e32 v144, v125, v144
	v_mfma_f32_32x32x16_bf16 v[80:95], v[164:167], v[222:225], v[80:95]
	s_lshl_b32 s87, s88, 1
	s_add_i32 s87, s87, s16
	s_mov_b32 s89, m0
	s_mov_b32 m0, s87
	s_nop 0
	global_load_lds_dwordx4 v[178:179], off
	s_mov_b32 m0, s89
	v_cvt_pk_bf16_f32 v152, v120, v121
	v_cvt_pk_bf16_f32 v153, v122, v123
	ds_read_b64_tr_b16 v[120:121], v206 offset:29696
	ds_read_b64_tr_b16 v[122:123], v206 offset:30208
	v_add_f32_e32 v144, v126, v144
	v_add_f32_e32 v144, v127, v144
	v_add_f32_e32 v144, v96, v144
	v_add_f32_e32 v144, v97, v144
	v_mfma_f32_32x32x16_bf16 v[64:79], v[140:143], v[222:225], v[64:79]
	s_addk_i32 s87, 0x2000
	s_mov_b32 s89, m0
	s_mov_b32 m0, s87
	s_nop 0
	global_load_lds_dwordx4 v[176:177], off
	s_mov_b32 m0, s89
	v_cvt_pk_bf16_f32 v154, v124, v125
	v_cvt_pk_bf16_f32 v155, v126, v127
	ds_read_b64_tr_b16 v[124:125], v206 offset:26624
	ds_read_b64_tr_b16 v[126:127], v206 offset:27136
	v_add_f32_e32 v144, v98, v144
	v_add_f32_e32 v144, v99, v144
	v_add_f32_e32 v144, v100, v144
	v_add_f32_e32 v144, v101, v144
	v_mfma_f32_32x32x16_bf16 v[80:95], v[160:163], v[226:229], v[80:95]
	v_cvt_pk_bf16_f32 v148, v96, v97
	v_cvt_pk_bf16_f32 v149, v98, v99
	ds_read_b64_tr_b16 v[198:199], v206 offset:30720
	ds_read_b64_tr_b16 v[200:201], v206 offset:31232
	v_add_f32_e32 v140, v102, v144
	v_add_f32_e32 v140, v103, v140
	v_add_f32_e32 v140, v104, v140
	v_add_f32_e32 v140, v105, v140
	v_mfma_f32_32x32x16_bf16 v[64:79], v[132:135], v[226:229], v[64:79]
	v_cvt_pk_bf16_f32 v150, v100, v101
	v_cvt_pk_bf16_f32 v151, v102, v103
	ds_read_b64_tr_b16 v[202:203], v206 offset:27648
	ds_read_b64_tr_b16 v[204:205], v206 offset:28160
	v_add_f32_e32 v100, v106, v140
	v_add_f32_e32 v100, v107, v100
	v_add_f32_e32 v100, v108, v100
	v_add_f32_e32 v100, v109, v100
	v_mfma_f32_32x32x16_bf16 v[80:95], v[136:139], v[230:233], v[80:95]
	v_cvt_pk_bf16_f32 v144, v104, v105
	v_cvt_pk_bf16_f32 v145, v106, v107
	ds_read_b64_tr_b16 v[104:105], v206 offset:31744
	ds_read_b64_tr_b16 v[106:107], v206 offset:32256
	v_add_f32_e32 v100, v110, v100
	v_add_f32_e32 v100, v111, v100
	v_add_f32_e32 v100, 0, v100
	v_cvt_pk_bf16_f32 v146, v108, v109
	v_mfma_f32_32x32x16_bf16 v[64:79], v[128:131], v[230:233], v[64:79]
	v_cvt_pk_bf16_f32 v147, v110, v111
	v_add_f32_e32 v193, v193, v100
	s_waitcnt lgkmcnt(12)
	v_mfma_f32_32x32x16_bf16 v[48:63], v[156:159], v[194:197], v[48:63]
	ds_read_b64_tr_b16 v[108:109], v206 offset:32768
	ds_read_b64_tr_b16 v[110:111], v206 offset:33280
	v_exp_f32_e32 v80, v80
	v_exp_f32_e32 v81, v81
	v_mfma_f32_32x32x16_bf16 v[32:47], v[156:159], v[112:115], v[32:47]
	ds_read_b64_tr_b16 v[194:195], v206 offset:36864
	ds_read_b64_tr_b16 v[196:197], v206 offset:37376
	v_exp_f32_e32 v82, v82
	v_exp_f32_e32 v83, v83
	v_add_u32_e32 v242, s88, v234
	v_add_u32_e32 v243, s88, v235
	v_add_u32_e32 v244, s88, v236
	v_add_u32_e32 v245, s88, v237
	ds_read_b128 v[100:103], v242
	ds_read_b128 v[96:99], v242 offset:4096
	s_waitcnt lgkmcnt(14)
	v_mfma_f32_32x32x16_bf16 v[48:63], v[152:155], v[116:119], v[48:63]
	ds_read_b64_tr_b16 v[112:113], v206 offset:33792
	ds_read_b64_tr_b16 v[114:115], v206 offset:34304
	v_exp_f32_e32 v84, v84
	v_exp_f32_e32 v85, v85
	ds_read_b128 v[164:167], v243
	ds_read_b128 v[160:163], v243 offset:4096
	v_mfma_f32_32x32x16_bf16 v[32:47], v[152:155], v[120:123], v[32:47]
	ds_read_b64_tr_b16 v[116:117], v206 offset:37888
	ds_read_b64_tr_b16 v[118:119], v206 offset:38400
	v_exp_f32_e32 v86, v86
	v_exp_f32_e32 v87, v87
	ds_read_b128 v[140:143], v244
	ds_read_b128 v[136:139], v244 offset:4096
	s_waitcnt lgkmcnt(14)
	v_mfma_f32_32x32x16_bf16 v[48:63], v[148:151], v[124:127], v[48:63]
	ds_read_b64_tr_b16 v[120:121], v206 offset:34816
	ds_read_b64_tr_b16 v[122:123], v206 offset:35328
	v_exp_f32_e32 v88, v88
	v_exp_f32_e32 v89, v89
	ds_read_b128 v[132:135], v245
	ds_read_b128 v[128:131], v245 offset:4096
	v_mfma_f32_32x32x16_bf16 v[32:47], v[148:151], v[198:201], v[32:47]
	ds_read_b64_tr_b16 v[124:125], v206 offset:38912
	ds_read_b64_tr_b16 v[126:127], v206 offset:39424
	v_exp_f32_e32 v90, v90
	v_exp_f32_e32 v91, v91
	s_waitcnt lgkmcnt(14)
	v_mfma_f32_32x32x16_bf16 v[48:63], v[144:147], v[202:205], v[48:63]
	ds_read_b64_tr_b16 v[198:199], v206 offset:35840
	ds_read_b64_tr_b16 v[200:201], v206 offset:36352
	v_exp_f32_e32 v92, v92
	v_exp_f32_e32 v93, v93
	v_mfma_f32_32x32x16_bf16 v[32:47], v[144:147], v[104:107], v[32:47]
	ds_read_b64_tr_b16 v[202:203], v206 offset:39936
	ds_read_b64_tr_b16 v[204:205], v206 offset:40448
	v_exp_f32_e32 v94, v94
	v_exp_f32_e32 v95, v95
	s_waitcnt lgkmcnt(14)
	v_mfma_f32_32x32x16_bf16 v[16:31], v[156:159], v[108:111], v[16:31]
	v_exp_f32_e32 v64, v64
	v_exp_f32_e32 v65, v65
	v_mfma_f32_32x32x16_bf16 v[0:15], v[156:159], v[194:197], v[0:15]
	v_exp_f32_e32 v66, v66
	v_exp_f32_e32 v67, v67
	v_mfma_f32_32x32x16_bf16 v[16:31], v[152:155], v[112:115], v[16:31]
	v_exp_f32_e32 v68, v68
	v_exp_f32_e32 v69, v69
	s_waitcnt lgkmcnt(12)
	v_mfma_f32_32x32x16_bf16 v[0:15], v[152:155], v[116:119], v[0:15]
	v_exp_f32_e32 v70, v70
	v_exp_f32_e32 v71, v71
	s_waitcnt lgkmcnt(8)
	v_mfma_f32_32x32x16_bf16 v[16:31], v[148:151], v[120:123], v[16:31]
	v_exp_f32_e32 v72, v72
	v_exp_f32_e32 v73, v73
	s_waitcnt lgkmcnt(4)
	v_mfma_f32_32x32x16_bf16 v[0:15], v[148:151], v[124:127], v[0:15]
	v_exp_f32_e32 v74, v74
	v_exp_f32_e32 v75, v75
	s_waitcnt lgkmcnt(2)
	v_mfma_f32_32x32x16_bf16 v[16:31], v[144:147], v[198:201], v[16:31]
	v_exp_f32_e32 v76, v76
	v_exp_f32_e32 v77, v77
	s_waitcnt lgkmcnt(0)
	v_mfma_f32_32x32x16_bf16 v[0:15], v[144:147], v[202:205], v[0:15]
	v_exp_f32_e32 v78, v78
	v_exp_f32_e32 v79, v79
	s_add_i32 s90, s88, 0x2000
	s_waitcnt vmcnt(3) lgkmcnt(0)
	s_barrier
; #define WAIT_BAR(N) asm volatile("s_waitcnt vmcnt(" #N ") lgkmcnt(0)\n\ts_barrier":::"memory")
;   #define RESC() do{ if(!NOMAX&&resc){ asm volatile("s_waitcnt lgkmcnt(0)":::"memory"); \
;       _Pragma("unroll") for(int d_=0;d_<2*VM;++d_) _Pragma("unroll") for(int r=0;r<16;++r)o[d_][r]*=wsf[crow(r,hi)]; } }while(0)
;   #define ROT() do{sl_prev=sl_cur;sl_cur=sl_next;sl_next=(sl_next==(NSLOT-1)*SLOTB)?0:sl_next+SLOTB;}while(0)
;   #define ENDW(tt) do{ if((tt)+3<NT){ if constexpr(VM==2){WAIT_BAR(3);}else{WAIT_BAR(2);} } else if((tt)+2<NT){ if constexpr(VM==2){WAIT_BAR(2);}else{WAIT_BAR(1);} } else {WAIT_BAR(0);} }while(0)
; template<int THRL,int VM,bool NOMAX> __device__ __forceinline__ void attn_unit(const bf16*Qb,const bf16*__restrict__ Kh,const bf16*__restrict__ Vh,bf16*Ob,const int NT,const int sp,float*wscr,char*shm){
;     ...
;   for(;t+5<NT;t+=2){
;     STEP(pB0,pB1,pA0,pA1,t,true,true,true);     if constexpr(VM==2){WAIT_BAR(3);}else{WAIT_BAR(2);} RESC(); ROT();
;     STEP(pA0,pA1,pB0,pB1,t+1,true,true,true);   if constexpr(VM==2){WAIT_BAR(3);}else{WAIT_BAR(2);} RESC(); ROT();
;   }
;     ...
;   for(;t+1<NT;t+=2){
;     STEP(pB0,pB1,pA0,pA1,t,(t+3<NT),(t+1<NT),(t+1<NT));       ENDW(t);   RESC(); ROT();
	s_cmpk_lg_i32 s88, 0x4000
	s_mov_b32 s89, s86
	s_cselect_b32 s86, s90, 0
	s_add_i32 s85, s85, 2
	v_lshl_add_u64 v[176:177], v[176:177], 0, s[58:59]
	v_lshl_add_u64 v[178:179], v[178:179], 0, s[58:59]
	v_lshl_add_u64 v[180:181], v[180:181], 0, s[58:59]
	s_mov_b32 s87, s88
	s_cmp_lt_u32 s85, 57
	s_cbranch_scc1 .LBB0_874
	s_and_b32 s34, s34, 0x3fffffc0
	s_lshl_b32 s34, s34, 2
	s_add_i32 s34, s34, 0
	s_add_i32 s34, s34, 0x12000
	s_cmp_lg_u32 0, -1
	s_cselect_b32 s85, 0, 0
	s_add_i32 s86, s85, 0x6000
	v_add_u32_e32 v104, s86, v191
	v_add3_u32 v176, v104, v190, v192
	v_add_u32_e32 v177, 0x6000, v188
	ds_read_b64_tr_b16 v[178:179], v188 offset:40960
	ds_read_b64_tr_b16 v[180:181], v188 offset:41472
	v_add_f32_e32 v108, v80, v81
	ds_read_b128 v[104:107], v168
	v_add_f32_e32 v108, v82, v108
	v_add_f32_e32 v108, v83, v108
	v_add_f32_e32 v108, v84, v108
	v_add_f32_e32 v108, v85, v108
	v_cvt_pk_bf16_f32 v156, v80, v81
	v_cvt_pk_bf16_f32 v157, v82, v83
	s_waitcnt lgkmcnt(0)
	v_mfma_f32_32x32x16_bf16 v[112:127], v[100:103], v[104:107], 0
	ds_read_b64_tr_b16 v[80:81], v188 offset:45056
	ds_read_b64_tr_b16 v[82:83], v188 offset:45568
	ds_read_b128 v[100:103], v168
	v_add_f32_e32 v104, v86, v108
	v_add_f32_e32 v104, v87, v104
	v_add_f32_e32 v104, v88, v104
	v_add_f32_e32 v144, v89, v104
	v_cvt_pk_bf16_f32 v158, v84, v85
	v_cvt_pk_bf16_f32 v159, v86, v87
	s_waitcnt lgkmcnt(0)
	v_mfma_f32_32x32x16_bf16 v[96:111], v[96:99], v[100:103], 0
	ds_read_b64_tr_b16 v[84:85], v188 offset:41984
	ds_read_b64_tr_b16 v[86:87], v188 offset:42496
	ds_read_b128 v[194:197], v168 offset:1024
	v_add_f32_e32 v144, v90, v144
	v_add_f32_e32 v144, v91, v144
	v_add_f32_e32 v144, v92, v144
	v_add_f32_e32 v144, v93, v144
	v_cvt_pk_bf16_f32 v152, v88, v89
	v_cvt_pk_bf16_f32 v153, v90, v91
	s_waitcnt lgkmcnt(0)
	v_mfma_f32_32x32x16_bf16 v[112:127], v[164:167], v[194:197], v[112:127]
	ds_read_b64_tr_b16 v[88:89], v188 offset:46080
	ds_read_b64_tr_b16 v[90:91], v188 offset:46592
	ds_read_b128 v[164:167], v168 offset:1024
	v_add_f32_e32 v144, v94, v144
	v_add_f32_e32 v144, v95, v144
	v_add_f32_e32 v144, v64, v144
	v_add_f32_e32 v144, v65, v144
	v_cvt_pk_bf16_f32 v154, v92, v93
	v_cvt_pk_bf16_f32 v155, v94, v95
	s_waitcnt lgkmcnt(0)
	v_mfma_f32_32x32x16_bf16 v[96:111], v[160:163], v[164:167], v[96:111]
	ds_read_b64_tr_b16 v[194:195], v188 offset:43008
	ds_read_b64_tr_b16 v[196:197], v188 offset:43520
	ds_read_b128 v[92:95], v168 offset:2048
	v_add_f32_e32 v144, v66, v144
	v_add_f32_e32 v144, v67, v144
	v_add_f32_e32 v144, v68, v144
	v_add_f32_e32 v144, v69, v144
	v_cvt_pk_bf16_f32 v148, v64, v65
	v_cvt_pk_bf16_f32 v149, v66, v67
	s_waitcnt lgkmcnt(0)
	v_mfma_f32_32x32x16_bf16 v[112:127], v[140:143], v[92:95], v[112:127]
	ds_read_b64_tr_b16 v[140:141], v188 offset:47104
	ds_read_b64_tr_b16 v[142:143], v188 offset:47616
	ds_read_b128 v[64:67], v168 offset:2048
	v_add_f32_e32 v92, v70, v144
	v_add_f32_e32 v92, v71, v92
	v_add_f32_e32 v92, v72, v92
	v_add_f32_e32 v92, v73, v92
	v_cvt_pk_bf16_f32 v150, v68, v69
	v_cvt_pk_bf16_f32 v151, v70, v71
	s_waitcnt lgkmcnt(0)
	v_mfma_f32_32x32x16_bf16 v[96:111], v[136:139], v[64:67], v[96:111]
	ds_read_b64_tr_b16 v[136:137], v188 offset:44032
	ds_read_b64_tr_b16 v[138:139], v188 offset:44544
	ds_read_b128 v[64:67], v168 offset:3072
	v_add_f32_e32 v68, v74, v92
	v_add_f32_e32 v68, v75, v68
	v_add_f32_e32 v68, v76, v68
	v_add_f32_e32 v68, v77, v68
	v_cvt_pk_bf16_f32 v144, v72, v73
	v_cvt_pk_bf16_f32 v145, v74, v75
	s_waitcnt lgkmcnt(0)
	v_mfma_f32_32x32x16_bf16 v[112:127], v[132:135], v[64:67], v[112:127]
	ds_read_b64_tr_b16 v[72:73], v188 offset:48128
	ds_read_b64_tr_b16 v[74:75], v188 offset:48640
	ds_read_b128 v[64:67], v168 offset:3072
	v_add_f32_e32 v68, v78, v68
	v_add_f32_e32 v68, v79, v68
	v_add_f32_e32 v68, 0, v68
	v_cvt_pk_bf16_f32 v146, v76, v77
	v_cvt_pk_bf16_f32 v147, v78, v79
	s_waitcnt lgkmcnt(0)
	v_mfma_f32_32x32x16_bf16 v[96:111], v[128:131], v[64:67], v[96:111]
	s_add_i32 s85, s85, s35
	v_lshl_add_u64 v[64:65], v[174:175], 0, s[60:61]
	s_add_i32 s35, s85, 0x4000
	s_mov_b32 s86, m0
	s_mov_b32 m0, s35
	s_nop 0
	global_load_lds_dwordx4 v[64:65], off
	s_mov_b32 m0, s86
	v_lshl_add_u64 v[64:65], v[170:171], 0, s[62:63]
	s_mov_b32 s35, m0
	s_mov_b32 m0, s16
	s_nop 0
	global_load_lds_dwordx4 v[64:65], off
	s_mov_b32 m0, s35
	v_lshl_add_u64 v[64:65], v[172:173], 0, s[62:63]
	s_add_i32 s35, s16, 0x2000
	s_mov_b32 s86, m0
	s_mov_b32 m0, s35
	s_nop 0
	global_load_lds_dwordx4 v[64:65], off
	s_mov_b32 m0, s86
	v_add_f32_e32 v198, v193, v68
	v_mfma_f32_32x32x16_bf16 v[48:63], v[156:159], v[178:181], v[48:63]
	ds_read_b64_tr_b16 v[76:77], v188 offset:49152
	ds_read_b64_tr_b16 v[78:79], v188 offset:49664
	v_exp_f32_e32 v112, v112
	v_exp_f32_e32 v113, v113
	v_mfma_f32_32x32x16_bf16 v[32:47], v[156:159], v[80:83], v[32:47]
	ds_read_b64_tr_b16 v[128:129], v188 offset:53248
	ds_read_b64_tr_b16 v[130:131], v188 offset:53760
	v_exp_f32_e32 v114, v114
	v_exp_f32_e32 v115, v115
	ds_read_b128 v[68:71], v234
	ds_read_b128 v[64:67], v234 offset:4096
	v_mfma_f32_32x32x16_bf16 v[48:63], v[152:155], v[84:87], v[48:63]
	ds_read_b64_tr_b16 v[132:133], v188 offset:50176
	ds_read_b64_tr_b16 v[134:135], v188 offset:50688
	v_exp_f32_e32 v116, v116
	v_exp_f32_e32 v117, v117
	ds_read_b128 v[164:167], v235
	ds_read_b128 v[92:95], v235 offset:4096
	v_mfma_f32_32x32x16_bf16 v[32:47], v[152:155], v[88:91], v[32:47]
	ds_read_b64_tr_b16 v[178:179], v188 offset:54272
	ds_read_b64_tr_b16 v[180:181], v188 offset:54784
	v_exp_f32_e32 v118, v118
	v_exp_f32_e32 v119, v119
	ds_read_b128 v[160:163], v236
	ds_read_b128 v[84:87], v236 offset:4096
	v_mfma_f32_32x32x16_bf16 v[48:63], v[148:151], v[194:197], v[48:63]
	ds_read_b64_tr_b16 v[190:191], v188 offset:51200
	ds_read_b64_tr_b16 v[192:193], v188 offset:51712
	v_exp_f32_e32 v120, v120
	v_exp_f32_e32 v121, v121
	ds_read_b128 v[88:91], v237
	ds_read_b128 v[80:83], v237 offset:4096
	v_mfma_f32_32x32x16_bf16 v[32:47], v[148:151], v[140:143], v[32:47]
	ds_read_b64_tr_b16 v[194:195], v188 offset:55296
	ds_read_b64_tr_b16 v[196:197], v188 offset:55808
	v_exp_f32_e32 v122, v122
	v_exp_f32_e32 v123, v123
	v_mfma_f32_32x32x16_bf16 v[48:63], v[144:147], v[136:139], v[48:63]
	ds_read_b64_tr_b16 v[140:141], v188 offset:52224
	ds_read_b64_tr_b16 v[142:143], v188 offset:52736
	v_exp_f32_e32 v124, v124
	v_exp_f32_e32 v125, v125
	v_mfma_f32_32x32x16_bf16 v[32:47], v[144:147], v[72:75], v[32:47]
	ds_read_b64_tr_b16 v[136:137], v188 offset:56320
	ds_read_b64_tr_b16 v[138:139], v188 offset:56832
	v_exp_f32_e32 v126, v126
	v_exp_f32_e32 v127, v127
	s_waitcnt lgkmcnt(14)
	v_mfma_f32_32x32x16_bf16 v[16:31], v[156:159], v[76:79], v[16:31]
	v_exp_f32_e32 v96, v96
	v_exp_f32_e32 v97, v97
	v_mfma_f32_32x32x16_bf16 v[0:15], v[156:159], v[128:131], v[0:15]
	v_exp_f32_e32 v98, v98
	v_exp_f32_e32 v99, v99
	v_mfma_f32_32x32x16_bf16 v[16:31], v[152:155], v[132:135], v[16:31]
	v_exp_f32_e32 v100, v100
	v_exp_f32_e32 v101, v101
	s_waitcnt lgkmcnt(12)
	v_mfma_f32_32x32x16_bf16 v[0:15], v[152:155], v[178:181], v[0:15]
	v_exp_f32_e32 v102, v102
	v_exp_f32_e32 v103, v103
	s_waitcnt lgkmcnt(8)
	v_mfma_f32_32x32x16_bf16 v[16:31], v[148:151], v[190:193], v[16:31]
	v_exp_f32_e32 v104, v104
	v_exp_f32_e32 v105, v105
	s_waitcnt lgkmcnt(4)
	v_mfma_f32_32x32x16_bf16 v[0:15], v[148:151], v[194:197], v[0:15]
	v_exp_f32_e32 v106, v106
	v_exp_f32_e32 v107, v107
	s_waitcnt lgkmcnt(2)
	v_mfma_f32_32x32x16_bf16 v[16:31], v[144:147], v[140:143], v[16:31]
	v_exp_f32_e32 v108, v108
	v_exp_f32_e32 v109, v109
	s_waitcnt lgkmcnt(0)
	v_mfma_f32_32x32x16_bf16 v[0:15], v[144:147], v[136:139], v[0:15]
	v_exp_f32_e32 v110, v110
	v_exp_f32_e32 v111, v111
	s_waitcnt vmcnt(3) lgkmcnt(0)
	s_barrier
	ds_read_b64_tr_b16 v[178:179], v188 offset:57344
	ds_read_b64_tr_b16 v[180:181], v188 offset:57856
	v_add_f32_e32 v76, v112, v113
	ds_read_b128 v[72:75], v168
	v_add_f32_e32 v76, v114, v76
	v_add_f32_e32 v76, v115, v76
	v_add_f32_e32 v76, v116, v76
	v_add_f32_e32 v76, v117, v76
	v_cvt_pk_bf16_f32 v156, v112, v113
	v_cvt_pk_bf16_f32 v157, v114, v115
	s_waitcnt lgkmcnt(0)
	v_mfma_f32_32x32x16_bf16 v[128:143], v[68:71], v[72:75], 0
	ds_read_b64_tr_b16 v[112:113], v188 offset:61440
	ds_read_b64_tr_b16 v[114:115], v188 offset:61952
	ds_read_b128 v[68:71], v168
	v_add_f32_e32 v72, v118, v76
	v_add_f32_e32 v72, v119, v72
	v_add_f32_e32 v72, v120, v72
	v_add_f32_e32 v144, v121, v72
	s_waitcnt lgkmcnt(0)
	v_mfma_f32_32x32x16_bf16 v[64:79], v[64:67], v[68:71], 0
	v_cvt_pk_bf16_f32 v158, v116, v117
	v_cvt_pk_bf16_f32 v159, v118, v119
	ds_read_b64_tr_b16 v[116:117], v188 offset:58368
	ds_read_b64_tr_b16 v[118:119], v188 offset:58880
	ds_read_b128 v[190:193], v168 offset:1024
	v_add_f32_e32 v144, v122, v144
	v_add_f32_e32 v144, v123, v144
	v_add_f32_e32 v144, v124, v144
	v_add_f32_e32 v144, v125, v144
	v_cvt_pk_bf16_f32 v152, v120, v121
	v_cvt_pk_bf16_f32 v153, v122, v123
	s_waitcnt lgkmcnt(0)
	v_mfma_f32_32x32x16_bf16 v[128:143], v[164:167], v[190:193], v[128:143]
	ds_read_b64_tr_b16 v[120:121], v188 offset:62464
	ds_read_b64_tr_b16 v[122:123], v188 offset:62976
	ds_read_b128 v[164:167], v168 offset:1024
	v_add_f32_e32 v144, v126, v144
	v_add_f32_e32 v144, v127, v144
	v_add_f32_e32 v144, v96, v144
	v_add_f32_e32 v144, v97, v144
	s_waitcnt lgkmcnt(0)
	v_mfma_f32_32x32x16_bf16 v[64:79], v[92:95], v[164:167], v[64:79]
	v_cvt_pk_bf16_f32 v154, v124, v125
	v_cvt_pk_bf16_f32 v155, v126, v127
	ds_read_b64_tr_b16 v[92:93], v188 offset:59392
	ds_read_b64_tr_b16 v[94:95], v188 offset:59904
	ds_read_b128 v[124:127], v168 offset:2048
	v_add_f32_e32 v144, v98, v144
	v_add_f32_e32 v144, v99, v144
	v_add_f32_e32 v144, v100, v144
	v_add_f32_e32 v144, v101, v144
	v_cvt_pk_bf16_f32 v148, v96, v97
	v_cvt_pk_bf16_f32 v149, v98, v99
	s_waitcnt lgkmcnt(0)
	v_mfma_f32_32x32x16_bf16 v[128:143], v[160:163], v[124:127], v[128:143]
	ds_read_b64_tr_b16 v[96:97], v188 offset:63488
	ds_read_b64_tr_b16 v[98:99], v188 offset:64000
	ds_read_b128 v[124:127], v168 offset:2048
	v_add_f32_e32 v144, v102, v144
	v_add_f32_e32 v144, v103, v144
	v_add_f32_e32 v144, v104, v144
	v_add_f32_e32 v144, v105, v144
	s_waitcnt lgkmcnt(0)
	v_mfma_f32_32x32x16_bf16 v[64:79], v[84:87], v[124:127], v[64:79]
	v_cvt_pk_bf16_f32 v150, v100, v101
	v_cvt_pk_bf16_f32 v151, v102, v103
	ds_read_b64_tr_b16 v[100:101], v188 offset:60416
	ds_read_b64_tr_b16 v[102:103], v188 offset:60928
	ds_read_b128 v[84:87], v168 offset:3072
	v_add_f32_e32 v124, v106, v144
	v_add_f32_e32 v124, v107, v124
	v_add_f32_e32 v124, v108, v124
	v_add_f32_e32 v124, v109, v124
	v_cvt_pk_bf16_f32 v144, v104, v105
	v_cvt_pk_bf16_f32 v145, v106, v107
	s_waitcnt lgkmcnt(0)
	v_mfma_f32_32x32x16_bf16 v[128:143], v[88:91], v[84:87], v[128:143]
	ds_read_b64_tr_b16 v[88:89], v188 offset:64512
	ds_read_b64_tr_b16 v[90:91], v188 offset:65024
	ds_read_b128 v[84:87], v168 offset:3072
	v_add_f32_e32 v104, v110, v124
	v_add_f32_e32 v104, v111, v104
	v_add_f32_e32 v104, 0, v104
	v_cvt_pk_bf16_f32 v146, v108, v109
	s_waitcnt lgkmcnt(0)
	v_mfma_f32_32x32x16_bf16 v[64:79], v[80:83], v[84:87], v[64:79]
	v_cvt_pk_bf16_f32 v147, v110, v111
	v_lshl_add_u64 v[80:81], v[174:175], 0, s[64:65]
	s_mov_b32 s86, m0
	s_mov_b32 m0, s17
	s_nop 0
	global_load_lds_dwordx4 v[80:81], off
	s_mov_b32 m0, s86
	v_lshl_add_u64 v[80:81], v[170:171], 0, s[66:67]
	s_add_i32 s17, s85, 0xa000
	s_mov_b32 s86, m0
	s_mov_b32 m0, s17
	s_nop 0
	global_load_lds_dwordx4 v[80:81], off
	s_mov_b32 m0, s86
	v_lshl_add_u64 v[80:81], v[172:173], 0, s[66:67]
	s_add_i32 s17, s85, 0xc000
	s_mov_b32 s86, m0
	s_mov_b32 m0, s17
	s_nop 0
	global_load_lds_dwordx4 v[80:81], off
	s_mov_b32 m0, s86
	v_add_f32_e32 v198, v198, v104
	v_mfma_f32_32x32x16_bf16 v[48:63], v[156:159], v[178:181], v[48:63]
	ds_read_b64_tr_b16 v[104:105], v177 offset:40960
	ds_read_b64_tr_b16 v[106:107], v177 offset:41472
	v_exp_f32_e32 v128, v128
	v_exp_f32_e32 v129, v129
	v_mfma_f32_32x32x16_bf16 v[32:47], v[156:159], v[112:115], v[32:47]
	ds_read_b64_tr_b16 v[108:109], v177 offset:45056
	ds_read_b64_tr_b16 v[110:111], v177 offset:45568
	v_exp_f32_e32 v130, v130
	v_exp_f32_e32 v131, v131
	ds_read_b128 v[84:87], v234 offset:8192
	ds_read_b128 v[80:83], v234 offset:12288
	v_mfma_f32_32x32x16_bf16 v[48:63], v[152:155], v[116:119], v[48:63]
	ds_read_b64_tr_b16 v[178:179], v177 offset:41984
	ds_read_b64_tr_b16 v[180:181], v177 offset:42496
	v_exp_f32_e32 v132, v132
	v_exp_f32_e32 v133, v133
	ds_read_b128 v[164:167], v235 offset:8192
	ds_read_b128 v[124:127], v235 offset:12288
	v_mfma_f32_32x32x16_bf16 v[32:47], v[152:155], v[120:123], v[32:47]
	ds_read_b64_tr_b16 v[190:191], v177 offset:46080
	ds_read_b64_tr_b16 v[192:193], v177 offset:46592
	v_exp_f32_e32 v134, v134
	v_exp_f32_e32 v135, v135
	ds_read_b128 v[160:163], v236 offset:8192
	ds_read_b128 v[116:119], v236 offset:12288
	v_mfma_f32_32x32x16_bf16 v[48:63], v[148:151], v[92:95], v[48:63]
	ds_read_b64_tr_b16 v[194:195], v177 offset:43008
	ds_read_b64_tr_b16 v[196:197], v177 offset:43520
	v_exp_f32_e32 v136, v136
	v_exp_f32_e32 v137, v137
	ds_read_b128 v[120:123], v237 offset:8192
	ds_read_b128 v[112:115], v237 offset:12288
	v_mfma_f32_32x32x16_bf16 v[32:47], v[148:151], v[96:99], v[32:47]
	ds_read_b64_tr_b16 v[92:93], v177 offset:47104
	ds_read_b64_tr_b16 v[94:95], v177 offset:47616
	v_exp_f32_e32 v138, v138
	v_exp_f32_e32 v139, v139
	v_mfma_f32_32x32x16_bf16 v[48:63], v[144:147], v[100:103], v[48:63]
	ds_read_b64_tr_b16 v[96:97], v177 offset:44032
	ds_read_b64_tr_b16 v[98:99], v177 offset:44544
	v_exp_f32_e32 v140, v140
	v_exp_f32_e32 v141, v141
	v_mfma_f32_32x32x16_bf16 v[32:47], v[144:147], v[88:91], v[32:47]
	ds_read_b64_tr_b16 v[100:101], v177 offset:48128
	ds_read_b64_tr_b16 v[102:103], v177 offset:48640
	v_exp_f32_e32 v142, v142
	v_exp_f32_e32 v143, v143
	s_waitcnt lgkmcnt(14)
	v_mfma_f32_32x32x16_bf16 v[16:31], v[156:159], v[104:107], v[16:31]
	v_exp_f32_e32 v64, v64
	v_exp_f32_e32 v65, v65
	v_mfma_f32_32x32x16_bf16 v[0:15], v[156:159], v[108:111], v[0:15]
	v_exp_f32_e32 v66, v66
	v_exp_f32_e32 v67, v67
	v_mfma_f32_32x32x16_bf16 v[16:31], v[152:155], v[178:181], v[16:31]
	v_exp_f32_e32 v68, v68
	v_exp_f32_e32 v69, v69
	s_waitcnt lgkmcnt(12)
	v_mfma_f32_32x32x16_bf16 v[0:15], v[152:155], v[190:193], v[0:15]
	v_exp_f32_e32 v70, v70
	v_exp_f32_e32 v71, v71
	s_waitcnt lgkmcnt(8)
	v_mfma_f32_32x32x16_bf16 v[16:31], v[148:151], v[194:197], v[16:31]
	v_exp_f32_e32 v72, v72
	v_exp_f32_e32 v73, v73
	s_waitcnt lgkmcnt(4)
	v_mfma_f32_32x32x16_bf16 v[0:15], v[148:151], v[92:95], v[0:15]
	v_exp_f32_e32 v74, v74
	v_exp_f32_e32 v75, v75
	s_waitcnt lgkmcnt(2)
	v_mfma_f32_32x32x16_bf16 v[16:31], v[144:147], v[96:99], v[16:31]
	v_exp_f32_e32 v76, v76
	v_exp_f32_e32 v77, v77
	s_waitcnt lgkmcnt(0)
	v_mfma_f32_32x32x16_bf16 v[0:15], v[144:147], v[100:103], v[0:15]
	v_exp_f32_e32 v78, v78
	v_exp_f32_e32 v79, v79
	s_waitcnt vmcnt(3) lgkmcnt(0)
	s_barrier
	ds_read_b64_tr_b16 v[178:179], v188 offset:24576
	ds_read_b64_tr_b16 v[180:181], v188 offset:25088
	v_add_f32_e32 v92, v128, v129
	ds_read_b128 v[88:91], v168
	v_add_f32_e32 v92, v130, v92
	v_add_f32_e32 v92, v131, v92
	v_add_f32_e32 v92, v132, v92
	v_add_f32_e32 v92, v133, v92
	v_cvt_pk_bf16_f32 v156, v128, v129
	v_cvt_pk_bf16_f32 v157, v130, v131
	s_waitcnt lgkmcnt(0)
	v_mfma_f32_32x32x16_bf16 v[96:111], v[84:87], v[88:91], 0
	ds_read_b64_tr_b16 v[128:129], v188 offset:28672
	ds_read_b64_tr_b16 v[130:131], v188 offset:29184
	ds_read_b128 v[84:87], v168
	v_add_f32_e32 v88, v134, v92
	v_add_f32_e32 v88, v135, v88
	v_add_f32_e32 v88, v136, v88
	v_add_f32_e32 v144, v137, v88
	v_cvt_pk_bf16_f32 v158, v132, v133
	v_cvt_pk_bf16_f32 v159, v134, v135
	s_waitcnt lgkmcnt(0)
	v_mfma_f32_32x32x16_bf16 v[80:95], v[80:83], v[84:87], 0
	ds_read_b64_tr_b16 v[132:133], v188 offset:25600
	ds_read_b64_tr_b16 v[134:135], v188 offset:26112
	ds_read_b128 v[190:193], v168 offset:1024
	v_add_f32_e32 v144, v138, v144
	v_add_f32_e32 v144, v139, v144
	v_add_f32_e32 v144, v140, v144
	v_add_f32_e32 v144, v141, v144
	v_cvt_pk_bf16_f32 v152, v136, v137
	v_cvt_pk_bf16_f32 v153, v138, v139
	s_waitcnt lgkmcnt(0)
	v_mfma_f32_32x32x16_bf16 v[96:111], v[164:167], v[190:193], v[96:111]
	ds_read_b64_tr_b16 v[136:137], v188 offset:29696
	ds_read_b64_tr_b16 v[138:139], v188 offset:30208
	ds_read_b128 v[164:167], v168 offset:1024
	v_add_f32_e32 v144, v142, v144
	v_add_f32_e32 v144, v143, v144
	v_add_f32_e32 v144, v64, v144
	v_add_f32_e32 v144, v65, v144
	v_cvt_pk_bf16_f32 v154, v140, v141
	v_cvt_pk_bf16_f32 v155, v142, v143
	s_waitcnt lgkmcnt(0)
	v_mfma_f32_32x32x16_bf16 v[80:95], v[124:127], v[164:167], v[80:95]
	ds_read_b64_tr_b16 v[124:125], v188 offset:26624
	ds_read_b64_tr_b16 v[126:127], v188 offset:27136
	ds_read_b128 v[140:143], v168 offset:2048
	v_add_f32_e32 v144, v66, v144
	v_add_f32_e32 v144, v67, v144
	v_add_f32_e32 v144, v68, v144
	v_add_f32_e32 v144, v69, v144
	v_cvt_pk_bf16_f32 v148, v64, v65
	v_cvt_pk_bf16_f32 v149, v66, v67
	s_waitcnt lgkmcnt(0)
	v_mfma_f32_32x32x16_bf16 v[96:111], v[160:163], v[140:143], v[96:111]
	ds_read_b64_tr_b16 v[190:191], v188 offset:30720
	ds_read_b64_tr_b16 v[192:193], v188 offset:31232
	ds_read_b128 v[64:67], v168 offset:2048
	v_add_f32_e32 v140, v70, v144
	v_add_f32_e32 v140, v71, v140
	v_add_f32_e32 v140, v72, v140
	v_add_f32_e32 v140, v73, v140
	v_cvt_pk_bf16_f32 v150, v68, v69
	v_cvt_pk_bf16_f32 v151, v70, v71
	s_waitcnt lgkmcnt(0)
	v_mfma_f32_32x32x16_bf16 v[80:95], v[116:119], v[64:67], v[80:95]
	ds_read_b64_tr_b16 v[116:117], v188 offset:27648
	ds_read_b64_tr_b16 v[118:119], v188 offset:28160
	ds_read_b128 v[64:67], v168 offset:3072
	v_add_f32_e32 v68, v74, v140
	v_add_f32_e32 v68, v75, v68
	v_add_f32_e32 v68, v76, v68
	v_add_f32_e32 v68, v77, v68
	v_cvt_pk_bf16_f32 v144, v72, v73
	v_cvt_pk_bf16_f32 v145, v74, v75
	s_waitcnt lgkmcnt(0)
	v_mfma_f32_32x32x16_bf16 v[96:111], v[120:123], v[64:67], v[96:111]
	ds_read_b64_tr_b16 v[72:73], v188 offset:31744
	ds_read_b64_tr_b16 v[74:75], v188 offset:32256
	ds_read_b128 v[64:67], v168 offset:3072
	v_add_f32_e32 v68, v78, v68
	v_add_f32_e32 v68, v79, v68
	v_add_f32_e32 v68, 0, v68
	v_cvt_pk_bf16_f32 v146, v76, v77
	v_cvt_pk_bf16_f32 v147, v78, v79
	s_waitcnt lgkmcnt(0)
	v_mfma_f32_32x32x16_bf16 v[80:95], v[112:115], v[64:67], v[80:95]
	v_lshl_add_u64 v[64:65], v[170:171], 0, s[60:61]
	s_add_i32 s17, s85, 0xe000
	s_mov_b32 s86, m0
	s_mov_b32 m0, s17
	s_nop 0
	global_load_lds_dwordx4 v[64:65], off
	s_mov_b32 m0, s86
	v_lshl_add_u64 v[64:65], v[172:173], 0, s[60:61]
	s_add_i32 s85, s85, 0x10000
	s_mov_b32 s17, m0
	s_mov_b32 m0, s85
	s_nop 0
	global_load_lds_dwordx4 v[64:65], off
	s_mov_b32 m0, s17
	v_add_f32_e32 v174, v198, v68
	v_mfma_f32_32x32x16_bf16 v[48:63], v[156:159], v[178:181], v[48:63]
	ds_read_b64_tr_b16 v[76:77], v188 offset:32768
	ds_read_b64_tr_b16 v[78:79], v188 offset:33280
	v_exp_f32_e32 v96, v96
	v_exp_f32_e32 v97, v97
	v_mfma_f32_32x32x16_bf16 v[32:47], v[156:159], v[128:131], v[32:47]
	ds_read_b64_tr_b16 v[112:113], v188 offset:36864
	ds_read_b64_tr_b16 v[114:115], v188 offset:37376
	v_exp_f32_e32 v98, v98
	v_exp_f32_e32 v99, v99
	ds_read_b128 v[68:71], v234 offset:16384
	ds_read_b128 v[64:67], v234 offset:20480
	v_mfma_f32_32x32x16_bf16 v[48:63], v[152:155], v[132:135], v[48:63]
	ds_read_b64_tr_b16 v[120:121], v188 offset:33792
	ds_read_b64_tr_b16 v[122:123], v188 offset:34304
	v_exp_f32_e32 v100, v100
	v_exp_f32_e32 v101, v101
	ds_read_b128 v[164:167], v235 offset:16384
	ds_read_b128 v[140:143], v235 offset:20480
	v_mfma_f32_32x32x16_bf16 v[32:47], v[152:155], v[136:139], v[32:47]
	ds_read_b64_tr_b16 v[178:179], v188 offset:37888
	ds_read_b64_tr_b16 v[180:181], v188 offset:38400
	v_exp_f32_e32 v102, v102
	v_exp_f32_e32 v103, v103
	ds_read_b128 v[160:163], v236 offset:16384
	ds_read_b128 v[132:135], v236 offset:20480
	v_mfma_f32_32x32x16_bf16 v[48:63], v[148:151], v[124:127], v[48:63]
	ds_read_b64_tr_b16 v[194:195], v188 offset:34816
	ds_read_b64_tr_b16 v[196:197], v188 offset:35328
	v_exp_f32_e32 v104, v104
	v_exp_f32_e32 v105, v105
	ds_read_b128 v[136:139], v237 offset:16384
	ds_read_b128 v[128:131], v237 offset:20480
	v_mfma_f32_32x32x16_bf16 v[32:47], v[148:151], v[190:193], v[32:47]
	ds_read_b64_tr_b16 v[124:125], v188 offset:38912
	ds_read_b64_tr_b16 v[126:127], v188 offset:39424
	v_exp_f32_e32 v106, v106
	v_exp_f32_e32 v107, v107
	v_mfma_f32_32x32x16_bf16 v[48:63], v[144:147], v[116:119], v[48:63]
	ds_read_b64_tr_b16 v[190:191], v188 offset:35840
	ds_read_b64_tr_b16 v[192:193], v188 offset:36352
	v_exp_f32_e32 v108, v108
	v_exp_f32_e32 v109, v109
	v_mfma_f32_32x32x16_bf16 v[32:47], v[144:147], v[72:75], v[32:47]
	ds_read_b64_tr_b16 v[116:117], v188 offset:39936
	ds_read_b64_tr_b16 v[118:119], v188 offset:40448
	v_exp_f32_e32 v110, v110
	v_exp_f32_e32 v111, v111
	s_waitcnt lgkmcnt(14)
	v_mfma_f32_32x32x16_bf16 v[16:31], v[156:159], v[76:79], v[16:31]
	v_exp_f32_e32 v80, v80
	v_exp_f32_e32 v81, v81
	v_mfma_f32_32x32x16_bf16 v[0:15], v[156:159], v[112:115], v[0:15]
	v_exp_f32_e32 v82, v82
	v_exp_f32_e32 v83, v83
	v_mfma_f32_32x32x16_bf16 v[16:31], v[152:155], v[120:123], v[16:31]
	v_exp_f32_e32 v84, v84
	v_exp_f32_e32 v85, v85
	s_waitcnt lgkmcnt(12)
	v_mfma_f32_32x32x16_bf16 v[0:15], v[152:155], v[178:181], v[0:15]
	v_exp_f32_e32 v86, v86
	v_exp_f32_e32 v87, v87
	s_waitcnt lgkmcnt(8)
	v_mfma_f32_32x32x16_bf16 v[16:31], v[148:151], v[194:197], v[16:31]
	v_exp_f32_e32 v88, v88
	v_exp_f32_e32 v89, v89
	s_waitcnt lgkmcnt(4)
	v_mfma_f32_32x32x16_bf16 v[0:15], v[148:151], v[124:127], v[0:15]
	v_exp_f32_e32 v90, v90
	v_exp_f32_e32 v91, v91
	s_waitcnt lgkmcnt(2)
	v_mfma_f32_32x32x16_bf16 v[16:31], v[144:147], v[190:193], v[16:31]
	v_exp_f32_e32 v92, v92
	v_exp_f32_e32 v93, v93
	s_waitcnt lgkmcnt(0)
	v_mfma_f32_32x32x16_bf16 v[0:15], v[144:147], v[116:119], v[0:15]
	v_exp_f32_e32 v94, v94
	v_exp_f32_e32 v95, v95
	s_waitcnt vmcnt(2) lgkmcnt(0)
	s_barrier
	ds_read_b64_tr_b16 v[178:179], v188 offset:40960
	ds_read_b64_tr_b16 v[180:181], v188 offset:41472
	v_add_f32_e32 v76, v96, v97
	ds_read_b128 v[72:75], v168
	v_add_f32_e32 v76, v98, v76
	v_add_f32_e32 v76, v99, v76
	v_add_f32_e32 v76, v100, v76
	v_add_f32_e32 v76, v101, v76
	v_cvt_pk_bf16_f32 v156, v96, v97
	v_cvt_pk_bf16_f32 v157, v98, v99
	s_waitcnt lgkmcnt(0)
	v_mfma_f32_32x32x16_bf16 v[112:127], v[68:71], v[72:75], 0
	ds_read_b64_tr_b16 v[96:97], v188 offset:45056
	ds_read_b64_tr_b16 v[98:99], v188 offset:45568
	ds_read_b128 v[68:71], v168
	v_add_f32_e32 v72, v102, v76
	v_add_f32_e32 v72, v103, v72
	v_add_f32_e32 v72, v104, v72
	v_add_f32_e32 v144, v105, v72
	s_waitcnt lgkmcnt(0)
	v_mfma_f32_32x32x16_bf16 v[64:79], v[64:67], v[68:71], 0
	v_cvt_pk_bf16_f32 v158, v100, v101
	v_cvt_pk_bf16_f32 v159, v102, v103
	ds_read_b64_tr_b16 v[100:101], v188 offset:41984
	ds_read_b64_tr_b16 v[102:103], v188 offset:42496
	ds_read_b128 v[190:193], v168 offset:1024
	v_add_f32_e32 v144, v106, v144
	v_add_f32_e32 v144, v107, v144
	v_add_f32_e32 v144, v108, v144
	v_add_f32_e32 v144, v109, v144
	v_cvt_pk_bf16_f32 v152, v104, v105
	v_cvt_pk_bf16_f32 v153, v106, v107
	s_waitcnt lgkmcnt(0)
	v_mfma_f32_32x32x16_bf16 v[112:127], v[164:167], v[190:193], v[112:127]
	ds_read_b64_tr_b16 v[104:105], v188 offset:46080
	ds_read_b64_tr_b16 v[106:107], v188 offset:46592
	ds_read_b128 v[164:167], v168 offset:1024
	v_add_f32_e32 v144, v110, v144
	v_add_f32_e32 v144, v111, v144
	v_add_f32_e32 v144, v80, v144
	v_add_f32_e32 v144, v81, v144
	s_waitcnt lgkmcnt(0)
	v_mfma_f32_32x32x16_bf16 v[64:79], v[140:143], v[164:167], v[64:79]
	v_cvt_pk_bf16_f32 v154, v108, v109
	v_cvt_pk_bf16_f32 v155, v110, v111
	ds_read_b64_tr_b16 v[108:109], v188 offset:43008
	ds_read_b64_tr_b16 v[110:111], v188 offset:43520
	ds_read_b128 v[140:143], v168 offset:2048
	v_add_f32_e32 v144, v82, v144
	v_add_f32_e32 v144, v83, v144
	v_add_f32_e32 v144, v84, v144
	v_add_f32_e32 v144, v85, v144
	v_cvt_pk_bf16_f32 v148, v80, v81
	v_cvt_pk_bf16_f32 v149, v82, v83
	s_waitcnt lgkmcnt(0)
	v_mfma_f32_32x32x16_bf16 v[112:127], v[160:163], v[140:143], v[112:127]
	ds_read_b64_tr_b16 v[190:191], v188 offset:47104
	ds_read_b64_tr_b16 v[192:193], v188 offset:47616
	ds_read_b128 v[80:83], v168 offset:2048
	v_add_f32_e32 v140, v86, v144
	v_add_f32_e32 v140, v87, v140
	v_add_f32_e32 v140, v88, v140
	v_add_f32_e32 v140, v89, v140
	s_waitcnt lgkmcnt(0)
	v_mfma_f32_32x32x16_bf16 v[64:79], v[132:135], v[80:83], v[64:79]
	v_cvt_pk_bf16_f32 v150, v84, v85
	v_cvt_pk_bf16_f32 v151, v86, v87
	ds_read_b64_tr_b16 v[84:85], v188 offset:44032
	ds_read_b64_tr_b16 v[86:87], v188 offset:44544
	ds_read_b128 v[80:83], v168 offset:3072
	v_add_f32_e32 v132, v90, v140
	v_add_f32_e32 v132, v91, v132
	v_add_f32_e32 v132, v92, v132
	v_add_f32_e32 v132, v93, v132
	v_cvt_pk_bf16_f32 v144, v88, v89
	v_cvt_pk_bf16_f32 v145, v90, v91
	s_waitcnt lgkmcnt(0)
	v_mfma_f32_32x32x16_bf16 v[112:127], v[136:139], v[80:83], v[112:127]
	ds_read_b64_tr_b16 v[88:89], v188 offset:48128
	ds_read_b64_tr_b16 v[90:91], v188 offset:48640
	ds_read_b128 v[80:83], v168 offset:3072
	v_add_f32_e32 v132, v94, v132
	v_add_f32_e32 v132, v95, v132
	v_add_f32_e32 v132, 0, v132
	v_cvt_pk_bf16_f32 v146, v92, v93
	s_waitcnt lgkmcnt(0)
	v_mfma_f32_32x32x16_bf16 v[64:79], v[128:131], v[80:83], v[64:79]
	v_cvt_pk_bf16_f32 v147, v94, v95
	v_lshl_add_u64 v[80:81], v[170:171], 0, s[64:65]
	s_mov_b32 s17, m0
	s_mov_b32 m0, s16
	s_nop 0
	global_load_lds_dwordx4 v[80:81], off
	s_mov_b32 m0, s17
	v_lshl_add_u64 v[80:81], v[172:173], 0, s[64:65]
	s_mov_b32 s16, m0
	s_mov_b32 m0, s35
	s_nop 0
	global_load_lds_dwordx4 v[80:81], off
	s_mov_b32 m0, s16
	v_add_f32_e32 v174, v174, v132
	v_mfma_f32_32x32x16_bf16 v[48:63], v[156:159], v[178:181], v[48:63]
	ds_read_b64_tr_b16 v[92:93], v188 offset:49152
	ds_read_b64_tr_b16 v[94:95], v188 offset:49664
	v_exp_f32_e32 v112, v112
	v_exp_f32_e32 v113, v113
	v_mfma_f32_32x32x16_bf16 v[32:47], v[156:159], v[96:99], v[32:47]
	ds_read_b64_tr_b16 v[170:171], v188 offset:53248
	ds_read_b64_tr_b16 v[172:173], v188 offset:53760
	v_exp_f32_e32 v114, v114
	v_exp_f32_e32 v115, v115
	ds_read_b128 v[80:83], v234
	ds_read_b128 v[96:99], v234 offset:4096
	v_mfma_f32_32x32x16_bf16 v[48:63], v[152:155], v[100:103], v[48:63]
	ds_read_b64_tr_b16 v[178:179], v188 offset:50176
	ds_read_b64_tr_b16 v[180:181], v188 offset:50688
	v_exp_f32_e32 v116, v116
	v_exp_f32_e32 v117, v117
	ds_read_b128 v[164:167], v235
	ds_read_b128 v[140:143], v235 offset:4096
	v_mfma_f32_32x32x16_bf16 v[32:47], v[152:155], v[104:107], v[32:47]
	ds_read_b64_tr_b16 v[100:101], v188 offset:54272
	ds_read_b64_tr_b16 v[102:103], v188 offset:54784
	v_exp_f32_e32 v118, v118
	v_exp_f32_e32 v119, v119
	ds_read_b128 v[160:163], v236
	ds_read_b128 v[132:135], v236 offset:4096
	v_mfma_f32_32x32x16_bf16 v[48:63], v[148:151], v[108:111], v[48:63]
	ds_read_b64_tr_b16 v[104:105], v188 offset:51200
	ds_read_b64_tr_b16 v[106:107], v188 offset:51712
	v_exp_f32_e32 v120, v120
	v_exp_f32_e32 v121, v121
	ds_read_b128 v[136:139], v237
	ds_read_b128 v[128:131], v237 offset:4096
	v_mfma_f32_32x32x16_bf16 v[32:47], v[148:151], v[190:193], v[32:47]
	ds_read_b64_tr_b16 v[108:109], v188 offset:55296
	ds_read_b64_tr_b16 v[110:111], v188 offset:55808
	v_exp_f32_e32 v122, v122
	v_exp_f32_e32 v123, v123
	v_mfma_f32_32x32x16_bf16 v[48:63], v[144:147], v[84:87], v[48:63]
	ds_read_b64_tr_b16 v[190:191], v188 offset:52224
	ds_read_b64_tr_b16 v[192:193], v188 offset:52736
	v_exp_f32_e32 v124, v124
	v_exp_f32_e32 v125, v125
	v_mfma_f32_32x32x16_bf16 v[32:47], v[144:147], v[88:91], v[32:47]
	ds_read_b64_tr_b16 v[84:85], v188 offset:56320
	ds_read_b64_tr_b16 v[86:87], v188 offset:56832
	v_exp_f32_e32 v126, v126
	v_exp_f32_e32 v127, v127
	s_waitcnt lgkmcnt(14)
	v_mfma_f32_32x32x16_bf16 v[16:31], v[156:159], v[92:95], v[16:31]
	v_exp_f32_e32 v64, v64
	v_exp_f32_e32 v65, v65
	v_mfma_f32_32x32x16_bf16 v[0:15], v[156:159], v[170:173], v[0:15]
	v_exp_f32_e32 v66, v66
	v_exp_f32_e32 v67, v67
	v_mfma_f32_32x32x16_bf16 v[16:31], v[152:155], v[178:181], v[16:31]
	v_exp_f32_e32 v68, v68
	v_exp_f32_e32 v69, v69
	s_waitcnt lgkmcnt(12)
	v_mfma_f32_32x32x16_bf16 v[0:15], v[152:155], v[100:103], v[0:15]
	v_exp_f32_e32 v70, v70
	v_exp_f32_e32 v71, v71
	s_waitcnt lgkmcnt(8)
	v_mfma_f32_32x32x16_bf16 v[16:31], v[148:151], v[104:107], v[16:31]
	v_exp_f32_e32 v72, v72
	v_exp_f32_e32 v73, v73
	s_waitcnt lgkmcnt(4)
	v_mfma_f32_32x32x16_bf16 v[0:15], v[148:151], v[108:111], v[0:15]
	v_exp_f32_e32 v74, v74
	v_exp_f32_e32 v75, v75
	s_waitcnt lgkmcnt(2)
	v_mfma_f32_32x32x16_bf16 v[16:31], v[144:147], v[190:193], v[16:31]
	v_exp_f32_e32 v76, v76
	v_exp_f32_e32 v77, v77
	s_waitcnt lgkmcnt(0)
	v_mfma_f32_32x32x16_bf16 v[0:15], v[144:147], v[84:87], v[0:15]
	v_exp_f32_e32 v78, v78
	v_exp_f32_e32 v79, v79
	s_waitcnt vmcnt(0) lgkmcnt(0)
	s_barrier
	ds_read_b64_tr_b16 v[170:171], v188 offset:57344
	ds_read_b64_tr_b16 v[172:173], v188 offset:57856
	v_add_f32_e32 v88, v112, v113
	ds_read_b128 v[84:87], v168
	v_add_f32_e32 v88, v114, v88
	v_add_f32_e32 v88, v115, v88
	v_add_f32_e32 v88, v116, v88
	v_add_f32_e32 v104, v117, v88
	v_cvt_pk_bf16_f32 v156, v112, v113
	v_cvt_pk_bf16_f32 v157, v114, v115
	s_waitcnt lgkmcnt(0)
	v_mfma_f32_32x32x16_bf16 v[80:95], v[80:83], v[84:87], 0
	ds_read_b64_tr_b16 v[112:113], v188 offset:61440
	ds_read_b64_tr_b16 v[114:115], v188 offset:61952
	ds_read_b128 v[100:103], v168
	v_add_f32_e32 v104, v118, v104
	v_add_f32_e32 v104, v119, v104
	v_add_f32_e32 v104, v120, v104
	v_add_f32_e32 v144, v121, v104
	v_cvt_pk_bf16_f32 v158, v116, v117
	v_cvt_pk_bf16_f32 v159, v118, v119
	s_waitcnt lgkmcnt(0)
	v_mfma_f32_32x32x16_bf16 v[96:111], v[96:99], v[100:103], 0
	ds_read_b64_tr_b16 v[116:117], v188 offset:58368
	ds_read_b64_tr_b16 v[118:119], v188 offset:58880
	ds_read_b128 v[178:181], v168 offset:1024
	v_add_f32_e32 v144, v122, v144
	v_add_f32_e32 v144, v123, v144
	v_add_f32_e32 v144, v124, v144
	v_add_f32_e32 v144, v125, v144
	v_cvt_pk_bf16_f32 v152, v120, v121
	v_cvt_pk_bf16_f32 v153, v122, v123
	s_waitcnt lgkmcnt(0)
	v_mfma_f32_32x32x16_bf16 v[80:95], v[164:167], v[178:181], v[80:95]
	ds_read_b64_tr_b16 v[120:121], v188 offset:62464
	ds_read_b64_tr_b16 v[122:123], v188 offset:62976
	ds_read_b128 v[164:167], v168 offset:1024
	v_add_f32_e32 v144, v126, v144
	v_add_f32_e32 v144, v127, v144
	v_add_f32_e32 v144, v64, v144
	v_add_f32_e32 v144, v65, v144
	v_cvt_pk_bf16_f32 v154, v124, v125
	v_cvt_pk_bf16_f32 v155, v126, v127
	s_waitcnt lgkmcnt(0)
	v_mfma_f32_32x32x16_bf16 v[96:111], v[140:143], v[164:167], v[96:111]
	ds_read_b64_tr_b16 v[124:125], v188 offset:59392
	ds_read_b64_tr_b16 v[126:127], v188 offset:59904
	ds_read_b128 v[140:143], v168 offset:2048
	v_add_f32_e32 v144, v66, v144
	v_add_f32_e32 v144, v67, v144
	v_add_f32_e32 v144, v68, v144
	v_add_f32_e32 v144, v69, v144
	v_cvt_pk_bf16_f32 v148, v64, v65
	v_cvt_pk_bf16_f32 v149, v66, v67
	s_waitcnt lgkmcnt(0)
	v_mfma_f32_32x32x16_bf16 v[80:95], v[160:163], v[140:143], v[80:95]
	ds_read_b64_tr_b16 v[64:65], v188 offset:63488
	ds_read_b64_tr_b16 v[66:67], v188 offset:64000
	ds_read_b128 v[140:143], v168 offset:2048
	v_add_f32_e32 v144, v70, v144
	v_add_f32_e32 v144, v71, v144
	v_add_f32_e32 v144, v72, v144
	v_add_f32_e32 v144, v73, v144
	v_cvt_pk_bf16_f32 v150, v68, v69
	v_cvt_pk_bf16_f32 v151, v70, v71
	s_waitcnt lgkmcnt(0)
	v_mfma_f32_32x32x16_bf16 v[96:111], v[132:135], v[140:143], v[96:111]
	ds_read_b64_tr_b16 v[68:69], v188 offset:60416
	ds_read_b64_tr_b16 v[70:71], v188 offset:60928
	ds_read_b128 v[132:135], v168 offset:3072
	v_add_f32_e32 v140, v74, v144
	v_add_f32_e32 v140, v75, v140
	v_add_f32_e32 v140, v76, v140
	v_add_f32_e32 v140, v77, v140
	v_cvt_pk_bf16_f32 v144, v72, v73
	v_cvt_pk_bf16_f32 v145, v74, v75
	s_waitcnt lgkmcnt(0)
	v_mfma_f32_32x32x16_bf16 v[80:95], v[136:139], v[132:135], v[80:95]
	ds_read_b64_tr_b16 v[72:73], v188 offset:64512
	ds_read_b64_tr_b16 v[74:75], v188 offset:65024
	ds_read_b128 v[132:135], v168 offset:3072
	v_add_f32_e32 v136, v78, v140
	v_add_f32_e32 v136, v79, v136
	v_add_f32_e32 v136, 0, v136
	v_cvt_pk_bf16_f32 v146, v76, v77
	v_cvt_pk_bf16_f32 v147, v78, v79
	s_waitcnt lgkmcnt(0)
	v_mfma_f32_32x32x16_bf16 v[96:111], v[128:131], v[132:135], v[96:111]
	v_mfma_f32_32x32x16_bf16 v[48:63], v[156:159], v[170:173], v[48:63]
	ds_read_b64_tr_b16 v[76:77], v177 offset:40960
	ds_read_b64_tr_b16 v[78:79], v177 offset:41472
	v_exp_f32_e32 v80, v80
	v_exp_f32_e32 v81, v81
	v_mfma_f32_32x32x16_bf16 v[32:47], v[156:159], v[112:115], v[32:47]
	ds_read_b64_tr_b16 v[128:129], v177 offset:45056
	ds_read_b64_tr_b16 v[130:131], v177 offset:45568
	v_exp_f32_e32 v82, v82
	v_exp_f32_e32 v83, v83
	v_mfma_f32_32x32x16_bf16 v[48:63], v[152:155], v[116:119], v[48:63]
	ds_read_b64_tr_b16 v[112:113], v177 offset:41984
	ds_read_b64_tr_b16 v[114:115], v177 offset:42496
	v_exp_f32_e32 v84, v84
	v_exp_f32_e32 v85, v85
	v_mfma_f32_32x32x16_bf16 v[32:47], v[152:155], v[120:123], v[32:47]
	ds_read_b64_tr_b16 v[116:117], v177 offset:46080
	ds_read_b64_tr_b16 v[118:119], v177 offset:46592
	v_exp_f32_e32 v86, v86
	v_exp_f32_e32 v87, v87
	v_mfma_f32_32x32x16_bf16 v[48:63], v[148:151], v[124:127], v[48:63]
	ds_read_b64_tr_b16 v[120:121], v177 offset:43008
	ds_read_b64_tr_b16 v[122:123], v177 offset:43520
	v_exp_f32_e32 v88, v88
	v_exp_f32_e32 v89, v89
	v_mfma_f32_32x32x16_bf16 v[32:47], v[148:151], v[64:67], v[32:47]
	ds_read_b64_tr_b16 v[124:125], v177 offset:47104
	ds_read_b64_tr_b16 v[126:127], v177 offset:47616
	v_exp_f32_e32 v90, v90
	v_exp_f32_e32 v91, v91
	v_mfma_f32_32x32x16_bf16 v[48:63], v[144:147], v[68:71], v[48:63]
	ds_read_b64_tr_b16 v[64:65], v177 offset:44032
	ds_read_b64_tr_b16 v[66:67], v177 offset:44544
	v_exp_f32_e32 v92, v92
	v_exp_f32_e32 v93, v93
	v_mfma_f32_32x32x16_bf16 v[32:47], v[144:147], v[72:75], v[32:47]
	ds_read_b64_tr_b16 v[68:69], v177 offset:48128
	ds_read_b64_tr_b16 v[70:71], v177 offset:48640
	v_exp_f32_e32 v94, v94
	v_exp_f32_e32 v95, v95
	s_waitcnt lgkmcnt(14)
	v_mfma_f32_32x32x16_bf16 v[16:31], v[156:159], v[76:79], v[16:31]
	v_exp_f32_e32 v96, v96
	v_exp_f32_e32 v97, v97
	s_waitcnt lgkmcnt(12)
; #define SBAR() __builtin_amdgcn_sched_barrier(0)
; __device__ __forceinline__ void pv(f32x16*o,int vb,bf16x8 pa0,bf16x8 pa1,bf16x8 pa2,bf16x8 pa3){
;   #pragma unroll
;   for(int d0=0;d0<2;++d0){s16x4 lo[4],hi[4];
;     #pragma unroll
;     for(int ks=0;ks<4;++ks){
;       asm volatile("ds_read_b64_tr_b16 %0,%1 offset:%c2":"=&v"(lo[ks]):"v"(vb),"i"(d0*4096+ks*1024):"memory");
;       asm volatile("ds_read_b64_tr_b16 %0,%1 offset:%c2":"=&v"(hi[ks]):"v"(vb),"i"(d0*4096+ks*1024+512):"memory");}
;     asm volatile("s_waitcnt lgkmcnt(0)":::"memory");SBAR();
;     ...
;     o[d0]=__builtin_amdgcn_mfma_f32_32x32x16_bf16(pa0,PK(0),o[d0],0,0,0);
;     o[d0]=__builtin_amdgcn_mfma_f32_32x32x16_bf16(pa1,PK(1),o[d0],0,0,0);
;     o[d0]=__builtin_amdgcn_mfma_f32_32x32x16_bf16(pa2,PK(2),o[d0],0,0,0);
;     o[d0]=__builtin_amdgcn_mfma_f32_32x32x16_bf16(pa3,PK(3),o[d0],0,0,0);
;     ...
;   }
; }
; template<int THRL,int VM,bool NOMAX> __device__ __forceinline__ void attn_unit(const bf16*Qb,const bf16*__restrict__ Kh,const bf16*__restrict__ Vh,bf16*Ob,const int NT,const int sp,float*wscr,char*shm){
;     ...
;   int t=1;
;   for(;t+5<NT;t+=2){
;     STEP(pB0,pB1,pA0,pA1,t,true,true,true);     if constexpr(VM==2){WAIT_BAR(3);}else{WAIT_BAR(2);} RESC(); ROT();
;     STEP(pA0,pA1,pB0,pB1,t+1,true,true,true);   if constexpr(VM==2){WAIT_BAR(3);}else{WAIT_BAR(2);} RESC(); ROT();
;   }
;     ...
;   for(;t+1<NT;t+=2){
;     STEP(pB0,pB1,pA0,pA1,t,(t+3<NT),(t+1<NT),(t+1<NT));       ENDW(t);   RESC(); ROT();
;     STEP(pA0,pA1,pB0,pB1,t+1,(t+4<NT),(t+2<NT),(t+2<NT));     ENDW(t+1); RESC(); ROT();
;   }
;   STEP(pB0,pB1,pA0,pA1,NT-1,false,false,false); RESC();
;   { float sacc=pB0[0]+pB0[1]; _Pragma("unroll") for(int r=2;r<16;++r)sacc+=pB0[r]; _Pragma("unroll") for(int r=0;r<16;++r)sacc+=pB1[r]; l_reg+=sacc;
;     pw0=(u32x4){PKW(pB0,0),PKW(pB0,2),PKW(pB0,4),PKW(pB0,6)};pw1=(u32x4){PKW(pB0,8),PKW(pB0,10),PKW(pB0,12),PKW(pB0,14)};pw2=(u32x4){PKW(pB1,0),PKW(pB1,2),PKW(pB1,4),PKW(pB1,6)};pw3=(u32x4){PKW(pB1,8),PKW(pB1,10),PKW(pB1,12),PKW(pB1,14)};
;     SBAR(); pv(o,vb0+VM*sl_cur,PAF(0),PAF(1),PAF(2),PAF(3)); if constexpr(VM==2) pv(o+2,vb0+VM*sl_cur+8192,PAF(0),PAF(1),PAF(2),PAF(3)); }
;     ...
;   {auto rr=__builtin_amdgcn_permlane32_swap(__float_as_uint(l_reg),__float_as_uint(l_reg),false,false);l_reg=__uint_as_float(rr[0])+__uint_as_float(rr[1]);}
;   if(hi==0)wsf[32+r32]=l_reg;asm volatile("s_waitcnt lgkmcnt(0)":::"memory");
	v_mfma_f32_32x32x16_bf16 v[0:15], v[156:159], v[128:131], v[0:15]
	v_exp_f32_e32 v98, v98
	v_exp_f32_e32 v99, v99
	s_waitcnt lgkmcnt(10)
	v_mfma_f32_32x32x16_bf16 v[16:31], v[152:155], v[112:115], v[16:31]
	v_exp_f32_e32 v100, v100
	v_exp_f32_e32 v101, v101
	s_waitcnt lgkmcnt(8)
	v_mfma_f32_32x32x16_bf16 v[0:15], v[152:155], v[116:119], v[0:15]
	v_exp_f32_e32 v102, v102
	v_exp_f32_e32 v103, v103
	s_waitcnt lgkmcnt(6)
	v_mfma_f32_32x32x16_bf16 v[16:31], v[148:151], v[120:123], v[16:31]
	v_exp_f32_e32 v104, v104
	v_exp_f32_e32 v105, v105
	s_waitcnt lgkmcnt(4)
	v_mfma_f32_32x32x16_bf16 v[0:15], v[148:151], v[124:127], v[0:15]
	v_exp_f32_e32 v106, v106
	v_exp_f32_e32 v107, v107
	s_waitcnt lgkmcnt(2)
	v_mfma_f32_32x32x16_bf16 v[16:31], v[144:147], v[64:67], v[16:31]
	v_exp_f32_e32 v108, v108
	v_exp_f32_e32 v109, v109
	s_waitcnt lgkmcnt(0)
	v_mfma_f32_32x32x16_bf16 v[0:15], v[144:147], v[68:71], v[0:15]
	v_exp_f32_e32 v110, v110
	v_exp_f32_e32 v111, v111
	v_add_f32_e32 v64, v80, v81
	v_add_f32_e32 v64, v82, v64
	v_add_f32_e32 v64, v83, v64
	v_add_f32_e32 v64, v84, v64
	v_add_f32_e32 v64, v85, v64
	v_add_f32_e32 v64, v86, v64
	v_add_f32_e32 v64, v87, v64
	v_add_f32_e32 v64, v88, v64
	v_add_f32_e32 v64, v89, v64
	v_add_f32_e32 v64, v90, v64
	v_add_f32_e32 v64, v91, v64
	v_add_f32_e32 v64, v92, v64
	v_add_f32_e32 v64, v93, v64
	v_add_f32_e32 v64, v94, v64
	v_add_f32_e32 v64, v95, v64
	v_add_f32_e32 v64, v64, v96
	v_add_f32_e32 v64, v97, v64
	v_add_f32_e32 v64, v98, v64
	v_add_f32_e32 v64, v99, v64
	v_add_f32_e32 v64, v100, v64
	v_add_f32_e32 v64, v101, v64
	v_add_f32_e32 v64, v102, v64
	v_add_f32_e32 v64, v103, v64
	v_add_f32_e32 v64, v104, v64
	v_add_f32_e32 v64, v105, v64
	v_add_f32_e32 v64, v106, v64
	v_add_f32_e32 v64, v107, v64
	v_add_f32_e32 v64, v108, v64
	v_add_f32_e32 v64, v109, v64
	v_add_f32_e32 v64, v110, v64
	v_add_f32_e32 v64, v111, v64
	v_add_f32_e32 v65, v174, v136
	v_add_f32_e32 v64, v65, v64
	v_cvt_pk_bf16_f32 v66, v80, v81
	v_cvt_pk_bf16_f32 v67, v82, v83
	v_cvt_pk_bf16_f32 v68, v84, v85
	v_cvt_pk_bf16_f32 v69, v86, v87
	v_cvt_pk_bf16_f32 v70, v88, v89
	v_cvt_pk_bf16_f32 v71, v90, v91
	v_cvt_pk_bf16_f32 v72, v92, v93
	v_cvt_pk_bf16_f32 v73, v94, v95
	v_cvt_pk_bf16_f32 v74, v96, v97
	v_cvt_pk_bf16_f32 v75, v98, v99
	v_cvt_pk_bf16_f32 v76, v100, v101
	v_cvt_pk_bf16_f32 v77, v102, v103
	v_cvt_pk_bf16_f32 v78, v104, v105
	v_cvt_pk_bf16_f32 v79, v106, v107
	v_cvt_pk_bf16_f32 v80, v108, v109
	v_cvt_pk_bf16_f32 v81, v110, v111
	ds_read_b64_tr_b16 v[82:83],v176 offset:0
	ds_read_b64_tr_b16 v[84:85],v176 offset:512
	ds_read_b64_tr_b16 v[86:87],v176 offset:1024
	ds_read_b64_tr_b16 v[88:89],v176 offset:1536
	ds_read_b64_tr_b16 v[90:91],v176 offset:2048
	ds_read_b64_tr_b16 v[92:93],v176 offset:2560
	ds_read_b64_tr_b16 v[94:95],v176 offset:3072
	ds_read_b64_tr_b16 v[96:97],v176 offset:3584
	s_waitcnt lgkmcnt(0)
	s_nop 0
	v_mfma_f32_32x32x16_bf16 v[48:63], v[66:69], v[82:85], v[48:63]
	ds_read_b64_tr_b16 v[82:83],v176 offset:4096
	ds_read_b64_tr_b16 v[84:85],v176 offset:4608
	v_mfma_f32_32x32x16_bf16 v[48:63], v[70:73], v[86:89], v[48:63]
	ds_read_b64_tr_b16 v[86:87],v176 offset:5120
	ds_read_b64_tr_b16 v[88:89],v176 offset:5632
	v_mfma_f32_32x32x16_bf16 v[48:63], v[74:77], v[90:93], v[48:63]
	ds_read_b64_tr_b16 v[90:91],v176 offset:6144
	ds_read_b64_tr_b16 v[92:93],v176 offset:6656
	ds_read_b64_tr_b16 v[98:99],v176 offset:7168
	ds_read_b64_tr_b16 v[100:101],v176 offset:7680
	s_waitcnt lgkmcnt(0)
	v_mfma_f32_32x32x16_bf16 v[48:63], v[78:81], v[94:97], v[48:63]
	v_mfma_f32_32x32x16_bf16 v[32:47], v[66:69], v[82:85], v[32:47]
	v_add_u32_e32 v65, 0x2000, v176
	ds_read_b64_tr_b16 v[82:83],v65 offset:0
	ds_read_b64_tr_b16 v[84:85],v65 offset:512
	v_mfma_f32_32x32x16_bf16 v[32:47], v[70:73], v[86:89], v[32:47]
	ds_read_b64_tr_b16 v[86:87],v65 offset:1024
	ds_read_b64_tr_b16 v[88:89],v65 offset:1536
	v_mfma_f32_32x32x16_bf16 v[32:47], v[74:77], v[90:93], v[32:47]
	ds_read_b64_tr_b16 v[90:91],v65 offset:2048
	ds_read_b64_tr_b16 v[92:93],v65 offset:2560
	ds_read_b64_tr_b16 v[94:95],v65 offset:3072
	ds_read_b64_tr_b16 v[96:97],v65 offset:3584
	s_waitcnt lgkmcnt(0)
	v_mfma_f32_32x32x16_bf16 v[32:47], v[78:81], v[98:101], v[32:47]
	v_mfma_f32_32x32x16_bf16 v[16:31], v[66:69], v[82:85], v[16:31]
	ds_read_b64_tr_b16 v[82:83],v65 offset:4096
	ds_read_b64_tr_b16 v[84:85],v65 offset:4608
	v_mfma_f32_32x32x16_bf16 v[16:31], v[70:73], v[86:89], v[16:31]
	ds_read_b64_tr_b16 v[86:87],v65 offset:5120
	ds_read_b64_tr_b16 v[88:89],v65 offset:5632
	v_mfma_f32_32x32x16_bf16 v[16:31], v[74:77], v[90:93], v[16:31]
	ds_read_b64_tr_b16 v[90:91],v65 offset:6144
	ds_read_b64_tr_b16 v[92:93],v65 offset:6656
	ds_read_b64_tr_b16 v[98:99],v65 offset:7168
	ds_read_b64_tr_b16 v[100:101],v65 offset:7680
	s_waitcnt lgkmcnt(0)
	v_mfma_f32_32x32x16_bf16 v[16:31], v[78:81], v[94:97], v[16:31]
	v_mfma_f32_32x32x16_bf16 v[0:15], v[66:69], v[82:85], v[0:15]
	v_mov_b32_e32 v65, v64
	s_nop 1
	v_permlane32_swap_b32_e32 v64, v65
	v_cmp_gt_u32_e32 vcc, 32, v187
	v_mfma_f32_32x32x16_bf16 v[0:15], v[70:73], v[86:89], v[0:15]
	v_mfma_f32_32x32x16_bf16 v[0:15], v[74:77], v[90:93], v[0:15]
	v_mfma_f32_32x32x16_bf16 v[0:15], v[78:81], v[98:101], v[0:15]
	s_and_saveexec_b64 s[16:17], vcc
	s_cbranch_execz .LBB0_870
	v_add_f32_e32 v64, v64, v65
	v_lshl_add_u32 v65, v186, 2, s34
	ds_write_b32 v65, v64 offset:128
	s_branch .LBB0_870

.LBB0_882:
	v_mfma_f32_32x32x16_bf16 v[96:111], v[84:87], v[156:159], 0
	v_add_u32_e32 v187, s54, v182
	ds_read_b64_tr_b16 v[188:189], v187 offset:24576
	ds_read_b64_tr_b16 v[190:191], v187 offset:25088
	v_add_f32_e32 v88, v64, v65
	v_add_f32_e32 v88, v66, v88
	v_add_f32_e32 v88, v67, v88
	v_add_f32_e32 v88, v68, v88
	v_add_f32_e32 v88, v69, v88
	v_cvt_pk_bf16_f32 v140, v64, v65
	v_cvt_pk_bf16_f32 v141, v66, v67
	ds_read_b64_tr_b16 v[64:65], v187 offset:28672
	ds_read_b64_tr_b16 v[66:67], v187 offset:29184
	v_add_f32_e32 v84, v70, v88
	v_add_f32_e32 v84, v71, v84
	v_add_f32_e32 v84, v72, v84
	v_add_f32_e32 v128, v73, v84
	s_waitcnt lgkmcnt(10)
	v_mfma_f32_32x32x16_bf16 v[80:95], v[80:83], v[156:159], 0
	v_lshl_add_u64 v[238:239], v[176:177], 0, s[38:39]
	s_add_i32 s53, s52, s33
	s_mov_b32 s54, m0
	s_mov_b32 m0, s53
	s_nop 0
	global_load_lds_dwordx4 v[238:239], off
	s_mov_b32 m0, s54
	v_cvt_pk_bf16_f32 v142, v68, v69
	v_cvt_pk_bf16_f32 v143, v70, v71
	ds_read_b64_tr_b16 v[68:69], v187 offset:25600
	ds_read_b64_tr_b16 v[70:71], v187 offset:26112
	v_add_f32_e32 v128, v74, v128
	v_add_f32_e32 v128, v75, v128
	v_add_f32_e32 v128, v76, v128
	v_add_f32_e32 v128, v77, v128
	v_cvt_pk_bf16_f32 v136, v72, v73
	v_cvt_pk_bf16_f32 v137, v74, v75
	s_waitcnt lgkmcnt(11)
	v_mfma_f32_32x32x16_bf16 v[96:111], v[164:167], v[152:155], v[96:111]
	v_lshl_add_u64 v[238:239], v[174:175], 0, s[38:39]
	s_add_i32 s53, s35, s16
	s_mov_b32 s54, m0
	s_mov_b32 m0, s53
	s_nop 0
	global_load_lds_dwordx4 v[238:239], off
	s_mov_b32 m0, s54
	ds_read_b64_tr_b16 v[72:73], v187 offset:29696
	ds_read_b64_tr_b16 v[74:75], v187 offset:30208
	s_waitcnt lgkmcnt(12)
	v_mfma_f32_32x32x16_bf16 v[80:95], v[160:163], v[152:155], v[80:95]
	v_add_f32_e32 v128, v78, v128
	v_add_f32_e32 v128, v79, v128
	v_add_f32_e32 v128, v48, v128
	v_add_f32_e32 v128, v49, v128
	v_cvt_pk_bf16_f32 v138, v76, v77
	v_cvt_pk_bf16_f32 v139, v78, v79
	ds_read_b64_tr_b16 v[76:77], v187 offset:26624
	ds_read_b64_tr_b16 v[78:79], v187 offset:27136
	v_add_f32_e32 v128, v50, v128
	v_add_f32_e32 v128, v51, v128
	v_add_f32_e32 v128, v52, v128
	v_add_f32_e32 v128, v53, v128
	v_cvt_pk_bf16_f32 v132, v48, v49
	v_cvt_pk_bf16_f32 v133, v50, v51
	s_waitcnt lgkmcnt(13)
	v_mfma_f32_32x32x16_bf16 v[96:111], v[124:127], v[148:151], v[96:111]
	ds_read_b64_tr_b16 v[48:49], v187 offset:30720
	ds_read_b64_tr_b16 v[50:51], v187 offset:31232
	s_waitcnt lgkmcnt(14)
	v_mfma_f32_32x32x16_bf16 v[80:95], v[120:123], v[148:151], v[80:95]
	v_add_f32_e32 v124, v54, v128
	v_add_f32_e32 v124, v55, v124
	v_add_f32_e32 v124, v56, v124
	v_add_f32_e32 v124, v57, v124
	v_cvt_pk_bf16_f32 v134, v52, v53
	v_cvt_pk_bf16_f32 v135, v54, v55
	ds_read_b64_tr_b16 v[52:53], v187 offset:27648
	ds_read_b64_tr_b16 v[54:55], v187 offset:28160
	v_add_f32_e32 v120, v58, v124
	v_add_f32_e32 v120, v59, v120
	v_add_f32_e32 v120, v60, v120
	v_add_f32_e32 v120, v61, v120
	v_cvt_pk_bf16_f32 v128, v56, v57
	v_cvt_pk_bf16_f32 v129, v58, v59
	s_waitcnt lgkmcnt(14)
	v_mfma_f32_32x32x16_bf16 v[96:111], v[116:119], v[144:147], v[96:111]
	ds_read_b64_tr_b16 v[56:57], v187 offset:31744
	ds_read_b64_tr_b16 v[58:59], v187 offset:32256
	v_mfma_f32_32x32x16_bf16 v[80:95], v[112:115], v[144:147], v[80:95]
	v_add_f32_e32 v116, v62, v120
	v_add_f32_e32 v116, v63, v116
	v_add_f32_e32 v116, 0, v116
	v_cvt_pk_bf16_f32 v130, v60, v61
	v_cvt_pk_bf16_f32 v131, v62, v63
	v_add_f32_e32 v202, v186, v116
	s_waitcnt lgkmcnt(14)
	v_mfma_f32_32x32x16_bf16 v[16:31], v[140:143], v[188:191], v[16:31]
	v_exp_f32_e32 v96, v96
	v_exp_f32_e32 v97, v97
	v_exp_f32_e32 v98, v98
	v_exp_f32_e32 v99, v99
	s_waitcnt lgkmcnt(12)
	v_mfma_f32_32x32x16_bf16 v[32:47], v[140:143], v[64:67], v[32:47]
	v_exp_f32_e32 v100, v100
	v_exp_f32_e32 v101, v101
	v_exp_f32_e32 v102, v102
	v_exp_f32_e32 v103, v103
	v_add_u32_e32 v242, s35, v234
	v_add_u32_e32 v243, s35, v235
	v_add_u32_e32 v244, s35, v236
	v_add_u32_e32 v245, s35, v237
	ds_read_b128 v[60:63], v242
	ds_read_b128 v[112:115], v242 offset:4096
	s_waitcnt lgkmcnt(12)
	v_mfma_f32_32x32x16_bf16 v[16:31], v[136:139], v[68:71], v[16:31]
	v_exp_f32_e32 v104, v104
	v_exp_f32_e32 v105, v105
	v_exp_f32_e32 v106, v106
	v_exp_f32_e32 v107, v107
	ds_read_b128 v[116:119], v243
	ds_read_b128 v[120:123], v243 offset:4096
	s_waitcnt lgkmcnt(12)
	v_mfma_f32_32x32x16_bf16 v[32:47], v[136:139], v[72:75], v[32:47]
	v_exp_f32_e32 v108, v108
	v_exp_f32_e32 v109, v109
	v_exp_f32_e32 v110, v110
	v_exp_f32_e32 v111, v111
	ds_read_b128 v[124:127], v244
	ds_read_b128 v[160:163], v244 offset:4096
	s_waitcnt lgkmcnt(12)
	v_mfma_f32_32x32x16_bf16 v[16:31], v[132:135], v[76:79], v[16:31]
	v_exp_f32_e32 v80, v80
	v_exp_f32_e32 v81, v81
	v_exp_f32_e32 v82, v82
	v_exp_f32_e32 v83, v83
	ds_read_b128 v[164:167], v245
	ds_read_b128 v[186:189], v245 offset:4096
	s_waitcnt lgkmcnt(12)
	v_mfma_f32_32x32x16_bf16 v[32:47], v[132:135], v[48:51], v[32:47]
	v_exp_f32_e32 v84, v84
	v_exp_f32_e32 v85, v85
	v_exp_f32_e32 v86, v86
	v_exp_f32_e32 v87, v87
	s_waitcnt lgkmcnt(10)
	v_mfma_f32_32x32x16_bf16 v[16:31], v[128:131], v[52:55], v[16:31]
	v_exp_f32_e32 v88, v88
	v_exp_f32_e32 v89, v89
	v_exp_f32_e32 v90, v90
	v_exp_f32_e32 v91, v91
	s_waitcnt lgkmcnt(8)
	v_mfma_f32_32x32x16_bf16 v[32:47], v[128:131], v[56:59], v[32:47]
	v_exp_f32_e32 v92, v92
	v_exp_f32_e32 v93, v93
	v_exp_f32_e32 v94, v94
	v_exp_f32_e32 v95, v95
	s_waitcnt vmcnt(2) lgkmcnt(0)
	s_barrier
; #define WAIT_BAR(N) asm volatile("s_waitcnt vmcnt(" #N ") lgkmcnt(0)\n\ts_barrier":::"memory")
;   #define RESC() do{ if(!NOMAX&&resc){ asm volatile("s_waitcnt lgkmcnt(0)":::"memory"); \
;       _Pragma("unroll") for(int d_=0;d_<2*VM;++d_) _Pragma("unroll") for(int r=0;r<16;++r)o[d_][r]*=wsf[crow(r,hi)]; } }while(0)
;   #define ROT() do{sl_prev=sl_cur;sl_cur=sl_next;sl_next=(sl_next==(NSLOT-1)*SLOTB)?0:sl_next+SLOTB;}while(0)
; template<int THRL,int VM,bool NOMAX> __device__ __forceinline__ void attn_unit(const bf16*Qb,const bf16*__restrict__ Kh,const bf16*__restrict__ Vh,bf16*Ob,const int NT,const int sp,float*wscr,char*shm){
;     ...
;   int t=1;
;   for(;t+5<NT;t+=2){
;     STEP(pB0,pB1,pA0,pA1,t,true,true,true);     if constexpr(VM==2){WAIT_BAR(3);}else{WAIT_BAR(2);} RESC(); ROT();
;     STEP(pA0,pA1,pB0,pB1,t+1,true,true,true);   if constexpr(VM==2){WAIT_BAR(3);}else{WAIT_BAR(2);} RESC(); ROT();
	v_mfma_f32_32x32x16_bf16 v[64:79], v[60:63], v[156:159], 0
	s_add_i32 s53, s35, 0x2000
	s_cmpk_lg_i32 s35, 0x4000
	s_cselect_b32 s53, s53, 0
	v_add_u32_e32 v203, s52, v182
	ds_read_b64_tr_b16 v[190:191], v203 offset:24576
	ds_read_b64_tr_b16 v[192:193], v203 offset:25088
	v_add_f32_e32 v48, v96, v97
	v_add_f32_e32 v48, v98, v48
	v_add_f32_e32 v48, v99, v48
	v_add_f32_e32 v48, v100, v48
	v_add_f32_e32 v48, v101, v48
	v_cvt_pk_bf16_f32 v140, v96, v97
	v_cvt_pk_bf16_f32 v141, v98, v99
	ds_read_b64_tr_b16 v[96:97], v203 offset:28672
	ds_read_b64_tr_b16 v[98:99], v203 offset:29184
	v_add_f32_e32 v48, v102, v48
	v_add_f32_e32 v48, v103, v48
	v_add_f32_e32 v48, v104, v48
	v_add_f32_e32 v128, v105, v48
	s_waitcnt lgkmcnt(10)
	v_mfma_f32_32x32x16_bf16 v[48:63], v[112:115], v[156:159], 0
	s_add_i32 s52, s35, s33
	s_mov_b32 s54, m0
	s_mov_b32 m0, s52
	s_nop 0
	global_load_lds_dwordx4 v[176:177], off
	s_mov_b32 m0, s54
	v_cvt_pk_bf16_f32 v142, v100, v101
	v_cvt_pk_bf16_f32 v143, v102, v103
	ds_read_b64_tr_b16 v[100:101], v203 offset:25600
	ds_read_b64_tr_b16 v[102:103], v203 offset:26112
	s_waitcnt lgkmcnt(11)
	v_mfma_f32_32x32x16_bf16 v[64:79], v[116:119], v[152:155], v[64:79]
	s_add_i32 s52, s53, s16
	s_mov_b32 s54, m0
	s_mov_b32 m0, s52
	s_nop 0
	global_load_lds_dwordx4 v[174:175], off
	s_mov_b32 m0, s54
	v_add_f32_e32 v112, v106, v128
	v_add_f32_e32 v112, v107, v112
	v_add_f32_e32 v112, v108, v112
	v_add_f32_e32 v112, v109, v112
	v_cvt_pk_bf16_f32 v136, v104, v105
	v_cvt_pk_bf16_f32 v137, v106, v107
	ds_read_b64_tr_b16 v[104:105], v203 offset:29696
	ds_read_b64_tr_b16 v[106:107], v203 offset:30208
	s_waitcnt lgkmcnt(12)
	v_mfma_f32_32x32x16_bf16 v[48:63], v[120:123], v[152:155], v[48:63]
	v_add_f32_e32 v112, v110, v112
	v_add_f32_e32 v112, v111, v112
	v_add_f32_e32 v112, v80, v112
	v_add_f32_e32 v112, v81, v112
	v_cvt_pk_bf16_f32 v138, v108, v109
	v_cvt_pk_bf16_f32 v139, v110, v111
	ds_read_b64_tr_b16 v[108:109], v203 offset:26624
	ds_read_b64_tr_b16 v[110:111], v203 offset:27136
	s_waitcnt lgkmcnt(13)
	v_mfma_f32_32x32x16_bf16 v[64:79], v[124:127], v[148:151], v[64:79]
	v_add_f32_e32 v112, v82, v112
	v_add_f32_e32 v112, v83, v112
	v_add_f32_e32 v112, v84, v112
	v_add_f32_e32 v112, v85, v112
	v_cvt_pk_bf16_f32 v132, v80, v81
	v_cvt_pk_bf16_f32 v133, v82, v83
	ds_read_b64_tr_b16 v[194:195], v203 offset:30720
	ds_read_b64_tr_b16 v[196:197], v203 offset:31232
	s_waitcnt lgkmcnt(14)
	v_mfma_f32_32x32x16_bf16 v[48:63], v[160:163], v[148:151], v[48:63]
	v_add_f32_e32 v80, v86, v112
	v_add_f32_e32 v80, v87, v80
	v_add_f32_e32 v80, v88, v80
	v_add_f32_e32 v80, v89, v80
	v_cvt_pk_bf16_f32 v134, v84, v85
	v_cvt_pk_bf16_f32 v135, v86, v87
	ds_read_b64_tr_b16 v[198:199], v203 offset:27648
	ds_read_b64_tr_b16 v[200:201], v203 offset:28160
	s_waitcnt lgkmcnt(14)
	v_mfma_f32_32x32x16_bf16 v[64:79], v[164:167], v[144:147], v[64:79]
	v_add_f32_e32 v80, v90, v80
	v_add_f32_e32 v80, v91, v80
	v_add_f32_e32 v80, v92, v80
	v_add_f32_e32 v80, v93, v80
	v_cvt_pk_bf16_f32 v128, v88, v89
	v_cvt_pk_bf16_f32 v129, v90, v91
	ds_read_b64_tr_b16 v[88:89], v203 offset:31744
	ds_read_b64_tr_b16 v[90:91], v203 offset:32256
	v_mfma_f32_32x32x16_bf16 v[48:63], v[186:189], v[144:147], v[48:63]
	v_add_f32_e32 v80, v94, v80
	v_add_f32_e32 v80, v95, v80
	v_add_f32_e32 v80, 0, v80
	v_cvt_pk_bf16_f32 v130, v92, v93
	v_cvt_pk_bf16_f32 v131, v94, v95
	v_add_f32_e32 v186, v202, v80
	s_waitcnt lgkmcnt(14)
	v_mfma_f32_32x32x16_bf16 v[16:31], v[140:143], v[190:193], v[16:31]
	v_exp_f32_e32 v64, v64
	v_exp_f32_e32 v65, v65
	v_exp_f32_e32 v66, v66
	v_exp_f32_e32 v67, v67
	s_waitcnt lgkmcnt(12)
	v_mfma_f32_32x32x16_bf16 v[32:47], v[140:143], v[96:99], v[32:47]
	v_exp_f32_e32 v68, v68
	v_exp_f32_e32 v69, v69
	v_exp_f32_e32 v70, v70
	v_exp_f32_e32 v71, v71
	v_add_u32_e32 v242, s53, v234
	v_add_u32_e32 v243, s53, v235
	v_add_u32_e32 v244, s53, v236
	v_add_u32_e32 v245, s53, v237
	ds_read_b128 v[84:87], v242
	ds_read_b128 v[80:83], v242 offset:4096
	s_waitcnt lgkmcnt(12)
	v_mfma_f32_32x32x16_bf16 v[16:31], v[136:139], v[100:103], v[16:31]
	v_exp_f32_e32 v72, v72
	v_exp_f32_e32 v73, v73
	v_exp_f32_e32 v74, v74
	v_exp_f32_e32 v75, v75
	ds_read_b128 v[164:167], v243
	ds_read_b128 v[160:163], v243 offset:4096
	s_waitcnt lgkmcnt(12)
	v_mfma_f32_32x32x16_bf16 v[32:47], v[136:139], v[104:107], v[32:47]
	v_exp_f32_e32 v76, v76
	v_exp_f32_e32 v77, v77
	v_exp_f32_e32 v78, v78
	v_exp_f32_e32 v79, v79
	ds_read_b128 v[124:127], v244
	ds_read_b128 v[120:123], v244 offset:4096
	s_waitcnt lgkmcnt(12)
	v_mfma_f32_32x32x16_bf16 v[16:31], v[132:135], v[108:111], v[16:31]
	v_exp_f32_e32 v48, v48
	v_exp_f32_e32 v49, v49
	v_exp_f32_e32 v50, v50
	v_exp_f32_e32 v51, v51
	ds_read_b128 v[116:119], v245
	ds_read_b128 v[112:115], v245 offset:4096
	s_waitcnt lgkmcnt(12)
	v_mfma_f32_32x32x16_bf16 v[32:47], v[132:135], v[194:197], v[32:47]
	v_exp_f32_e32 v52, v52
	v_exp_f32_e32 v53, v53
	v_exp_f32_e32 v54, v54
	v_exp_f32_e32 v55, v55
	s_waitcnt lgkmcnt(10)
	v_mfma_f32_32x32x16_bf16 v[16:31], v[128:131], v[198:201], v[16:31]
	v_exp_f32_e32 v56, v56
	v_exp_f32_e32 v57, v57
	v_exp_f32_e32 v58, v58
	v_exp_f32_e32 v59, v59
	s_waitcnt lgkmcnt(8)
	v_mfma_f32_32x32x16_bf16 v[32:47], v[128:131], v[88:91], v[32:47]
	v_exp_f32_e32 v60, v60
	v_exp_f32_e32 v61, v61
	v_exp_f32_e32 v62, v62
	v_exp_f32_e32 v63, v63
	s_add_i32 s55, s53, 0x2000
	s_waitcnt vmcnt(2) lgkmcnt(0)
	s_barrier
	s_cmpk_lg_i32 s53, 0x4000
	s_mov_b32 s54, s35
	s_cselect_b32 s35, s55, 0
	s_add_i32 s34, s34, 2
	v_lshl_add_u64 v[174:175], v[174:175], 0, s[8:9]
	v_lshl_add_u64 v[176:177], v[176:177], 0, s[8:9]
	s_mov_b32 s52, s53
	s_cmpk_lt_u32 s34, 0x79
	s_cbranch_scc1 .LBB0_882
	s_and_b32 s29, s29, 0x3fffffc0
	s_lshl_b32 s29, s29, 2
	s_add_i32 s29, s29, 0
	s_cmp_lg_u32 0, -1
	s_cselect_b32 s34, 0, 0
	s_add_i32 s35, s34, 0x6000
	v_add3_u32 v174, v185, s35, v184
	ds_read_b64_tr_b16 v[188:189], v182 offset:40960
	ds_read_b64_tr_b16 v[190:191], v182 offset:41472
	v_add_f32_e32 v88, v64, v65
	v_add_f32_e32 v88, v66, v88
	v_add_f32_e32 v88, v67, v88
	v_add_f32_e32 v88, v68, v88
	v_add_f32_e32 v88, v69, v88
	v_cvt_pk_bf16_f32 v140, v64, v65
	v_cvt_pk_bf16_f32 v141, v66, v67
	s_waitcnt lgkmcnt(9)
	v_mfma_f32_32x32x16_bf16 v[96:111], v[84:87], v[156:159], 0
	ds_read_b64_tr_b16 v[64:65], v182 offset:45056
	ds_read_b64_tr_b16 v[66:67], v182 offset:45568
	v_add_f32_e32 v84, v70, v88
	v_add_f32_e32 v84, v71, v84
	v_add_f32_e32 v84, v72, v84
	v_add_f32_e32 v128, v73, v84
	v_cvt_pk_bf16_f32 v142, v68, v69
	v_cvt_pk_bf16_f32 v143, v70, v71
	s_waitcnt lgkmcnt(10)
	v_mfma_f32_32x32x16_bf16 v[80:95], v[80:83], v[156:159], 0
	ds_read_b64_tr_b16 v[68:69], v182 offset:41984
	ds_read_b64_tr_b16 v[70:71], v182 offset:42496
	v_add_f32_e32 v128, v74, v128
	v_add_f32_e32 v128, v75, v128
	v_add_f32_e32 v128, v76, v128
	v_add_f32_e32 v128, v77, v128
	v_cvt_pk_bf16_f32 v136, v72, v73
	v_cvt_pk_bf16_f32 v137, v74, v75
	s_waitcnt lgkmcnt(11)
	v_mfma_f32_32x32x16_bf16 v[96:111], v[164:167], v[152:155], v[96:111]
	ds_read_b64_tr_b16 v[72:73], v182 offset:46080
	ds_read_b64_tr_b16 v[74:75], v182 offset:46592
	v_add_f32_e32 v128, v78, v128
	v_add_f32_e32 v128, v79, v128
	v_add_f32_e32 v128, v48, v128
	v_add_f32_e32 v128, v49, v128
	v_cvt_pk_bf16_f32 v138, v76, v77
	v_cvt_pk_bf16_f32 v139, v78, v79
	s_waitcnt lgkmcnt(12)
	v_mfma_f32_32x32x16_bf16 v[80:95], v[160:163], v[152:155], v[80:95]
	ds_read_b64_tr_b16 v[76:77], v182 offset:43008
	ds_read_b64_tr_b16 v[78:79], v182 offset:43520
	v_add_f32_e32 v128, v50, v128
	v_add_f32_e32 v128, v51, v128
	v_add_f32_e32 v128, v52, v128
	v_add_f32_e32 v128, v53, v128
	v_cvt_pk_bf16_f32 v132, v48, v49
	v_cvt_pk_bf16_f32 v133, v50, v51
	s_waitcnt lgkmcnt(13)
	v_mfma_f32_32x32x16_bf16 v[96:111], v[124:127], v[148:151], v[96:111]
	ds_read_b64_tr_b16 v[48:49], v182 offset:47104
	ds_read_b64_tr_b16 v[50:51], v182 offset:47616
	v_add_f32_e32 v124, v54, v128
	v_add_f32_e32 v124, v55, v124
	v_add_f32_e32 v124, v56, v124
	v_add_f32_e32 v124, v57, v124
	v_cvt_pk_bf16_f32 v134, v52, v53
	v_cvt_pk_bf16_f32 v135, v54, v55
	s_waitcnt lgkmcnt(14)
	v_mfma_f32_32x32x16_bf16 v[80:95], v[120:123], v[148:151], v[80:95]
	ds_read_b64_tr_b16 v[52:53], v182 offset:44032
	ds_read_b64_tr_b16 v[54:55], v182 offset:44544
	v_add_f32_e32 v120, v58, v124
	v_add_f32_e32 v120, v59, v120
	v_add_f32_e32 v120, v60, v120
	v_add_f32_e32 v120, v61, v120
	v_cvt_pk_bf16_f32 v128, v56, v57
	v_cvt_pk_bf16_f32 v129, v58, v59
	s_waitcnt lgkmcnt(14)
	v_mfma_f32_32x32x16_bf16 v[96:111], v[116:119], v[144:147], v[96:111]
	ds_read_b64_tr_b16 v[56:57], v182 offset:48128
	ds_read_b64_tr_b16 v[58:59], v182 offset:48640
	v_add_f32_e32 v116, v62, v120
	v_add_f32_e32 v116, v63, v116
	v_add_f32_e32 v116, 0, v116
	v_cvt_pk_bf16_f32 v130, v60, v61
	v_cvt_pk_bf16_f32 v131, v62, v63
	v_mfma_f32_32x32x16_bf16 v[80:95], v[112:115], v[144:147], v[80:95]
	v_lshl_add_u64 v[60:61], v[172:173], 0, s[40:41]
	s_mov_b32 s35, m0
	s_mov_b32 m0, s33
	s_nop 0
	global_load_lds_dwordx4 v[60:61], off
	s_mov_b32 m0, s35
	s_add_i32 s33, s34, s17
	v_lshl_add_u64 v[60:61], v[170:171], 0, s[42:43]
	s_add_i32 s17, s33, 0x8000
	s_mov_b32 s34, m0
	s_mov_b32 m0, s17
	s_nop 0
	global_load_lds_dwordx4 v[60:61], off
	s_mov_b32 m0, s34
	v_add_f32_e32 v175, v186, v116
	s_waitcnt lgkmcnt(14)
	v_mfma_f32_32x32x16_bf16 v[16:31], v[140:143], v[188:191], v[16:31]
	v_exp_f32_e32 v96, v96
	v_exp_f32_e32 v97, v97
	v_exp_f32_e32 v98, v98
	v_exp_f32_e32 v99, v99
	s_waitcnt lgkmcnt(12)
	v_mfma_f32_32x32x16_bf16 v[32:47], v[140:143], v[64:67], v[32:47]
	v_exp_f32_e32 v100, v100
	v_exp_f32_e32 v101, v101
	v_exp_f32_e32 v102, v102
	v_exp_f32_e32 v103, v103
	ds_read_b128 v[60:63], v234 offset:8192
	ds_read_b128 v[64:67], v234 offset:12288
	s_waitcnt lgkmcnt(12)
	v_mfma_f32_32x32x16_bf16 v[16:31], v[136:139], v[68:71], v[16:31]
	v_exp_f32_e32 v104, v104
	v_exp_f32_e32 v105, v105
	v_exp_f32_e32 v106, v106
	v_exp_f32_e32 v107, v107
	ds_read_b128 v[68:71], v235 offset:8192
	ds_read_b128 v[160:163], v235 offset:12288
	s_waitcnt lgkmcnt(12)
	v_mfma_f32_32x32x16_bf16 v[32:47], v[136:139], v[72:75], v[32:47]
	v_exp_f32_e32 v108, v108
	v_exp_f32_e32 v109, v109
	v_exp_f32_e32 v110, v110
	v_exp_f32_e32 v111, v111
	ds_read_b128 v[72:75], v236 offset:8192
	ds_read_b128 v[164:167], v236 offset:12288
	s_waitcnt lgkmcnt(12)
	v_mfma_f32_32x32x16_bf16 v[16:31], v[132:135], v[76:79], v[16:31]
	v_exp_f32_e32 v80, v80
	v_exp_f32_e32 v81, v81
	v_exp_f32_e32 v82, v82
	v_exp_f32_e32 v83, v83
	ds_read_b128 v[76:79], v237 offset:8192
	ds_read_b128 v[184:187], v237 offset:12288
	s_waitcnt lgkmcnt(12)
	v_mfma_f32_32x32x16_bf16 v[32:47], v[132:135], v[48:51], v[32:47]
	v_exp_f32_e32 v84, v84
	v_exp_f32_e32 v85, v85
	v_exp_f32_e32 v86, v86
	v_exp_f32_e32 v87, v87
	s_waitcnt lgkmcnt(10)
	v_mfma_f32_32x32x16_bf16 v[16:31], v[128:131], v[52:55], v[16:31]
	v_exp_f32_e32 v88, v88
	v_exp_f32_e32 v89, v89
	v_exp_f32_e32 v90, v90
	v_exp_f32_e32 v91, v91
	s_waitcnt lgkmcnt(8)
	v_mfma_f32_32x32x16_bf16 v[32:47], v[128:131], v[56:59], v[32:47]
	v_exp_f32_e32 v92, v92
	v_exp_f32_e32 v93, v93
	v_exp_f32_e32 v94, v94
	v_exp_f32_e32 v95, v95
	s_waitcnt vmcnt(2) lgkmcnt(0)
	s_barrier
	ds_read_b64_tr_b16 v[188:189], v182 offset:24576
	ds_read_b64_tr_b16 v[190:191], v182 offset:25088
	v_add_f32_e32 v48, v96, v97
	v_add_f32_e32 v48, v98, v48
	v_add_f32_e32 v48, v99, v48
	v_add_f32_e32 v48, v100, v48
	v_add_f32_e32 v48, v101, v48
	v_cvt_pk_bf16_f32 v140, v96, v97
	v_cvt_pk_bf16_f32 v141, v98, v99
	s_waitcnt lgkmcnt(9)
	v_mfma_f32_32x32x16_bf16 v[112:127], v[60:63], v[156:159], 0
	ds_read_b64_tr_b16 v[96:97], v182 offset:28672
	ds_read_b64_tr_b16 v[98:99], v182 offset:29184
	v_add_f32_e32 v48, v102, v48
	v_add_f32_e32 v48, v103, v48
	v_add_f32_e32 v48, v104, v48
	v_add_f32_e32 v128, v105, v48
	s_waitcnt lgkmcnt(10)
	v_mfma_f32_32x32x16_bf16 v[48:63], v[64:67], v[156:159], 0
	v_cvt_pk_bf16_f32 v142, v100, v101
	v_cvt_pk_bf16_f32 v143, v102, v103
	ds_read_b64_tr_b16 v[64:65], v182 offset:25600
	ds_read_b64_tr_b16 v[66:67], v182 offset:26112
	v_add_f32_e32 v100, v106, v128
	v_add_f32_e32 v100, v107, v100
	v_add_f32_e32 v100, v108, v100
	v_add_f32_e32 v100, v109, v100
	v_cvt_pk_bf16_f32 v136, v104, v105
	v_cvt_pk_bf16_f32 v137, v106, v107
	s_waitcnt lgkmcnt(11)
	v_mfma_f32_32x32x16_bf16 v[112:127], v[68:71], v[152:155], v[112:127]
	ds_read_b64_tr_b16 v[68:69], v182 offset:29696
	ds_read_b64_tr_b16 v[70:71], v182 offset:30208
	s_waitcnt lgkmcnt(12)
	v_mfma_f32_32x32x16_bf16 v[48:63], v[160:163], v[152:155], v[48:63]
	v_add_f32_e32 v100, v110, v100
	v_add_f32_e32 v100, v111, v100
	v_add_f32_e32 v100, v80, v100
	v_add_f32_e32 v104, v81, v100
	v_cvt_pk_bf16_f32 v138, v108, v109
	v_cvt_pk_bf16_f32 v139, v110, v111
	ds_read_b64_tr_b16 v[100:101], v182 offset:26624
	ds_read_b64_tr_b16 v[102:103], v182 offset:27136
	v_add_f32_e32 v104, v82, v104
	v_add_f32_e32 v104, v83, v104
	v_add_f32_e32 v104, v84, v104
	v_add_f32_e32 v104, v85, v104
	v_cvt_pk_bf16_f32 v132, v80, v81
	v_cvt_pk_bf16_f32 v133, v82, v83
	s_waitcnt lgkmcnt(13)
	v_mfma_f32_32x32x16_bf16 v[112:127], v[72:75], v[148:151], v[112:127]
	ds_read_b64_tr_b16 v[72:73], v182 offset:30720
	ds_read_b64_tr_b16 v[74:75], v182 offset:31232
	s_waitcnt lgkmcnt(14)
	v_mfma_f32_32x32x16_bf16 v[48:63], v[164:167], v[148:151], v[48:63]
	v_add_f32_e32 v80, v86, v104
	v_add_f32_e32 v80, v87, v80
	v_add_f32_e32 v80, v88, v80
	v_add_f32_e32 v104, v89, v80
	v_cvt_pk_bf16_f32 v134, v84, v85
	v_cvt_pk_bf16_f32 v135, v86, v87
	ds_read_b64_tr_b16 v[80:81], v182 offset:27648
	ds_read_b64_tr_b16 v[82:83], v182 offset:28160
	v_add_f32_e32 v84, v90, v104
	v_add_f32_e32 v84, v91, v84
	v_add_f32_e32 v84, v92, v84
	v_add_f32_e32 v84, v93, v84
	v_cvt_pk_bf16_f32 v128, v88, v89
	v_cvt_pk_bf16_f32 v129, v90, v91
	s_waitcnt lgkmcnt(14)
	v_mfma_f32_32x32x16_bf16 v[112:127], v[76:79], v[144:147], v[112:127]
	ds_read_b64_tr_b16 v[76:77], v182 offset:31744
	ds_read_b64_tr_b16 v[78:79], v182 offset:32256
	v_mfma_f32_32x32x16_bf16 v[48:63], v[184:187], v[144:147], v[48:63]
	v_add_f32_e32 v84, v94, v84
	v_add_f32_e32 v84, v95, v84
	v_add_f32_e32 v84, 0, v84
	v_cvt_pk_bf16_f32 v130, v92, v93
	v_cvt_pk_bf16_f32 v131, v94, v95
	s_nop 0
	v_add_f32_e32 v175, v175, v84
	v_lshl_add_u64 v[84:85], v[172:173], 0, s[44:45]
	s_add_i32 s34, s33, 0x2000
	s_mov_b32 s35, m0
	s_mov_b32 m0, s34
	s_nop 0
	global_load_lds_dwordx4 v[84:85], off
	s_mov_b32 m0, s35
	v_lshl_add_u64 v[84:85], v[170:171], 0, s[48:49]
	s_add_i32 s33, s33, 0xa000
	s_mov_b32 s34, m0
	s_mov_b32 m0, s33
	s_nop 0
	global_load_lds_dwordx4 v[84:85], off
	s_mov_b32 m0, s34
	s_waitcnt lgkmcnt(14)
	v_mfma_f32_32x32x16_bf16 v[16:31], v[140:143], v[188:191], v[16:31]
	v_exp_f32_e32 v112, v112
	v_exp_f32_e32 v113, v113
	v_exp_f32_e32 v114, v114
	v_exp_f32_e32 v115, v115
	s_waitcnt lgkmcnt(12)
	v_mfma_f32_32x32x16_bf16 v[32:47], v[140:143], v[96:99], v[32:47]
	v_exp_f32_e32 v116, v116
	v_exp_f32_e32 v117, v117
	v_exp_f32_e32 v118, v118
	v_exp_f32_e32 v119, v119
	ds_read_b128 v[84:87], v234 offset:16384
	ds_read_b128 v[96:99], v234 offset:20480
	s_waitcnt lgkmcnt(12)
	v_mfma_f32_32x32x16_bf16 v[16:31], v[136:139], v[64:67], v[16:31]
	v_exp_f32_e32 v120, v120
	v_exp_f32_e32 v121, v121
	v_exp_f32_e32 v122, v122
	v_exp_f32_e32 v123, v123
	ds_read_b128 v[104:107], v235 offset:16384
	ds_read_b128 v[108:111], v235 offset:20480
	s_waitcnt lgkmcnt(12)
	v_mfma_f32_32x32x16_bf16 v[32:47], v[136:139], v[68:71], v[32:47]
	v_exp_f32_e32 v124, v124
	v_exp_f32_e32 v125, v125
	v_exp_f32_e32 v126, v126
	v_exp_f32_e32 v127, v127
	ds_read_b128 v[160:163], v236 offset:16384
	ds_read_b128 v[164:167], v236 offset:20480
	s_waitcnt lgkmcnt(12)
	v_mfma_f32_32x32x16_bf16 v[16:31], v[132:135], v[100:103], v[16:31]
	v_exp_f32_e32 v48, v48
	v_exp_f32_e32 v49, v49
	v_exp_f32_e32 v50, v50
	v_exp_f32_e32 v51, v51
	ds_read_b128 v[100:103], v237 offset:16384
	ds_read_b128 v[184:187], v237 offset:20480
	s_waitcnt lgkmcnt(12)
	v_mfma_f32_32x32x16_bf16 v[32:47], v[132:135], v[72:75], v[32:47]
	v_exp_f32_e32 v52, v52
	v_exp_f32_e32 v53, v53
	v_exp_f32_e32 v54, v54
	v_exp_f32_e32 v55, v55
	s_waitcnt lgkmcnt(10)
	v_mfma_f32_32x32x16_bf16 v[16:31], v[128:131], v[80:83], v[16:31]
	v_exp_f32_e32 v56, v56
	v_exp_f32_e32 v57, v57
	v_exp_f32_e32 v58, v58
	v_exp_f32_e32 v59, v59
	s_waitcnt lgkmcnt(8)
	v_mfma_f32_32x32x16_bf16 v[32:47], v[128:131], v[76:79], v[32:47]
	v_exp_f32_e32 v60, v60
	v_exp_f32_e32 v61, v61
	v_exp_f32_e32 v62, v62
	v_exp_f32_e32 v63, v63
	s_waitcnt vmcnt(2) lgkmcnt(0)
	s_barrier
	ds_read_b64_tr_b16 v[188:189], v182 offset:32768
	ds_read_b64_tr_b16 v[190:191], v182 offset:33280
	v_add_f32_e32 v64, v112, v113
	v_add_f32_e32 v64, v114, v64
	v_add_f32_e32 v64, v115, v64
	v_add_f32_e32 v64, v116, v64
	v_add_f32_e32 v64, v117, v64
	v_cvt_pk_bf16_f32 v140, v112, v113
	v_cvt_pk_bf16_f32 v141, v114, v115
	s_waitcnt lgkmcnt(9)
	v_mfma_f32_32x32x16_bf16 v[80:95], v[84:87], v[156:159], 0
	ds_read_b64_tr_b16 v[112:113], v182 offset:36864
	ds_read_b64_tr_b16 v[114:115], v182 offset:37376
	v_add_f32_e32 v64, v118, v64
	v_add_f32_e32 v64, v119, v64
	v_add_f32_e32 v64, v120, v64
	v_add_f32_e32 v128, v121, v64
	v_cvt_pk_bf16_f32 v142, v116, v117
	v_cvt_pk_bf16_f32 v143, v118, v119
	s_waitcnt lgkmcnt(10)
	v_mfma_f32_32x32x16_bf16 v[64:79], v[96:99], v[156:159], 0
	ds_read_b64_tr_b16 v[96:97], v182 offset:33792
	ds_read_b64_tr_b16 v[98:99], v182 offset:34304
	v_add_f32_e32 v116, v122, v128
	v_add_f32_e32 v116, v123, v116
	v_add_f32_e32 v116, v124, v116
	v_add_f32_e32 v116, v125, v116
	v_cvt_pk_bf16_f32 v136, v120, v121
	v_cvt_pk_bf16_f32 v137, v122, v123
	s_waitcnt lgkmcnt(11)
	v_mfma_f32_32x32x16_bf16 v[80:95], v[104:107], v[152:155], v[80:95]
	ds_read_b64_tr_b16 v[104:105], v182 offset:37888
	ds_read_b64_tr_b16 v[106:107], v182 offset:38400
	v_add_f32_e32 v116, v126, v116
	v_add_f32_e32 v116, v127, v116
	v_add_f32_e32 v116, v48, v116
	v_add_f32_e32 v116, v49, v116
	v_cvt_pk_bf16_f32 v138, v124, v125
	v_cvt_pk_bf16_f32 v139, v126, v127
	s_waitcnt lgkmcnt(12)
	v_mfma_f32_32x32x16_bf16 v[64:79], v[108:111], v[152:155], v[64:79]
	ds_read_b64_tr_b16 v[108:109], v182 offset:34816
	ds_read_b64_tr_b16 v[110:111], v182 offset:35328
	v_add_f32_e32 v116, v50, v116
	v_add_f32_e32 v116, v51, v116
	v_add_f32_e32 v116, v52, v116
	v_add_f32_e32 v116, v53, v116
	v_cvt_pk_bf16_f32 v132, v48, v49
	v_cvt_pk_bf16_f32 v133, v50, v51
	s_waitcnt lgkmcnt(13)
	v_mfma_f32_32x32x16_bf16 v[80:95], v[160:163], v[148:151], v[80:95]
	ds_read_b64_tr_b16 v[48:49], v182 offset:38912
	ds_read_b64_tr_b16 v[50:51], v182 offset:39424
	v_add_f32_e32 v116, v54, v116
	v_add_f32_e32 v116, v55, v116
	v_add_f32_e32 v116, v56, v116
	v_add_f32_e32 v116, v57, v116
	v_cvt_pk_bf16_f32 v134, v52, v53
	v_cvt_pk_bf16_f32 v135, v54, v55
	s_waitcnt lgkmcnt(14)
	v_mfma_f32_32x32x16_bf16 v[64:79], v[164:167], v[148:151], v[64:79]
	ds_read_b64_tr_b16 v[52:53], v182 offset:35840
	ds_read_b64_tr_b16 v[54:55], v182 offset:36352
	v_add_f32_e32 v116, v58, v116
	v_add_f32_e32 v116, v59, v116
	v_add_f32_e32 v116, v60, v116
	v_add_f32_e32 v116, v61, v116
	v_cvt_pk_bf16_f32 v128, v56, v57
	v_cvt_pk_bf16_f32 v129, v58, v59
	s_waitcnt lgkmcnt(14)
	v_mfma_f32_32x32x16_bf16 v[80:95], v[100:103], v[144:147], v[80:95]
	ds_read_b64_tr_b16 v[56:57], v182 offset:39936
	ds_read_b64_tr_b16 v[58:59], v182 offset:40448
	v_add_f32_e32 v100, v62, v116
	v_add_f32_e32 v100, v63, v100
	v_add_f32_e32 v100, 0, v100
	v_cvt_pk_bf16_f32 v130, v60, v61
	v_cvt_pk_bf16_f32 v131, v62, v63
	v_mfma_f32_32x32x16_bf16 v[64:79], v[184:187], v[144:147], v[64:79]
	v_lshl_add_u64 v[60:61], v[170:171], 0, s[40:41]
	s_mov_b32 s33, m0
	s_mov_b32 m0, s16
	s_nop 0
	global_load_lds_dwordx4 v[60:61], off
	s_mov_b32 m0, s33
	v_add_f32_e32 v172, v175, v100
	s_waitcnt lgkmcnt(14)
	v_mfma_f32_32x32x16_bf16 v[16:31], v[140:143], v[188:191], v[16:31]
	v_exp_f32_e32 v80, v80
	v_exp_f32_e32 v81, v81
	v_exp_f32_e32 v82, v82
	v_exp_f32_e32 v83, v83
	s_waitcnt lgkmcnt(12)
	v_mfma_f32_32x32x16_bf16 v[32:47], v[140:143], v[112:115], v[32:47]
	v_exp_f32_e32 v84, v84
	v_exp_f32_e32 v85, v85
	v_exp_f32_e32 v86, v86
	v_exp_f32_e32 v87, v87
	ds_read_b128 v[60:63], v234
	ds_read_b128 v[112:115], v234 offset:4096
	s_waitcnt lgkmcnt(12)
	v_mfma_f32_32x32x16_bf16 v[16:31], v[136:139], v[96:99], v[16:31]
	v_exp_f32_e32 v88, v88
	v_exp_f32_e32 v89, v89
	v_exp_f32_e32 v90, v90
	v_exp_f32_e32 v91, v91
	ds_read_b128 v[116:119], v235
	ds_read_b128 v[120:123], v235 offset:4096
	s_waitcnt lgkmcnt(12)
	v_mfma_f32_32x32x16_bf16 v[32:47], v[136:139], v[104:107], v[32:47]
	v_exp_f32_e32 v92, v92
	v_exp_f32_e32 v93, v93
	v_exp_f32_e32 v94, v94
	v_exp_f32_e32 v95, v95
	ds_read_b128 v[124:127], v236
	ds_read_b128 v[160:163], v236 offset:4096
	s_waitcnt lgkmcnt(12)
	v_mfma_f32_32x32x16_bf16 v[16:31], v[132:135], v[108:111], v[16:31]
	v_exp_f32_e32 v64, v64
	v_exp_f32_e32 v65, v65
	v_exp_f32_e32 v66, v66
	v_exp_f32_e32 v67, v67
	ds_read_b128 v[164:167], v237
	ds_read_b128 v[184:187], v237 offset:4096
	s_waitcnt lgkmcnt(12)
	v_mfma_f32_32x32x16_bf16 v[32:47], v[132:135], v[48:51], v[32:47]
	v_exp_f32_e32 v68, v68
	v_exp_f32_e32 v69, v69
	v_exp_f32_e32 v70, v70
	v_exp_f32_e32 v71, v71
	s_waitcnt lgkmcnt(10)
	v_mfma_f32_32x32x16_bf16 v[16:31], v[128:131], v[52:55], v[16:31]
	v_exp_f32_e32 v72, v72
	v_exp_f32_e32 v73, v73
	v_exp_f32_e32 v74, v74
	v_exp_f32_e32 v75, v75
	s_waitcnt lgkmcnt(8)
	v_mfma_f32_32x32x16_bf16 v[32:47], v[128:131], v[56:59], v[32:47]
	v_exp_f32_e32 v76, v76
	v_exp_f32_e32 v77, v77
	v_exp_f32_e32 v78, v78
	v_exp_f32_e32 v79, v79
	s_waitcnt vmcnt(1) lgkmcnt(0)
	s_barrier
	ds_read_b64_tr_b16 v[188:189], v182 offset:40960
	ds_read_b64_tr_b16 v[190:191], v182 offset:41472
	v_add_f32_e32 v48, v80, v81
	v_add_f32_e32 v48, v82, v48
	v_add_f32_e32 v48, v83, v48
	v_add_f32_e32 v48, v84, v48
	v_add_f32_e32 v48, v85, v48
	v_cvt_pk_bf16_f32 v140, v80, v81
	v_cvt_pk_bf16_f32 v141, v82, v83
	s_waitcnt lgkmcnt(9)
	v_mfma_f32_32x32x16_bf16 v[96:111], v[60:63], v[156:159], 0
	ds_read_b64_tr_b16 v[80:81], v182 offset:45056
	ds_read_b64_tr_b16 v[82:83], v182 offset:45568
	v_add_f32_e32 v48, v86, v48
	v_add_f32_e32 v48, v87, v48
	v_add_f32_e32 v48, v88, v48
	v_add_f32_e32 v128, v89, v48
	s_waitcnt lgkmcnt(10)
	v_mfma_f32_32x32x16_bf16 v[48:63], v[112:115], v[156:159], 0
	v_cvt_pk_bf16_f32 v142, v84, v85
	v_cvt_pk_bf16_f32 v143, v86, v87
	ds_read_b64_tr_b16 v[84:85], v182 offset:41984
	ds_read_b64_tr_b16 v[86:87], v182 offset:42496
	v_add_f32_e32 v112, v90, v128
	v_add_f32_e32 v112, v91, v112
	v_add_f32_e32 v112, v92, v112
	v_add_f32_e32 v112, v93, v112
	v_cvt_pk_bf16_f32 v136, v88, v89
	v_cvt_pk_bf16_f32 v137, v90, v91
	s_waitcnt lgkmcnt(11)
	v_mfma_f32_32x32x16_bf16 v[96:111], v[116:119], v[152:155], v[96:111]
	ds_read_b64_tr_b16 v[88:89], v182 offset:46080
	ds_read_b64_tr_b16 v[90:91], v182 offset:46592
	s_waitcnt lgkmcnt(12)
	v_mfma_f32_32x32x16_bf16 v[48:63], v[120:123], v[152:155], v[48:63]
	v_add_f32_e32 v112, v94, v112
	v_add_f32_e32 v112, v95, v112
	v_add_f32_e32 v112, v64, v112
	v_add_f32_e32 v112, v65, v112
	v_cvt_pk_bf16_f32 v138, v92, v93
	v_cvt_pk_bf16_f32 v139, v94, v95
	ds_read_b64_tr_b16 v[92:93], v182 offset:43008
	ds_read_b64_tr_b16 v[94:95], v182 offset:43520
	v_add_f32_e32 v112, v66, v112
	v_add_f32_e32 v112, v67, v112
	v_add_f32_e32 v112, v68, v112
	v_add_f32_e32 v112, v69, v112
	v_cvt_pk_bf16_f32 v132, v64, v65
	v_cvt_pk_bf16_f32 v133, v66, v67
	s_waitcnt lgkmcnt(13)
	v_mfma_f32_32x32x16_bf16 v[96:111], v[124:127], v[148:151], v[96:111]
	ds_read_b64_tr_b16 v[64:65], v182 offset:47104
	ds_read_b64_tr_b16 v[66:67], v182 offset:47616
	s_waitcnt lgkmcnt(14)
	v_mfma_f32_32x32x16_bf16 v[48:63], v[160:163], v[148:151], v[48:63]
	v_add_f32_e32 v112, v70, v112
	v_add_f32_e32 v112, v71, v112
	v_add_f32_e32 v112, v72, v112
	v_add_f32_e32 v112, v73, v112
	v_cvt_pk_bf16_f32 v134, v68, v69
	v_cvt_pk_bf16_f32 v135, v70, v71
	ds_read_b64_tr_b16 v[68:69], v182 offset:44032
	ds_read_b64_tr_b16 v[70:71], v182 offset:44544
	v_add_f32_e32 v112, v74, v112
	v_add_f32_e32 v112, v75, v112
	v_add_f32_e32 v112, v76, v112
	v_add_f32_e32 v112, v77, v112
	v_cvt_pk_bf16_f32 v128, v72, v73
	v_cvt_pk_bf16_f32 v129, v74, v75
	s_waitcnt lgkmcnt(14)
	v_mfma_f32_32x32x16_bf16 v[96:111], v[164:167], v[144:147], v[96:111]
	ds_read_b64_tr_b16 v[72:73], v182 offset:48128
	ds_read_b64_tr_b16 v[74:75], v182 offset:48640
	v_mfma_f32_32x32x16_bf16 v[48:63], v[184:187], v[144:147], v[48:63]
	v_add_f32_e32 v112, v78, v112
	v_add_f32_e32 v112, v79, v112
	v_add_f32_e32 v112, 0, v112
	v_cvt_pk_bf16_f32 v130, v76, v77
	v_cvt_pk_bf16_f32 v131, v78, v79
	v_lshl_add_u64 v[76:77], v[170:171], 0, s[44:45]
	s_mov_b32 s16, m0
	s_mov_b32 m0, s17
	s_nop 0
	global_load_lds_dwordx4 v[76:77], off
	s_mov_b32 m0, s16
	v_add_f32_e32 v120, v172, v112
	s_waitcnt lgkmcnt(14)
	v_mfma_f32_32x32x16_bf16 v[16:31], v[140:143], v[188:191], v[16:31]
	v_exp_f32_e32 v96, v96
	v_exp_f32_e32 v97, v97
	v_exp_f32_e32 v98, v98
	v_exp_f32_e32 v99, v99
	s_waitcnt lgkmcnt(12)
	v_mfma_f32_32x32x16_bf16 v[32:47], v[140:143], v[80:83], v[32:47]
	v_exp_f32_e32 v100, v100
	v_exp_f32_e32 v101, v101
	v_exp_f32_e32 v102, v102
	v_exp_f32_e32 v103, v103
	ds_read_b128 v[76:79], v234 offset:8192
	ds_read_b128 v[80:83], v234 offset:12288
	s_waitcnt lgkmcnt(12)
	v_mfma_f32_32x32x16_bf16 v[16:31], v[136:139], v[84:87], v[16:31]
	v_exp_f32_e32 v104, v104
	v_exp_f32_e32 v105, v105
	v_exp_f32_e32 v106, v106
	v_exp_f32_e32 v107, v107
	ds_read_b128 v[122:125], v235 offset:8192
	ds_read_b128 v[160:163], v235 offset:12288
	s_waitcnt lgkmcnt(12)
	v_mfma_f32_32x32x16_bf16 v[32:47], v[136:139], v[88:91], v[32:47]
	v_exp_f32_e32 v108, v108
	v_exp_f32_e32 v109, v109
	v_exp_f32_e32 v110, v110
	v_exp_f32_e32 v111, v111
	ds_read_b128 v[164:167], v236 offset:8192
	ds_read_b128 v[170:173], v236 offset:12288
	s_waitcnt lgkmcnt(12)
	v_mfma_f32_32x32x16_bf16 v[16:31], v[132:135], v[92:95], v[16:31]
	v_exp_f32_e32 v48, v48
	v_exp_f32_e32 v49, v49
	v_exp_f32_e32 v50, v50
	v_exp_f32_e32 v51, v51
	ds_read_b128 v[184:187], v237 offset:8192
	ds_read_b128 v[188:191], v237 offset:12288
	s_waitcnt lgkmcnt(12)
	v_mfma_f32_32x32x16_bf16 v[32:47], v[132:135], v[64:67], v[32:47]
	v_exp_f32_e32 v52, v52
	v_exp_f32_e32 v53, v53
	v_exp_f32_e32 v54, v54
	v_exp_f32_e32 v55, v55
	s_waitcnt lgkmcnt(10)
	v_mfma_f32_32x32x16_bf16 v[16:31], v[128:131], v[68:71], v[16:31]
	v_exp_f32_e32 v56, v56
	v_exp_f32_e32 v57, v57
	v_exp_f32_e32 v58, v58
	v_exp_f32_e32 v59, v59
	s_waitcnt lgkmcnt(8)
	v_mfma_f32_32x32x16_bf16 v[32:47], v[128:131], v[72:75], v[32:47]
	v_exp_f32_e32 v60, v60
	v_exp_f32_e32 v61, v61
	v_exp_f32_e32 v62, v62
	v_exp_f32_e32 v63, v63
	s_waitcnt vmcnt(0) lgkmcnt(0)
	s_barrier
	ds_read_b64_tr_b16 v[112:113], v182 offset:24576
	ds_read_b64_tr_b16 v[114:115], v182 offset:25088
	v_add_f32_e32 v64, v96, v97
	v_add_f32_e32 v64, v98, v64
	v_add_f32_e32 v64, v99, v64
	v_add_f32_e32 v64, v100, v64
	v_add_f32_e32 v84, v101, v64
	v_cvt_pk_bf16_f32 v140, v96, v97
	v_cvt_pk_bf16_f32 v141, v98, v99
	s_waitcnt lgkmcnt(9)
	v_mfma_f32_32x32x16_bf16 v[64:79], v[76:79], v[156:159], 0
	ds_read_b64_tr_b16 v[96:97], v182 offset:28672
	ds_read_b64_tr_b16 v[98:99], v182 offset:29184
	v_add_f32_e32 v84, v102, v84
	v_add_f32_e32 v84, v103, v84
	v_add_f32_e32 v84, v104, v84
	v_add_f32_e32 v121, v105, v84
	v_cvt_pk_bf16_f32 v142, v100, v101
	v_cvt_pk_bf16_f32 v143, v102, v103
	s_waitcnt lgkmcnt(10)
	v_mfma_f32_32x32x16_bf16 v[80:95], v[80:83], v[156:159], 0
	ds_read_b64_tr_b16 v[116:117], v182 offset:25600
	ds_read_b64_tr_b16 v[118:119], v182 offset:26112
	v_add_f32_e32 v100, v106, v121
	v_add_f32_e32 v100, v107, v100
	v_add_f32_e32 v100, v108, v100
	v_add_f32_e32 v121, v109, v100
	v_cvt_pk_bf16_f32 v136, v104, v105
	v_cvt_pk_bf16_f32 v137, v106, v107
	s_waitcnt lgkmcnt(11)
	v_mfma_f32_32x32x16_bf16 v[64:79], v[122:125], v[152:155], v[64:79]
	ds_read_b64_tr_b16 v[100:101], v182 offset:29696
	ds_read_b64_tr_b16 v[102:103], v182 offset:30208
	v_add_f32_e32 v104, v110, v121
	v_add_f32_e32 v104, v111, v104
	v_add_f32_e32 v104, v48, v104
	v_add_f32_e32 v121, v49, v104
	v_cvt_pk_bf16_f32 v138, v108, v109
	v_cvt_pk_bf16_f32 v139, v110, v111
	s_waitcnt lgkmcnt(12)
	v_mfma_f32_32x32x16_bf16 v[80:95], v[160:163], v[152:155], v[80:95]
	ds_read_b64_tr_b16 v[104:105], v182 offset:26624
	ds_read_b64_tr_b16 v[106:107], v182 offset:27136
	v_add_f32_e32 v108, v50, v121
	v_add_f32_e32 v108, v51, v108
	v_add_f32_e32 v108, v52, v108
	v_add_f32_e32 v108, v53, v108
	v_cvt_pk_bf16_f32 v132, v48, v49
	v_cvt_pk_bf16_f32 v133, v50, v51
	s_waitcnt lgkmcnt(13)
	v_mfma_f32_32x32x16_bf16 v[64:79], v[164:167], v[148:151], v[64:79]
	ds_read_b64_tr_b16 v[48:49], v182 offset:30720
	ds_read_b64_tr_b16 v[50:51], v182 offset:31232
	v_add_f32_e32 v108, v54, v108
	v_add_f32_e32 v108, v55, v108
	v_add_f32_e32 v108, v56, v108
	v_add_f32_e32 v121, v57, v108
	v_cvt_pk_bf16_f32 v134, v52, v53
	v_cvt_pk_bf16_f32 v135, v54, v55
	s_waitcnt lgkmcnt(14)
	v_mfma_f32_32x32x16_bf16 v[80:95], v[170:173], v[148:151], v[80:95]
	ds_read_b64_tr_b16 v[108:109], v182 offset:27648
	ds_read_b64_tr_b16 v[110:111], v182 offset:28160
	v_add_f32_e32 v52, v58, v121
	v_add_f32_e32 v52, v59, v52
	v_add_f32_e32 v52, v60, v52
	v_add_f32_e32 v121, v61, v52
	v_cvt_pk_bf16_f32 v128, v56, v57
	v_cvt_pk_bf16_f32 v129, v58, v59
	s_waitcnt lgkmcnt(14)
	v_mfma_f32_32x32x16_bf16 v[64:79], v[184:187], v[144:147], v[64:79]
	ds_read_b64_tr_b16 v[52:53], v182 offset:31744
	ds_read_b64_tr_b16 v[54:55], v182 offset:32256
	v_add_f32_e32 v56, v62, v121
	v_add_f32_e32 v56, v63, v56
	v_add_f32_e32 v56, 0, v56
	v_cvt_pk_bf16_f32 v130, v60, v61
	v_cvt_pk_bf16_f32 v131, v62, v63
	v_mfma_f32_32x32x16_bf16 v[80:95], v[188:191], v[144:147], v[80:95]
	s_nop 3
	v_exp_f32_e32 v64, v64
	v_exp_f32_e32 v65, v65
	v_exp_f32_e32 v66, v66
	v_exp_f32_e32 v67, v67
	s_nop 0
	v_exp_f32_e32 v68, v68
	v_exp_f32_e32 v69, v69
	v_exp_f32_e32 v70, v70
	v_exp_f32_e32 v71, v71
	s_nop 0
	v_exp_f32_e32 v72, v72
	v_exp_f32_e32 v73, v73
	v_exp_f32_e32 v74, v74
	v_exp_f32_e32 v75, v75
	s_nop 0
	v_exp_f32_e32 v76, v76
	v_exp_f32_e32 v77, v77
	v_exp_f32_e32 v78, v78
	v_exp_f32_e32 v79, v79
	v_exp_f32_e32 v80, v80
	v_exp_f32_e32 v81, v81
	v_exp_f32_e32 v82, v82
	v_exp_f32_e32 v83, v83
	s_nop 0
	v_exp_f32_e32 v84, v84
	v_exp_f32_e32 v85, v85
	v_exp_f32_e32 v86, v86
	v_exp_f32_e32 v87, v87
	s_nop 0
	v_exp_f32_e32 v88, v88
	v_exp_f32_e32 v89, v89
	v_exp_f32_e32 v90, v90
	v_exp_f32_e32 v91, v91
	s_nop 0
	v_exp_f32_e32 v92, v92
	v_exp_f32_e32 v93, v93
	v_exp_f32_e32 v94, v94
	v_exp_f32_e32 v95, v95
	s_waitcnt lgkmcnt(14)
; #define SBAR() __builtin_amdgcn_sched_barrier(0)
; __device__ __forceinline__ void pv(f32x16*o,int vb,bf16x8 pa0,bf16x8 pa1,bf16x8 pa2,bf16x8 pa3){
;   #pragma unroll
;   for(int d0=0;d0<2;++d0){s16x4 lo[4],hi[4];
;     #pragma unroll
;     for(int ks=0;ks<4;++ks){
;       asm volatile("ds_read_b64_tr_b16 %0,%1 offset:%c2":"=&v"(lo[ks]):"v"(vb),"i"(d0*4096+ks*1024):"memory");
;       asm volatile("ds_read_b64_tr_b16 %0,%1 offset:%c2":"=&v"(hi[ks]):"v"(vb),"i"(d0*4096+ks*1024+512):"memory");}
;     asm volatile("s_waitcnt lgkmcnt(0)":::"memory");SBAR();
;     ...
;     o[d0]=__builtin_amdgcn_mfma_f32_32x32x16_bf16(pa0,PK(0),o[d0],0,0,0);
;     o[d0]=__builtin_amdgcn_mfma_f32_32x32x16_bf16(pa1,PK(1),o[d0],0,0,0);
;     o[d0]=__builtin_amdgcn_mfma_f32_32x32x16_bf16(pa2,PK(2),o[d0],0,0,0);
;     o[d0]=__builtin_amdgcn_mfma_f32_32x32x16_bf16(pa3,PK(3),o[d0],0,0,0);
;     ...
;   }
; }
; template<int THRL,int VM,bool NOMAX> __device__ __forceinline__ void attn_unit(const bf16*Qb,const bf16*__restrict__ Kh,const bf16*__restrict__ Vh,bf16*Ob,const int NT,const int sp,float*wscr,char*shm){
;     ...
;   int t=1;
;   for(;t+5<NT;t+=2){
;     STEP(pB0,pB1,pA0,pA1,t,true,true,true);     if constexpr(VM==2){WAIT_BAR(3);}else{WAIT_BAR(2);} RESC(); ROT();
;     STEP(pA0,pA1,pB0,pB1,t+1,true,true,true);   if constexpr(VM==2){WAIT_BAR(3);}else{WAIT_BAR(2);} RESC(); ROT();
;   }
;     ...
;   for(;t+1<NT;t+=2){
;     STEP(pB0,pB1,pA0,pA1,t,(t+3<NT),(t+1<NT),(t+1<NT));       ENDW(t);   RESC(); ROT();
;     STEP(pA0,pA1,pB0,pB1,t+1,(t+4<NT),(t+2<NT),(t+2<NT));     ENDW(t+1); RESC(); ROT();
;   }
;   STEP(pB0,pB1,pA0,pA1,NT-1,false,false,false); RESC();
;   { float sacc=pB0[0]+pB0[1]; _Pragma("unroll") for(int r=2;r<16;++r)sacc+=pB0[r]; _Pragma("unroll") for(int r=0;r<16;++r)sacc+=pB1[r]; l_reg+=sacc;
;     pw0=(u32x4){PKW(pB0,0),PKW(pB0,2),PKW(pB0,4),PKW(pB0,6)};pw1=(u32x4){PKW(pB0,8),PKW(pB0,10),PKW(pB0,12),PKW(pB0,14)};pw2=(u32x4){PKW(pB1,0),PKW(pB1,2),PKW(pB1,4),PKW(pB1,6)};pw3=(u32x4){PKW(pB1,8),PKW(pB1,10),PKW(pB1,12),PKW(pB1,14)};
;     SBAR(); pv(o,vb0+VM*sl_cur,PAF(0),PAF(1),PAF(2),PAF(3)); if constexpr(VM==2) pv(o+2,vb0+VM*sl_cur+8192,PAF(0),PAF(1),PAF(2),PAF(3)); }
;     ...
;   {auto rr=__builtin_amdgcn_permlane32_swap(__float_as_uint(l_reg),__float_as_uint(l_reg),false,false);l_reg=__uint_as_float(rr[0])+__uint_as_float(rr[1]);}
;   if(hi==0)wsf[32+r32]=l_reg;asm volatile("s_waitcnt lgkmcnt(0)":::"memory");
	v_mfma_f32_32x32x16_bf16 v[16:31], v[140:143], v[112:115], v[16:31]
	v_add_f32_e32 v57, v64, v65
	v_add_f32_e32 v57, v66, v57
	v_add_f32_e32 v57, v67, v57
	v_add_f32_e32 v57, v68, v57
	v_add_f32_e32 v57, v69, v57
	v_add_f32_e32 v57, v70, v57
	v_add_f32_e32 v57, v71, v57
	s_waitcnt lgkmcnt(12)
	v_mfma_f32_32x32x16_bf16 v[32:47], v[140:143], v[96:99], v[32:47]
	v_add_f32_e32 v57, v72, v57
	v_add_f32_e32 v57, v73, v57
	v_add_f32_e32 v57, v74, v57
	v_add_f32_e32 v57, v75, v57
	v_add_f32_e32 v57, v76, v57
	v_add_f32_e32 v57, v77, v57
	v_add_f32_e32 v57, v78, v57
	s_waitcnt lgkmcnt(10)
	v_mfma_f32_32x32x16_bf16 v[16:31], v[136:139], v[116:119], v[16:31]
	v_add_f32_e32 v57, v79, v57
	v_add_f32_e32 v57, v80, v57
	v_add_f32_e32 v57, v81, v57
	v_add_f32_e32 v57, v82, v57
	v_add_f32_e32 v57, v83, v57
	v_add_f32_e32 v57, v84, v57
	v_add_f32_e32 v57, v85, v57
	s_waitcnt lgkmcnt(8)
	v_mfma_f32_32x32x16_bf16 v[32:47], v[136:139], v[100:103], v[32:47]
	v_add_f32_e32 v57, v86, v57
	v_add_f32_e32 v57, v87, v57
	v_add_f32_e32 v57, v88, v57
	v_add_f32_e32 v57, v89, v57
	v_add_f32_e32 v57, v90, v57
	v_add_f32_e32 v57, v91, v57
	v_add_f32_e32 v57, v92, v57
	s_waitcnt lgkmcnt(6)
	v_mfma_f32_32x32x16_bf16 v[16:31], v[132:135], v[104:107], v[16:31]
	v_add_f32_e32 v57, v93, v57
	v_add_f32_e32 v57, v94, v57
	v_add_f32_e32 v57, v95, v57
	v_add_f32_e32 v56, v120, v56
	v_add_f32_e32 v56, v56, v57
	v_cvt_pk_bf16_f32 v58, v64, v65
	v_cvt_pk_bf16_f32 v59, v66, v67
	s_waitcnt lgkmcnt(4)
	v_mfma_f32_32x32x16_bf16 v[32:47], v[132:135], v[48:51], v[32:47]
	v_cvt_pk_bf16_f32 v48, v80, v81
	v_cvt_pk_bf16_f32 v60, v68, v69
	v_cvt_pk_bf16_f32 v61, v70, v71
	v_cvt_pk_bf16_f32 v62, v72, v73
	v_cvt_pk_bf16_f32 v63, v74, v75
	v_cvt_pk_bf16_f32 v64, v76, v77
	v_cvt_pk_bf16_f32 v65, v78, v79
	s_waitcnt lgkmcnt(2)
	v_mfma_f32_32x32x16_bf16 v[16:31], v[128:131], v[108:111], v[16:31]
	v_cvt_pk_bf16_f32 v49, v82, v83
	v_cvt_pk_bf16_f32 v50, v84, v85
	v_cvt_pk_bf16_f32 v51, v86, v87
	v_cvt_pk_bf16_f32 v66, v88, v89
	v_cvt_pk_bf16_f32 v67, v90, v91
	v_cvt_pk_bf16_f32 v68, v92, v93
	v_cvt_pk_bf16_f32 v69, v94, v95
	s_waitcnt lgkmcnt(0)
	v_mfma_f32_32x32x16_bf16 v[32:47], v[128:131], v[52:55], v[32:47]
	v_add3_u32 v57, v174, v168, s18
	ds_read_b64_tr_b16 v[52:53],v57 offset:0
	ds_read_b64_tr_b16 v[54:55],v57 offset:512
	ds_read_b64_tr_b16 v[70:71],v57 offset:1024
	ds_read_b64_tr_b16 v[72:73],v57 offset:1536
	ds_read_b64_tr_b16 v[74:75],v57 offset:2048
	ds_read_b64_tr_b16 v[76:77],v57 offset:2560
	ds_read_b64_tr_b16 v[78:79],v57 offset:3072
	ds_read_b64_tr_b16 v[80:81],v57 offset:3584
	s_waitcnt lgkmcnt(0)
	s_nop 0
	v_mfma_f32_32x32x16_bf16 v[16:31], v[58:61], v[52:55], v[16:31]
	ds_read_b64_tr_b16 v[52:53],v57 offset:4096
	ds_read_b64_tr_b16 v[54:55],v57 offset:4608
	v_mfma_f32_32x32x16_bf16 v[16:31], v[62:65], v[70:73], v[16:31]
	ds_read_b64_tr_b16 v[70:71],v57 offset:5120
	ds_read_b64_tr_b16 v[72:73],v57 offset:5632
	v_mfma_f32_32x32x16_bf16 v[16:31], v[48:51], v[74:77], v[16:31]
	ds_read_b64_tr_b16 v[74:75],v57 offset:6144
	ds_read_b64_tr_b16 v[76:77],v57 offset:6656
	ds_read_b64_tr_b16 v[82:83],v57 offset:7168
	ds_read_b64_tr_b16 v[84:85],v57 offset:7680
	s_waitcnt lgkmcnt(0)
	v_mfma_f32_32x32x16_bf16 v[16:31], v[66:69], v[78:81], v[16:31]
	v_mfma_f32_32x32x16_bf16 v[32:47], v[58:61], v[52:55], v[32:47]
	v_cmp_gt_u32_e32 vcc, 32, v178
	v_mfma_f32_32x32x16_bf16 v[32:47], v[62:65], v[70:73], v[32:47]
	v_mfma_f32_32x32x16_bf16 v[32:47], v[48:51], v[74:77], v[32:47]
	v_mov_b32_e32 v48, v56
	s_nop 1
	v_permlane32_swap_b32_e32 v56, v48
	v_mfma_f32_32x32x16_bf16 v[32:47], v[66:69], v[82:85], v[32:47]
	s_and_saveexec_b64 s[16:17], vcc
	s_cbranch_execz .LBB0_878
	v_add_f32_e32 v48, v56, v48
	v_lshl_add_u32 v49, v180, 2, s29
	ds_write_b32 v49, v48 offset:49280
	s_branch .LBB0_878

.LBB0_891:
	v_mfma_f32_32x32x16_bf16 v[96:111], v[84:87], v[156:159], 0
	v_add_u32_e32 v187, s52, v168
	ds_read_b64_tr_b16 v[188:189], v187 offset:24576
	ds_read_b64_tr_b16 v[190:191], v187 offset:25088
	v_add_f32_e32 v88, v64, v65
	v_add_f32_e32 v88, v66, v88
	v_add_f32_e32 v88, v67, v88
	v_add_f32_e32 v88, v68, v88
	v_add_f32_e32 v88, v69, v88
	v_cvt_pk_bf16_f32 v140, v64, v65
	v_cvt_pk_bf16_f32 v141, v66, v67
	ds_read_b64_tr_b16 v[64:65], v187 offset:28672
	ds_read_b64_tr_b16 v[66:67], v187 offset:29184
	v_add_f32_e32 v84, v70, v88
	v_add_f32_e32 v84, v71, v84
	v_add_f32_e32 v84, v72, v84
	v_add_f32_e32 v128, v73, v84
	s_waitcnt lgkmcnt(10)
	v_mfma_f32_32x32x16_bf16 v[80:95], v[80:83], v[156:159], 0
	v_lshl_add_u64 v[238:239], v[176:177], 0, s[38:39]
	s_add_i32 s35, s34, s17
	s_mov_b32 s52, m0
	s_mov_b32 m0, s35
	s_nop 0
	global_load_lds_dwordx4 v[238:239], off
	s_mov_b32 m0, s52
	v_cvt_pk_bf16_f32 v142, v68, v69
	v_cvt_pk_bf16_f32 v143, v70, v71
	ds_read_b64_tr_b16 v[68:69], v187 offset:25600
	ds_read_b64_tr_b16 v[70:71], v187 offset:26112
	v_add_f32_e32 v128, v74, v128
	v_add_f32_e32 v128, v75, v128
	v_add_f32_e32 v128, v76, v128
	v_add_f32_e32 v128, v77, v128
	v_cvt_pk_bf16_f32 v136, v72, v73
	v_cvt_pk_bf16_f32 v137, v74, v75
	s_waitcnt lgkmcnt(11)
	v_mfma_f32_32x32x16_bf16 v[96:111], v[164:167], v[152:155], v[96:111]
	v_lshl_add_u64 v[238:239], v[174:175], 0, s[38:39]
	s_add_i32 s35, s33, s16
	s_mov_b32 s52, m0
	s_mov_b32 m0, s35
	s_nop 0
	global_load_lds_dwordx4 v[238:239], off
	s_mov_b32 m0, s52
	ds_read_b64_tr_b16 v[72:73], v187 offset:29696
	ds_read_b64_tr_b16 v[74:75], v187 offset:30208
	s_waitcnt lgkmcnt(12)
	v_mfma_f32_32x32x16_bf16 v[80:95], v[160:163], v[152:155], v[80:95]
	v_add_f32_e32 v128, v78, v128
	v_add_f32_e32 v128, v79, v128
	v_add_f32_e32 v128, v48, v128
	v_add_f32_e32 v128, v49, v128
	v_cvt_pk_bf16_f32 v138, v76, v77
	v_cvt_pk_bf16_f32 v139, v78, v79
	ds_read_b64_tr_b16 v[76:77], v187 offset:26624
	ds_read_b64_tr_b16 v[78:79], v187 offset:27136
	v_add_f32_e32 v128, v50, v128
	v_add_f32_e32 v128, v51, v128
	v_add_f32_e32 v128, v52, v128
	v_add_f32_e32 v128, v53, v128
	v_cvt_pk_bf16_f32 v132, v48, v49
	v_cvt_pk_bf16_f32 v133, v50, v51
	s_waitcnt lgkmcnt(13)
	v_mfma_f32_32x32x16_bf16 v[96:111], v[124:127], v[148:151], v[96:111]
	ds_read_b64_tr_b16 v[48:49], v187 offset:30720
	ds_read_b64_tr_b16 v[50:51], v187 offset:31232
	s_waitcnt lgkmcnt(14)
	v_mfma_f32_32x32x16_bf16 v[80:95], v[120:123], v[148:151], v[80:95]
	v_add_f32_e32 v124, v54, v128
	v_add_f32_e32 v124, v55, v124
	v_add_f32_e32 v124, v56, v124
	v_add_f32_e32 v124, v57, v124
	v_cvt_pk_bf16_f32 v134, v52, v53
	v_cvt_pk_bf16_f32 v135, v54, v55
	ds_read_b64_tr_b16 v[52:53], v187 offset:27648
	ds_read_b64_tr_b16 v[54:55], v187 offset:28160
	v_add_f32_e32 v120, v58, v124
	v_add_f32_e32 v120, v59, v120
	v_add_f32_e32 v120, v60, v120
	v_add_f32_e32 v120, v61, v120
	v_cvt_pk_bf16_f32 v128, v56, v57
	v_cvt_pk_bf16_f32 v129, v58, v59
	s_waitcnt lgkmcnt(14)
	v_mfma_f32_32x32x16_bf16 v[96:111], v[116:119], v[144:147], v[96:111]
	ds_read_b64_tr_b16 v[56:57], v187 offset:31744
	ds_read_b64_tr_b16 v[58:59], v187 offset:32256
	v_mfma_f32_32x32x16_bf16 v[80:95], v[112:115], v[144:147], v[80:95]
	v_add_f32_e32 v116, v62, v120
	v_add_f32_e32 v116, v63, v116
	v_add_f32_e32 v116, 0, v116
	v_cvt_pk_bf16_f32 v130, v60, v61
	v_cvt_pk_bf16_f32 v131, v62, v63
	v_add_f32_e32 v202, v186, v116
	s_waitcnt lgkmcnt(14)
	v_mfma_f32_32x32x16_bf16 v[16:31], v[140:143], v[188:191], v[16:31]
	v_exp_f32_e32 v96, v96
	v_exp_f32_e32 v97, v97
	v_exp_f32_e32 v98, v98
	v_exp_f32_e32 v99, v99
	s_waitcnt lgkmcnt(12)
	v_mfma_f32_32x32x16_bf16 v[32:47], v[140:143], v[64:67], v[32:47]
	v_exp_f32_e32 v100, v100
	v_exp_f32_e32 v101, v101
	v_exp_f32_e32 v102, v102
	v_exp_f32_e32 v103, v103
	v_add_u32_e32 v242, s33, v234
	v_add_u32_e32 v243, s33, v235
	v_add_u32_e32 v244, s33, v236
	v_add_u32_e32 v245, s33, v237
	ds_read_b128 v[60:63], v242
	ds_read_b128 v[112:115], v242 offset:4096
	s_waitcnt lgkmcnt(12)
	v_mfma_f32_32x32x16_bf16 v[16:31], v[136:139], v[68:71], v[16:31]
	v_exp_f32_e32 v104, v104
	v_exp_f32_e32 v105, v105
	v_exp_f32_e32 v106, v106
	v_exp_f32_e32 v107, v107
	ds_read_b128 v[116:119], v243
	ds_read_b128 v[120:123], v243 offset:4096
	s_waitcnt lgkmcnt(12)
	v_mfma_f32_32x32x16_bf16 v[32:47], v[136:139], v[72:75], v[32:47]
	v_exp_f32_e32 v108, v108
	v_exp_f32_e32 v109, v109
	v_exp_f32_e32 v110, v110
	v_exp_f32_e32 v111, v111
	ds_read_b128 v[124:127], v244
	ds_read_b128 v[160:163], v244 offset:4096
	s_waitcnt lgkmcnt(12)
	v_mfma_f32_32x32x16_bf16 v[16:31], v[132:135], v[76:79], v[16:31]
	v_exp_f32_e32 v80, v80
	v_exp_f32_e32 v81, v81
	v_exp_f32_e32 v82, v82
	v_exp_f32_e32 v83, v83
	ds_read_b128 v[164:167], v245
	ds_read_b128 v[186:189], v245 offset:4096
	s_waitcnt lgkmcnt(12)
	v_mfma_f32_32x32x16_bf16 v[32:47], v[132:135], v[48:51], v[32:47]
	v_exp_f32_e32 v84, v84
	v_exp_f32_e32 v85, v85
	v_exp_f32_e32 v86, v86
	v_exp_f32_e32 v87, v87
	s_waitcnt lgkmcnt(10)
	v_mfma_f32_32x32x16_bf16 v[16:31], v[128:131], v[52:55], v[16:31]
	v_exp_f32_e32 v88, v88
	v_exp_f32_e32 v89, v89
	v_exp_f32_e32 v90, v90
	v_exp_f32_e32 v91, v91
	s_waitcnt lgkmcnt(8)
	v_mfma_f32_32x32x16_bf16 v[32:47], v[128:131], v[56:59], v[32:47]
	v_exp_f32_e32 v92, v92
	v_exp_f32_e32 v93, v93
	v_exp_f32_e32 v94, v94
	v_exp_f32_e32 v95, v95
	s_waitcnt vmcnt(2) lgkmcnt(0)
	s_barrier
; #define WAIT_BAR(N) asm volatile("s_waitcnt vmcnt(" #N ") lgkmcnt(0)\n\ts_barrier":::"memory")
;   #define RESC() do{ if(!NOMAX&&resc){ asm volatile("s_waitcnt lgkmcnt(0)":::"memory"); \
;       _Pragma("unroll") for(int d_=0;d_<2*VM;++d_) _Pragma("unroll") for(int r=0;r<16;++r)o[d_][r]*=wsf[crow(r,hi)]; } }while(0)
;   #define ROT() do{sl_prev=sl_cur;sl_cur=sl_next;sl_next=(sl_next==(NSLOT-1)*SLOTB)?0:sl_next+SLOTB;}while(0)
; template<int THRL,int VM,bool NOMAX> __device__ __forceinline__ void attn_unit(const bf16*Qb,const bf16*__restrict__ Kh,const bf16*__restrict__ Vh,bf16*Ob,const int NT,const int sp,float*wscr,char*shm){
;     ...
;   int t=1;
;   for(;t+5<NT;t+=2){
;     STEP(pB0,pB1,pA0,pA1,t,true,true,true);     if constexpr(VM==2){WAIT_BAR(3);}else{WAIT_BAR(2);} RESC(); ROT();
;     STEP(pA0,pA1,pB0,pB1,t+1,true,true,true);   if constexpr(VM==2){WAIT_BAR(3);}else{WAIT_BAR(2);} RESC(); ROT();
	v_mfma_f32_32x32x16_bf16 v[64:79], v[60:63], v[156:159], 0
	s_add_i32 s35, s33, 0x2000
	s_cmpk_lg_i32 s33, 0x4000
	s_cselect_b32 s35, s35, 0
	v_add_u32_e32 v203, s34, v168
	ds_read_b64_tr_b16 v[190:191], v203 offset:24576
	ds_read_b64_tr_b16 v[192:193], v203 offset:25088
	v_add_f32_e32 v48, v96, v97
	v_add_f32_e32 v48, v98, v48
	v_add_f32_e32 v48, v99, v48
	v_add_f32_e32 v48, v100, v48
	v_add_f32_e32 v48, v101, v48
	v_cvt_pk_bf16_f32 v140, v96, v97
	v_cvt_pk_bf16_f32 v141, v98, v99
	ds_read_b64_tr_b16 v[96:97], v203 offset:28672
	ds_read_b64_tr_b16 v[98:99], v203 offset:29184
	v_add_f32_e32 v48, v102, v48
	v_add_f32_e32 v48, v103, v48
	v_add_f32_e32 v48, v104, v48
	v_add_f32_e32 v128, v105, v48
	s_waitcnt lgkmcnt(10)
	v_mfma_f32_32x32x16_bf16 v[48:63], v[112:115], v[156:159], 0
	s_add_i32 s34, s33, s17
	s_mov_b32 s52, m0
	s_mov_b32 m0, s34
	s_nop 0
	global_load_lds_dwordx4 v[176:177], off
	s_mov_b32 m0, s52
	v_cvt_pk_bf16_f32 v142, v100, v101
	v_cvt_pk_bf16_f32 v143, v102, v103
	ds_read_b64_tr_b16 v[100:101], v203 offset:25600
	ds_read_b64_tr_b16 v[102:103], v203 offset:26112
	s_waitcnt lgkmcnt(11)
	v_mfma_f32_32x32x16_bf16 v[64:79], v[116:119], v[152:155], v[64:79]
	s_add_i32 s34, s35, s16
	s_mov_b32 s52, m0
	s_mov_b32 m0, s34
	s_nop 0
	global_load_lds_dwordx4 v[174:175], off
	s_mov_b32 m0, s52
	v_add_f32_e32 v112, v106, v128
	v_add_f32_e32 v112, v107, v112
	v_add_f32_e32 v112, v108, v112
	v_add_f32_e32 v112, v109, v112
	v_cvt_pk_bf16_f32 v136, v104, v105
	v_cvt_pk_bf16_f32 v137, v106, v107
	ds_read_b64_tr_b16 v[104:105], v203 offset:29696
	ds_read_b64_tr_b16 v[106:107], v203 offset:30208
	s_waitcnt lgkmcnt(12)
	v_mfma_f32_32x32x16_bf16 v[48:63], v[120:123], v[152:155], v[48:63]
	v_add_f32_e32 v112, v110, v112
	v_add_f32_e32 v112, v111, v112
	v_add_f32_e32 v112, v80, v112
	v_add_f32_e32 v112, v81, v112
	v_cvt_pk_bf16_f32 v138, v108, v109
	v_cvt_pk_bf16_f32 v139, v110, v111
	ds_read_b64_tr_b16 v[108:109], v203 offset:26624
	ds_read_b64_tr_b16 v[110:111], v203 offset:27136
	s_waitcnt lgkmcnt(13)
	v_mfma_f32_32x32x16_bf16 v[64:79], v[124:127], v[148:151], v[64:79]
	v_add_f32_e32 v112, v82, v112
	v_add_f32_e32 v112, v83, v112
	v_add_f32_e32 v112, v84, v112
	v_add_f32_e32 v112, v85, v112
	v_cvt_pk_bf16_f32 v132, v80, v81
	v_cvt_pk_bf16_f32 v133, v82, v83
	ds_read_b64_tr_b16 v[194:195], v203 offset:30720
	ds_read_b64_tr_b16 v[196:197], v203 offset:31232
	s_waitcnt lgkmcnt(14)
	v_mfma_f32_32x32x16_bf16 v[48:63], v[160:163], v[148:151], v[48:63]
	v_add_f32_e32 v80, v86, v112
	v_add_f32_e32 v80, v87, v80
	v_add_f32_e32 v80, v88, v80
	v_add_f32_e32 v80, v89, v80
	v_cvt_pk_bf16_f32 v134, v84, v85
	v_cvt_pk_bf16_f32 v135, v86, v87
	ds_read_b64_tr_b16 v[198:199], v203 offset:27648
	ds_read_b64_tr_b16 v[200:201], v203 offset:28160
	s_waitcnt lgkmcnt(14)
	v_mfma_f32_32x32x16_bf16 v[64:79], v[164:167], v[144:147], v[64:79]
	v_add_f32_e32 v80, v90, v80
	v_add_f32_e32 v80, v91, v80
	v_add_f32_e32 v80, v92, v80
	v_add_f32_e32 v80, v93, v80
	v_cvt_pk_bf16_f32 v128, v88, v89
	v_cvt_pk_bf16_f32 v129, v90, v91
	ds_read_b64_tr_b16 v[88:89], v203 offset:31744
	ds_read_b64_tr_b16 v[90:91], v203 offset:32256
	v_mfma_f32_32x32x16_bf16 v[48:63], v[186:189], v[144:147], v[48:63]
	v_add_f32_e32 v80, v94, v80
	v_add_f32_e32 v80, v95, v80
	v_add_f32_e32 v80, 0, v80
	v_cvt_pk_bf16_f32 v130, v92, v93
	v_cvt_pk_bf16_f32 v131, v94, v95
	v_add_f32_e32 v186, v202, v80
	s_waitcnt lgkmcnt(14)
	v_mfma_f32_32x32x16_bf16 v[16:31], v[140:143], v[190:193], v[16:31]
	v_exp_f32_e32 v64, v64
	v_exp_f32_e32 v65, v65
	v_exp_f32_e32 v66, v66
	v_exp_f32_e32 v67, v67
	s_waitcnt lgkmcnt(12)
	v_mfma_f32_32x32x16_bf16 v[32:47], v[140:143], v[96:99], v[32:47]
	v_exp_f32_e32 v68, v68
	v_exp_f32_e32 v69, v69
	v_exp_f32_e32 v70, v70
	v_exp_f32_e32 v71, v71
	v_add_u32_e32 v242, s35, v234
	v_add_u32_e32 v243, s35, v235
	v_add_u32_e32 v244, s35, v236
	v_add_u32_e32 v245, s35, v237
	ds_read_b128 v[84:87], v242
	ds_read_b128 v[80:83], v242 offset:4096
	s_waitcnt lgkmcnt(12)
	v_mfma_f32_32x32x16_bf16 v[16:31], v[136:139], v[100:103], v[16:31]
	v_exp_f32_e32 v72, v72
	v_exp_f32_e32 v73, v73
	v_exp_f32_e32 v74, v74
	v_exp_f32_e32 v75, v75
	ds_read_b128 v[164:167], v243
	ds_read_b128 v[160:163], v243 offset:4096
	s_waitcnt lgkmcnt(12)
	v_mfma_f32_32x32x16_bf16 v[32:47], v[136:139], v[104:107], v[32:47]
	v_exp_f32_e32 v76, v76
	v_exp_f32_e32 v77, v77
	v_exp_f32_e32 v78, v78
	v_exp_f32_e32 v79, v79
	ds_read_b128 v[124:127], v244
	ds_read_b128 v[120:123], v244 offset:4096
	s_waitcnt lgkmcnt(12)
	v_mfma_f32_32x32x16_bf16 v[16:31], v[132:135], v[108:111], v[16:31]
	v_exp_f32_e32 v48, v48
	v_exp_f32_e32 v49, v49
	v_exp_f32_e32 v50, v50
	v_exp_f32_e32 v51, v51
	ds_read_b128 v[116:119], v245
	ds_read_b128 v[112:115], v245 offset:4096
	s_waitcnt lgkmcnt(12)
	v_mfma_f32_32x32x16_bf16 v[32:47], v[132:135], v[194:197], v[32:47]
	v_exp_f32_e32 v52, v52
	v_exp_f32_e32 v53, v53
	v_exp_f32_e32 v54, v54
	v_exp_f32_e32 v55, v55
	s_waitcnt lgkmcnt(10)
	v_mfma_f32_32x32x16_bf16 v[16:31], v[128:131], v[198:201], v[16:31]
	v_exp_f32_e32 v56, v56
	v_exp_f32_e32 v57, v57
	v_exp_f32_e32 v58, v58
	v_exp_f32_e32 v59, v59
	s_waitcnt lgkmcnt(8)
	v_mfma_f32_32x32x16_bf16 v[32:47], v[128:131], v[88:91], v[32:47]
	v_exp_f32_e32 v60, v60
	v_exp_f32_e32 v61, v61
	v_exp_f32_e32 v62, v62
	v_exp_f32_e32 v63, v63
	s_add_i32 s53, s35, 0x2000
	s_waitcnt vmcnt(2) lgkmcnt(0)
	s_barrier
	s_cmpk_lg_i32 s35, 0x4000
	s_mov_b32 s52, s33
	s_cselect_b32 s33, s53, 0
	s_add_i32 s29, s29, 2
	v_lshl_add_u64 v[174:175], v[174:175], 0, s[8:9]
	v_lshl_add_u64 v[176:177], v[176:177], 0, s[8:9]
	s_mov_b32 s34, s35
	s_cmp_lt_u32 s29, 57
	s_cbranch_scc1 .LBB0_891
	s_and_b32 s19, s19, 0x3fffffc0
	s_lshl_b32 s19, s19, 2
	s_add_i32 s19, s19, 0
	s_cmp_lg_u32 0, -1
	s_cselect_b32 s29, 0, 0
	s_add_i32 s33, s29, 0x6000
	v_add_u32_e32 v88, s33, v184
	v_add3_u32 v174, v88, v183, v185
	ds_read_b64_tr_b16 v[188:189], v168 offset:32768
	ds_read_b64_tr_b16 v[190:191], v168 offset:33280
	v_add_f32_e32 v88, v64, v65
	v_add_f32_e32 v88, v66, v88
	v_add_f32_e32 v88, v67, v88
	v_add_f32_e32 v88, v68, v88
	v_add_f32_e32 v88, v69, v88
	v_cvt_pk_bf16_f32 v140, v64, v65
	v_cvt_pk_bf16_f32 v141, v66, v67
	s_waitcnt lgkmcnt(9)
	v_mfma_f32_32x32x16_bf16 v[96:111], v[84:87], v[156:159], 0
	ds_read_b64_tr_b16 v[64:65], v168 offset:36864
	ds_read_b64_tr_b16 v[66:67], v168 offset:37376
	v_add_f32_e32 v84, v70, v88
	v_add_f32_e32 v84, v71, v84
	v_add_f32_e32 v84, v72, v84
	v_add_f32_e32 v128, v73, v84
	v_cvt_pk_bf16_f32 v142, v68, v69
	v_cvt_pk_bf16_f32 v143, v70, v71
	s_waitcnt lgkmcnt(10)
	v_mfma_f32_32x32x16_bf16 v[80:95], v[80:83], v[156:159], 0
	ds_read_b64_tr_b16 v[68:69], v168 offset:33792
	ds_read_b64_tr_b16 v[70:71], v168 offset:34304
	v_add_f32_e32 v128, v74, v128
	v_add_f32_e32 v128, v75, v128
	v_add_f32_e32 v128, v76, v128
	v_add_f32_e32 v128, v77, v128
	v_cvt_pk_bf16_f32 v136, v72, v73
	v_cvt_pk_bf16_f32 v137, v74, v75
	s_waitcnt lgkmcnt(11)
	v_mfma_f32_32x32x16_bf16 v[96:111], v[164:167], v[152:155], v[96:111]
	ds_read_b64_tr_b16 v[72:73], v168 offset:37888
	ds_read_b64_tr_b16 v[74:75], v168 offset:38400
	v_add_f32_e32 v128, v78, v128
	v_add_f32_e32 v128, v79, v128
	v_add_f32_e32 v128, v48, v128
	v_add_f32_e32 v128, v49, v128
	v_cvt_pk_bf16_f32 v138, v76, v77
	v_cvt_pk_bf16_f32 v139, v78, v79
	s_waitcnt lgkmcnt(12)
	v_mfma_f32_32x32x16_bf16 v[80:95], v[160:163], v[152:155], v[80:95]
	ds_read_b64_tr_b16 v[76:77], v168 offset:34816
	ds_read_b64_tr_b16 v[78:79], v168 offset:35328
	v_add_f32_e32 v128, v50, v128
	v_add_f32_e32 v128, v51, v128
	v_add_f32_e32 v128, v52, v128
	v_add_f32_e32 v128, v53, v128
	v_cvt_pk_bf16_f32 v132, v48, v49
	v_cvt_pk_bf16_f32 v133, v50, v51
	s_waitcnt lgkmcnt(13)
	v_mfma_f32_32x32x16_bf16 v[96:111], v[124:127], v[148:151], v[96:111]
	ds_read_b64_tr_b16 v[48:49], v168 offset:38912
	ds_read_b64_tr_b16 v[50:51], v168 offset:39424
	v_add_f32_e32 v124, v54, v128
	v_add_f32_e32 v124, v55, v124
	v_add_f32_e32 v124, v56, v124
	v_add_f32_e32 v124, v57, v124
	v_cvt_pk_bf16_f32 v134, v52, v53
	v_cvt_pk_bf16_f32 v135, v54, v55
	s_waitcnt lgkmcnt(14)
	v_mfma_f32_32x32x16_bf16 v[80:95], v[120:123], v[148:151], v[80:95]
	ds_read_b64_tr_b16 v[52:53], v168 offset:35840
	ds_read_b64_tr_b16 v[54:55], v168 offset:36352
	v_add_f32_e32 v120, v58, v124
	v_add_f32_e32 v120, v59, v120
	v_add_f32_e32 v120, v60, v120
	v_add_f32_e32 v120, v61, v120
	v_cvt_pk_bf16_f32 v128, v56, v57
	v_cvt_pk_bf16_f32 v129, v58, v59
	s_waitcnt lgkmcnt(14)
	v_mfma_f32_32x32x16_bf16 v[96:111], v[116:119], v[144:147], v[96:111]
	ds_read_b64_tr_b16 v[56:57], v168 offset:39936
	ds_read_b64_tr_b16 v[58:59], v168 offset:40448
	v_add_f32_e32 v116, v62, v120
	v_add_f32_e32 v116, v63, v116
	v_add_f32_e32 v116, 0, v116
	v_cvt_pk_bf16_f32 v130, v60, v61
	v_cvt_pk_bf16_f32 v131, v62, v63
	v_mfma_f32_32x32x16_bf16 v[80:95], v[112:115], v[144:147], v[80:95]
	s_add_i32 s28, s29, s28
	v_lshl_add_u64 v[60:61], v[172:173], 0, s[40:41]
	s_add_i32 s29, s28, 0x4000
	s_mov_b32 s33, m0
	s_mov_b32 m0, s29
	s_nop 0
	global_load_lds_dwordx4 v[60:61], off
	s_mov_b32 m0, s33
	v_lshl_add_u64 v[60:61], v[170:171], 0, s[42:43]
	s_mov_b32 s29, m0
	s_mov_b32 m0, s16
	s_nop 0
	global_load_lds_dwordx4 v[60:61], off
	s_mov_b32 m0, s29
	v_add_f32_e32 v175, v186, v116
	s_waitcnt lgkmcnt(14)
	v_mfma_f32_32x32x16_bf16 v[16:31], v[140:143], v[188:191], v[16:31]
	v_exp_f32_e32 v96, v96
	v_exp_f32_e32 v97, v97
	v_exp_f32_e32 v98, v98
	v_exp_f32_e32 v99, v99
	s_waitcnt lgkmcnt(12)
	v_mfma_f32_32x32x16_bf16 v[32:47], v[140:143], v[64:67], v[32:47]
	v_exp_f32_e32 v100, v100
	v_exp_f32_e32 v101, v101
	v_exp_f32_e32 v102, v102
	v_exp_f32_e32 v103, v103
	ds_read_b128 v[60:63], v234
	ds_read_b128 v[64:67], v234 offset:4096
	s_waitcnt lgkmcnt(12)
	v_mfma_f32_32x32x16_bf16 v[16:31], v[136:139], v[68:71], v[16:31]
	v_exp_f32_e32 v104, v104
	v_exp_f32_e32 v105, v105
	v_exp_f32_e32 v106, v106
	v_exp_f32_e32 v107, v107
	ds_read_b128 v[68:71], v235
	ds_read_b128 v[160:163], v235 offset:4096
	s_waitcnt lgkmcnt(12)
	v_mfma_f32_32x32x16_bf16 v[32:47], v[136:139], v[72:75], v[32:47]
	v_exp_f32_e32 v108, v108
	v_exp_f32_e32 v109, v109
	v_exp_f32_e32 v110, v110
	v_exp_f32_e32 v111, v111
	ds_read_b128 v[72:75], v236
	ds_read_b128 v[164:167], v236 offset:4096
	s_waitcnt lgkmcnt(12)
	v_mfma_f32_32x32x16_bf16 v[16:31], v[132:135], v[76:79], v[16:31]
	v_exp_f32_e32 v80, v80
	v_exp_f32_e32 v81, v81
	v_exp_f32_e32 v82, v82
	v_exp_f32_e32 v83, v83
	ds_read_b128 v[76:79], v237
	ds_read_b128 v[184:187], v237 offset:4096
	s_waitcnt lgkmcnt(12)
	v_mfma_f32_32x32x16_bf16 v[32:47], v[132:135], v[48:51], v[32:47]
	v_exp_f32_e32 v84, v84
	v_exp_f32_e32 v85, v85
	v_exp_f32_e32 v86, v86
	v_exp_f32_e32 v87, v87
	s_waitcnt lgkmcnt(10)
	v_mfma_f32_32x32x16_bf16 v[16:31], v[128:131], v[52:55], v[16:31]
	v_exp_f32_e32 v88, v88
	v_exp_f32_e32 v89, v89
	v_exp_f32_e32 v90, v90
	v_exp_f32_e32 v91, v91
	s_waitcnt lgkmcnt(8)
	v_mfma_f32_32x32x16_bf16 v[32:47], v[128:131], v[56:59], v[32:47]
	v_exp_f32_e32 v92, v92
	v_exp_f32_e32 v93, v93
	v_exp_f32_e32 v94, v94
	v_exp_f32_e32 v95, v95
	s_waitcnt vmcnt(2) lgkmcnt(0)
	s_barrier
	ds_read_b64_tr_b16 v[188:189], v168 offset:40960
	ds_read_b64_tr_b16 v[190:191], v168 offset:41472
	v_add_f32_e32 v48, v96, v97
	v_add_f32_e32 v48, v98, v48
	v_add_f32_e32 v48, v99, v48
	v_add_f32_e32 v48, v100, v48
	v_add_f32_e32 v48, v101, v48
	v_cvt_pk_bf16_f32 v140, v96, v97
	v_cvt_pk_bf16_f32 v141, v98, v99
	s_waitcnt lgkmcnt(9)
	v_mfma_f32_32x32x16_bf16 v[112:127], v[60:63], v[156:159], 0
	ds_read_b64_tr_b16 v[96:97], v168 offset:45056
	ds_read_b64_tr_b16 v[98:99], v168 offset:45568
	v_add_f32_e32 v48, v102, v48
	v_add_f32_e32 v48, v103, v48
	v_add_f32_e32 v48, v104, v48
	v_add_f32_e32 v128, v105, v48
	s_waitcnt lgkmcnt(10)
	v_mfma_f32_32x32x16_bf16 v[48:63], v[64:67], v[156:159], 0
	v_cvt_pk_bf16_f32 v142, v100, v101
	v_cvt_pk_bf16_f32 v143, v102, v103
	ds_read_b64_tr_b16 v[64:65], v168 offset:41984
	ds_read_b64_tr_b16 v[66:67], v168 offset:42496
	v_add_f32_e32 v100, v106, v128
	v_add_f32_e32 v100, v107, v100
	v_add_f32_e32 v100, v108, v100
	v_add_f32_e32 v100, v109, v100
	v_cvt_pk_bf16_f32 v136, v104, v105
	v_cvt_pk_bf16_f32 v137, v106, v107
	s_waitcnt lgkmcnt(11)
	v_mfma_f32_32x32x16_bf16 v[112:127], v[68:71], v[152:155], v[112:127]
	ds_read_b64_tr_b16 v[68:69], v168 offset:46080
	ds_read_b64_tr_b16 v[70:71], v168 offset:46592
	s_waitcnt lgkmcnt(12)
	v_mfma_f32_32x32x16_bf16 v[48:63], v[160:163], v[152:155], v[48:63]
	v_add_f32_e32 v100, v110, v100
	v_add_f32_e32 v100, v111, v100
	v_add_f32_e32 v100, v80, v100
	v_add_f32_e32 v104, v81, v100
	v_cvt_pk_bf16_f32 v138, v108, v109
	v_cvt_pk_bf16_f32 v139, v110, v111
	ds_read_b64_tr_b16 v[100:101], v168 offset:43008
	ds_read_b64_tr_b16 v[102:103], v168 offset:43520
	v_add_f32_e32 v104, v82, v104
	v_add_f32_e32 v104, v83, v104
	v_add_f32_e32 v104, v84, v104
	v_add_f32_e32 v104, v85, v104
	v_cvt_pk_bf16_f32 v132, v80, v81
	v_cvt_pk_bf16_f32 v133, v82, v83
	s_waitcnt lgkmcnt(13)
	v_mfma_f32_32x32x16_bf16 v[112:127], v[72:75], v[148:151], v[112:127]
	ds_read_b64_tr_b16 v[72:73], v168 offset:47104
	ds_read_b64_tr_b16 v[74:75], v168 offset:47616
	s_waitcnt lgkmcnt(14)
	v_mfma_f32_32x32x16_bf16 v[48:63], v[164:167], v[148:151], v[48:63]
	v_add_f32_e32 v80, v86, v104
	v_add_f32_e32 v80, v87, v80
	v_add_f32_e32 v80, v88, v80
	v_add_f32_e32 v104, v89, v80
	v_cvt_pk_bf16_f32 v134, v84, v85
	v_cvt_pk_bf16_f32 v135, v86, v87
	ds_read_b64_tr_b16 v[80:81], v168 offset:44032
	ds_read_b64_tr_b16 v[82:83], v168 offset:44544
	v_add_f32_e32 v84, v90, v104
	v_add_f32_e32 v84, v91, v84
	v_add_f32_e32 v84, v92, v84
	v_add_f32_e32 v84, v93, v84
	v_cvt_pk_bf16_f32 v128, v88, v89
	v_cvt_pk_bf16_f32 v129, v90, v91
	s_waitcnt lgkmcnt(14)
	v_mfma_f32_32x32x16_bf16 v[112:127], v[76:79], v[144:147], v[112:127]
	ds_read_b64_tr_b16 v[76:77], v168 offset:48128
	ds_read_b64_tr_b16 v[78:79], v168 offset:48640
	v_mfma_f32_32x32x16_bf16 v[48:63], v[184:187], v[144:147], v[48:63]
	v_add_f32_e32 v84, v94, v84
	v_add_f32_e32 v84, v95, v84
	v_add_f32_e32 v84, 0, v84
	v_cvt_pk_bf16_f32 v130, v92, v93
	v_cvt_pk_bf16_f32 v131, v94, v95
	s_nop 0
	v_add_f32_e32 v175, v175, v84
	v_lshl_add_u64 v[84:85], v[172:173], 0, s[44:45]
	s_mov_b32 s29, m0
	s_mov_b32 m0, s17
	s_nop 0
	global_load_lds_dwordx4 v[84:85], off
	s_mov_b32 m0, s29
	v_lshl_add_u64 v[84:85], v[170:171], 0, s[48:49]
	s_add_i32 s17, s28, 0x8000
	s_mov_b32 s29, m0
	s_mov_b32 m0, s17
	s_nop 0
	global_load_lds_dwordx4 v[84:85], off
	s_mov_b32 m0, s29
	s_waitcnt lgkmcnt(14)
	v_mfma_f32_32x32x16_bf16 v[16:31], v[140:143], v[188:191], v[16:31]
	v_exp_f32_e32 v112, v112
	v_exp_f32_e32 v113, v113
	v_exp_f32_e32 v114, v114
	v_exp_f32_e32 v115, v115
	s_waitcnt lgkmcnt(12)
	v_mfma_f32_32x32x16_bf16 v[32:47], v[140:143], v[96:99], v[32:47]
	v_exp_f32_e32 v116, v116
	v_exp_f32_e32 v117, v117
	v_exp_f32_e32 v118, v118
	v_exp_f32_e32 v119, v119
	ds_read_b128 v[84:87], v234 offset:8192
	ds_read_b128 v[96:99], v234 offset:12288
	s_waitcnt lgkmcnt(12)
	v_mfma_f32_32x32x16_bf16 v[16:31], v[136:139], v[64:67], v[16:31]
	v_exp_f32_e32 v120, v120
	v_exp_f32_e32 v121, v121
	v_exp_f32_e32 v122, v122
	v_exp_f32_e32 v123, v123
	ds_read_b128 v[104:107], v235 offset:8192
	ds_read_b128 v[108:111], v235 offset:12288
	s_waitcnt lgkmcnt(12)
	v_mfma_f32_32x32x16_bf16 v[32:47], v[136:139], v[68:71], v[32:47]
	v_exp_f32_e32 v124, v124
	v_exp_f32_e32 v125, v125
	v_exp_f32_e32 v126, v126
	v_exp_f32_e32 v127, v127
	ds_read_b128 v[160:163], v236 offset:8192
	ds_read_b128 v[164:167], v236 offset:12288
	s_waitcnt lgkmcnt(12)
	v_mfma_f32_32x32x16_bf16 v[16:31], v[132:135], v[100:103], v[16:31]
	v_exp_f32_e32 v48, v48
	v_exp_f32_e32 v49, v49
	v_exp_f32_e32 v50, v50
	v_exp_f32_e32 v51, v51
	ds_read_b128 v[100:103], v237 offset:8192
	ds_read_b128 v[184:187], v237 offset:12288
	s_waitcnt lgkmcnt(12)
	v_mfma_f32_32x32x16_bf16 v[32:47], v[132:135], v[72:75], v[32:47]
	v_exp_f32_e32 v52, v52
	v_exp_f32_e32 v53, v53
	v_exp_f32_e32 v54, v54
	v_exp_f32_e32 v55, v55
	s_waitcnt lgkmcnt(10)
	v_mfma_f32_32x32x16_bf16 v[16:31], v[128:131], v[80:83], v[16:31]
	v_exp_f32_e32 v56, v56
	v_exp_f32_e32 v57, v57
	v_exp_f32_e32 v58, v58
	v_exp_f32_e32 v59, v59
	s_waitcnt lgkmcnt(8)
	v_mfma_f32_32x32x16_bf16 v[32:47], v[128:131], v[76:79], v[32:47]
	v_exp_f32_e32 v60, v60
	v_exp_f32_e32 v61, v61
	v_exp_f32_e32 v62, v62
	v_exp_f32_e32 v63, v63
	s_waitcnt vmcnt(2) lgkmcnt(0)
	s_barrier
	ds_read_b64_tr_b16 v[188:189], v168 offset:24576
	ds_read_b64_tr_b16 v[190:191], v168 offset:25088
	v_add_f32_e32 v64, v112, v113
	v_add_f32_e32 v64, v114, v64
	v_add_f32_e32 v64, v115, v64
	v_add_f32_e32 v64, v116, v64
	v_add_f32_e32 v64, v117, v64
	v_cvt_pk_bf16_f32 v140, v112, v113
	v_cvt_pk_bf16_f32 v141, v114, v115
	s_waitcnt lgkmcnt(9)
	v_mfma_f32_32x32x16_bf16 v[80:95], v[84:87], v[156:159], 0
	ds_read_b64_tr_b16 v[112:113], v168 offset:28672
	ds_read_b64_tr_b16 v[114:115], v168 offset:29184
	v_add_f32_e32 v64, v118, v64
	v_add_f32_e32 v64, v119, v64
	v_add_f32_e32 v64, v120, v64
	v_add_f32_e32 v128, v121, v64
	v_cvt_pk_bf16_f32 v142, v116, v117
	v_cvt_pk_bf16_f32 v143, v118, v119
	s_waitcnt lgkmcnt(10)
	v_mfma_f32_32x32x16_bf16 v[64:79], v[96:99], v[156:159], 0
	ds_read_b64_tr_b16 v[96:97], v168 offset:25600
	ds_read_b64_tr_b16 v[98:99], v168 offset:26112
	v_add_f32_e32 v116, v122, v128
	v_add_f32_e32 v116, v123, v116
	v_add_f32_e32 v116, v124, v116
	v_add_f32_e32 v116, v125, v116
	v_cvt_pk_bf16_f32 v136, v120, v121
	v_cvt_pk_bf16_f32 v137, v122, v123
	s_waitcnt lgkmcnt(11)
	v_mfma_f32_32x32x16_bf16 v[80:95], v[104:107], v[152:155], v[80:95]
	ds_read_b64_tr_b16 v[104:105], v168 offset:29696
	ds_read_b64_tr_b16 v[106:107], v168 offset:30208
	v_add_f32_e32 v116, v126, v116
	v_add_f32_e32 v116, v127, v116
	v_add_f32_e32 v116, v48, v116
	v_add_f32_e32 v116, v49, v116
	v_cvt_pk_bf16_f32 v138, v124, v125
	v_cvt_pk_bf16_f32 v139, v126, v127
	s_waitcnt lgkmcnt(12)
	v_mfma_f32_32x32x16_bf16 v[64:79], v[108:111], v[152:155], v[64:79]
	ds_read_b64_tr_b16 v[108:109], v168 offset:26624
	ds_read_b64_tr_b16 v[110:111], v168 offset:27136
	v_add_f32_e32 v116, v50, v116
	v_add_f32_e32 v116, v51, v116
	v_add_f32_e32 v116, v52, v116
	v_add_f32_e32 v116, v53, v116
	v_cvt_pk_bf16_f32 v132, v48, v49
	v_cvt_pk_bf16_f32 v133, v50, v51
	s_waitcnt lgkmcnt(13)
	v_mfma_f32_32x32x16_bf16 v[80:95], v[160:163], v[148:151], v[80:95]
	ds_read_b64_tr_b16 v[48:49], v168 offset:30720
	ds_read_b64_tr_b16 v[50:51], v168 offset:31232
	v_add_f32_e32 v116, v54, v116
	v_add_f32_e32 v116, v55, v116
	v_add_f32_e32 v116, v56, v116
	v_add_f32_e32 v116, v57, v116
	v_cvt_pk_bf16_f32 v134, v52, v53
	v_cvt_pk_bf16_f32 v135, v54, v55
	s_waitcnt lgkmcnt(14)
	v_mfma_f32_32x32x16_bf16 v[64:79], v[164:167], v[148:151], v[64:79]
	ds_read_b64_tr_b16 v[52:53], v168 offset:27648
	ds_read_b64_tr_b16 v[54:55], v168 offset:28160
	v_add_f32_e32 v116, v58, v116
	v_add_f32_e32 v116, v59, v116
	v_add_f32_e32 v116, v60, v116
	v_add_f32_e32 v116, v61, v116
	v_cvt_pk_bf16_f32 v128, v56, v57
	v_cvt_pk_bf16_f32 v129, v58, v59
	s_waitcnt lgkmcnt(14)
	v_mfma_f32_32x32x16_bf16 v[80:95], v[100:103], v[144:147], v[80:95]
	ds_read_b64_tr_b16 v[56:57], v168 offset:31744
	ds_read_b64_tr_b16 v[58:59], v168 offset:32256
	v_add_f32_e32 v100, v62, v116
	v_add_f32_e32 v100, v63, v100
	v_add_f32_e32 v100, 0, v100
	v_cvt_pk_bf16_f32 v130, v60, v61
	v_cvt_pk_bf16_f32 v131, v62, v63
	v_mfma_f32_32x32x16_bf16 v[64:79], v[184:187], v[144:147], v[64:79]
	v_lshl_add_u64 v[60:61], v[170:171], 0, s[40:41]
	s_add_i32 s28, s28, 0xa000
	s_mov_b32 s17, m0
	s_mov_b32 m0, s28
	s_nop 0
	global_load_lds_dwordx4 v[60:61], off
	s_mov_b32 m0, s17
	v_add_f32_e32 v172, v175, v100
	s_waitcnt lgkmcnt(14)
	v_mfma_f32_32x32x16_bf16 v[16:31], v[140:143], v[188:191], v[16:31]
	v_exp_f32_e32 v80, v80
	v_exp_f32_e32 v81, v81
	v_exp_f32_e32 v82, v82
	v_exp_f32_e32 v83, v83
	s_waitcnt lgkmcnt(12)
	v_mfma_f32_32x32x16_bf16 v[32:47], v[140:143], v[112:115], v[32:47]
	v_exp_f32_e32 v84, v84
	v_exp_f32_e32 v85, v85
	v_exp_f32_e32 v86, v86
	v_exp_f32_e32 v87, v87
	ds_read_b128 v[60:63], v234 offset:16384
	ds_read_b128 v[112:115], v234 offset:20480
	s_waitcnt lgkmcnt(12)
	v_mfma_f32_32x32x16_bf16 v[16:31], v[136:139], v[96:99], v[16:31]
	v_exp_f32_e32 v88, v88
	v_exp_f32_e32 v89, v89
	v_exp_f32_e32 v90, v90
	v_exp_f32_e32 v91, v91
	ds_read_b128 v[116:119], v235 offset:16384
	ds_read_b128 v[120:123], v235 offset:20480
	s_waitcnt lgkmcnt(12)
	v_mfma_f32_32x32x16_bf16 v[32:47], v[136:139], v[104:107], v[32:47]
	v_exp_f32_e32 v92, v92
	v_exp_f32_e32 v93, v93
	v_exp_f32_e32 v94, v94
	v_exp_f32_e32 v95, v95
	ds_read_b128 v[124:127], v236 offset:16384
	ds_read_b128 v[160:163], v236 offset:20480
	s_waitcnt lgkmcnt(12)
	v_mfma_f32_32x32x16_bf16 v[16:31], v[132:135], v[108:111], v[16:31]
	v_exp_f32_e32 v64, v64
	v_exp_f32_e32 v65, v65
	v_exp_f32_e32 v66, v66
	v_exp_f32_e32 v67, v67
	ds_read_b128 v[164:167], v237 offset:16384
	ds_read_b128 v[184:187], v237 offset:20480
	s_waitcnt lgkmcnt(12)
	v_mfma_f32_32x32x16_bf16 v[32:47], v[132:135], v[48:51], v[32:47]
	v_exp_f32_e32 v68, v68
	v_exp_f32_e32 v69, v69
	v_exp_f32_e32 v70, v70
	v_exp_f32_e32 v71, v71
	s_waitcnt lgkmcnt(10)
	v_mfma_f32_32x32x16_bf16 v[16:31], v[128:131], v[52:55], v[16:31]
	v_exp_f32_e32 v72, v72
	v_exp_f32_e32 v73, v73
	v_exp_f32_e32 v74, v74
	v_exp_f32_e32 v75, v75
	s_waitcnt lgkmcnt(8)
	v_mfma_f32_32x32x16_bf16 v[32:47], v[128:131], v[56:59], v[32:47]
	v_exp_f32_e32 v76, v76
	v_exp_f32_e32 v77, v77
	v_exp_f32_e32 v78, v78
	v_exp_f32_e32 v79, v79
	s_waitcnt vmcnt(1) lgkmcnt(0)
	s_barrier
	ds_read_b64_tr_b16 v[188:189], v168 offset:32768
	ds_read_b64_tr_b16 v[190:191], v168 offset:33280
	v_add_f32_e32 v48, v80, v81
	v_add_f32_e32 v48, v82, v48
	v_add_f32_e32 v48, v83, v48
	v_add_f32_e32 v48, v84, v48
	v_add_f32_e32 v48, v85, v48
	v_cvt_pk_bf16_f32 v140, v80, v81
	v_cvt_pk_bf16_f32 v141, v82, v83
	s_waitcnt lgkmcnt(9)
	v_mfma_f32_32x32x16_bf16 v[96:111], v[60:63], v[156:159], 0
	ds_read_b64_tr_b16 v[80:81], v168 offset:36864
	ds_read_b64_tr_b16 v[82:83], v168 offset:37376
	v_add_f32_e32 v48, v86, v48
	v_add_f32_e32 v48, v87, v48
	v_add_f32_e32 v48, v88, v48
	v_add_f32_e32 v128, v89, v48
	s_waitcnt lgkmcnt(10)
	v_mfma_f32_32x32x16_bf16 v[48:63], v[112:115], v[156:159], 0
	v_cvt_pk_bf16_f32 v142, v84, v85
	v_cvt_pk_bf16_f32 v143, v86, v87
	ds_read_b64_tr_b16 v[84:85], v168 offset:33792
	ds_read_b64_tr_b16 v[86:87], v168 offset:34304
	v_add_f32_e32 v112, v90, v128
	v_add_f32_e32 v112, v91, v112
	v_add_f32_e32 v112, v92, v112
	v_add_f32_e32 v112, v93, v112
	v_cvt_pk_bf16_f32 v136, v88, v89
	v_cvt_pk_bf16_f32 v137, v90, v91
	s_waitcnt lgkmcnt(11)
	v_mfma_f32_32x32x16_bf16 v[96:111], v[116:119], v[152:155], v[96:111]
	ds_read_b64_tr_b16 v[88:89], v168 offset:37888
	ds_read_b64_tr_b16 v[90:91], v168 offset:38400
	s_waitcnt lgkmcnt(12)
	v_mfma_f32_32x32x16_bf16 v[48:63], v[120:123], v[152:155], v[48:63]
	v_add_f32_e32 v112, v94, v112
	v_add_f32_e32 v112, v95, v112
	v_add_f32_e32 v112, v64, v112
	v_add_f32_e32 v112, v65, v112
	v_cvt_pk_bf16_f32 v138, v92, v93
	v_cvt_pk_bf16_f32 v139, v94, v95
	ds_read_b64_tr_b16 v[92:93], v168 offset:34816
	ds_read_b64_tr_b16 v[94:95], v168 offset:35328
	v_add_f32_e32 v112, v66, v112
	v_add_f32_e32 v112, v67, v112
	v_add_f32_e32 v112, v68, v112
	v_add_f32_e32 v112, v69, v112
	v_cvt_pk_bf16_f32 v132, v64, v65
	v_cvt_pk_bf16_f32 v133, v66, v67
	s_waitcnt lgkmcnt(13)
	v_mfma_f32_32x32x16_bf16 v[96:111], v[124:127], v[148:151], v[96:111]
	ds_read_b64_tr_b16 v[64:65], v168 offset:38912
	ds_read_b64_tr_b16 v[66:67], v168 offset:39424
	s_waitcnt lgkmcnt(14)
	v_mfma_f32_32x32x16_bf16 v[48:63], v[160:163], v[148:151], v[48:63]
	v_add_f32_e32 v112, v70, v112
	v_add_f32_e32 v112, v71, v112
	v_add_f32_e32 v112, v72, v112
	v_add_f32_e32 v112, v73, v112
	v_cvt_pk_bf16_f32 v134, v68, v69
	v_cvt_pk_bf16_f32 v135, v70, v71
	ds_read_b64_tr_b16 v[68:69], v168 offset:35840
	ds_read_b64_tr_b16 v[70:71], v168 offset:36352
	v_add_f32_e32 v112, v74, v112
	v_add_f32_e32 v112, v75, v112
	v_add_f32_e32 v112, v76, v112
	v_add_f32_e32 v112, v77, v112
	v_cvt_pk_bf16_f32 v128, v72, v73
	v_cvt_pk_bf16_f32 v129, v74, v75
	s_waitcnt lgkmcnt(14)
	v_mfma_f32_32x32x16_bf16 v[96:111], v[164:167], v[144:147], v[96:111]
	ds_read_b64_tr_b16 v[72:73], v168 offset:39936
	ds_read_b64_tr_b16 v[74:75], v168 offset:40448
	v_mfma_f32_32x32x16_bf16 v[48:63], v[184:187], v[144:147], v[48:63]
	v_add_f32_e32 v112, v78, v112
	v_add_f32_e32 v112, v79, v112
	v_add_f32_e32 v112, 0, v112
	v_cvt_pk_bf16_f32 v130, v76, v77
	v_cvt_pk_bf16_f32 v131, v78, v79
	v_lshl_add_u64 v[76:77], v[170:171], 0, s[44:45]
	s_mov_b32 s17, m0
	s_mov_b32 m0, s16
	s_nop 0
	global_load_lds_dwordx4 v[76:77], off
	s_mov_b32 m0, s17
	v_add_f32_e32 v120, v172, v112
	s_waitcnt lgkmcnt(14)
	v_mfma_f32_32x32x16_bf16 v[16:31], v[140:143], v[188:191], v[16:31]
	v_exp_f32_e32 v96, v96
	v_exp_f32_e32 v97, v97
	v_exp_f32_e32 v98, v98
	v_exp_f32_e32 v99, v99
	s_waitcnt lgkmcnt(12)
	v_mfma_f32_32x32x16_bf16 v[32:47], v[140:143], v[80:83], v[32:47]
	v_exp_f32_e32 v100, v100
	v_exp_f32_e32 v101, v101
	v_exp_f32_e32 v102, v102
	v_exp_f32_e32 v103, v103
	ds_read_b128 v[76:79], v234
	ds_read_b128 v[80:83], v234 offset:4096
	s_waitcnt lgkmcnt(12)
	v_mfma_f32_32x32x16_bf16 v[16:31], v[136:139], v[84:87], v[16:31]
	v_exp_f32_e32 v104, v104
	v_exp_f32_e32 v105, v105
	v_exp_f32_e32 v106, v106
	v_exp_f32_e32 v107, v107
	ds_read_b128 v[122:125], v235
	ds_read_b128 v[160:163], v235 offset:4096
	s_waitcnt lgkmcnt(12)
	v_mfma_f32_32x32x16_bf16 v[32:47], v[136:139], v[88:91], v[32:47]
	v_exp_f32_e32 v108, v108
	v_exp_f32_e32 v109, v109
	v_exp_f32_e32 v110, v110
	v_exp_f32_e32 v111, v111
	ds_read_b128 v[164:167], v236
	ds_read_b128 v[170:173], v236 offset:4096
	s_waitcnt lgkmcnt(12)
	v_mfma_f32_32x32x16_bf16 v[16:31], v[132:135], v[92:95], v[16:31]
	v_exp_f32_e32 v48, v48
	v_exp_f32_e32 v49, v49
	v_exp_f32_e32 v50, v50
	v_exp_f32_e32 v51, v51
	ds_read_b128 v[184:187], v237
	ds_read_b128 v[188:191], v237 offset:4096
	s_waitcnt lgkmcnt(12)
	v_mfma_f32_32x32x16_bf16 v[32:47], v[132:135], v[64:67], v[32:47]
	v_exp_f32_e32 v52, v52
	v_exp_f32_e32 v53, v53
	v_exp_f32_e32 v54, v54
	v_exp_f32_e32 v55, v55
	s_waitcnt lgkmcnt(10)
	v_mfma_f32_32x32x16_bf16 v[16:31], v[128:131], v[68:71], v[16:31]
	v_exp_f32_e32 v56, v56
	v_exp_f32_e32 v57, v57
	v_exp_f32_e32 v58, v58
	v_exp_f32_e32 v59, v59
	s_waitcnt lgkmcnt(8)
	v_mfma_f32_32x32x16_bf16 v[32:47], v[128:131], v[72:75], v[32:47]
	v_exp_f32_e32 v60, v60
	v_exp_f32_e32 v61, v61
	v_exp_f32_e32 v62, v62
	v_exp_f32_e32 v63, v63
	s_waitcnt vmcnt(0) lgkmcnt(0)
	s_barrier
	ds_read_b64_tr_b16 v[112:113], v168 offset:40960
	ds_read_b64_tr_b16 v[114:115], v168 offset:41472
	v_add_f32_e32 v64, v96, v97
	v_add_f32_e32 v64, v98, v64
	v_add_f32_e32 v64, v99, v64
	v_add_f32_e32 v64, v100, v64
	v_add_f32_e32 v84, v101, v64
	v_cvt_pk_bf16_f32 v140, v96, v97
	v_cvt_pk_bf16_f32 v141, v98, v99
	s_waitcnt lgkmcnt(9)
	v_mfma_f32_32x32x16_bf16 v[64:79], v[76:79], v[156:159], 0
	ds_read_b64_tr_b16 v[96:97], v168 offset:45056
	ds_read_b64_tr_b16 v[98:99], v168 offset:45568
	v_add_f32_e32 v84, v102, v84
	v_add_f32_e32 v84, v103, v84
	v_add_f32_e32 v84, v104, v84
	v_add_f32_e32 v121, v105, v84
	v_cvt_pk_bf16_f32 v142, v100, v101
	v_cvt_pk_bf16_f32 v143, v102, v103
	s_waitcnt lgkmcnt(10)
	v_mfma_f32_32x32x16_bf16 v[80:95], v[80:83], v[156:159], 0
	ds_read_b64_tr_b16 v[116:117], v168 offset:41984
	ds_read_b64_tr_b16 v[118:119], v168 offset:42496
	v_add_f32_e32 v100, v106, v121
	v_add_f32_e32 v100, v107, v100
	v_add_f32_e32 v100, v108, v100
	v_add_f32_e32 v121, v109, v100
	v_cvt_pk_bf16_f32 v136, v104, v105
	v_cvt_pk_bf16_f32 v137, v106, v107
	s_waitcnt lgkmcnt(11)
	v_mfma_f32_32x32x16_bf16 v[64:79], v[122:125], v[152:155], v[64:79]
	ds_read_b64_tr_b16 v[100:101], v168 offset:46080
	ds_read_b64_tr_b16 v[102:103], v168 offset:46592
	v_add_f32_e32 v104, v110, v121
	v_add_f32_e32 v104, v111, v104
	v_add_f32_e32 v104, v48, v104
	v_add_f32_e32 v121, v49, v104
	v_cvt_pk_bf16_f32 v138, v108, v109
	v_cvt_pk_bf16_f32 v139, v110, v111
	s_waitcnt lgkmcnt(12)
	v_mfma_f32_32x32x16_bf16 v[80:95], v[160:163], v[152:155], v[80:95]
	ds_read_b64_tr_b16 v[104:105], v168 offset:43008
	ds_read_b64_tr_b16 v[106:107], v168 offset:43520
	v_add_f32_e32 v108, v50, v121
	v_add_f32_e32 v108, v51, v108
	v_add_f32_e32 v108, v52, v108
	v_add_f32_e32 v108, v53, v108
	v_cvt_pk_bf16_f32 v132, v48, v49
	v_cvt_pk_bf16_f32 v133, v50, v51
	s_waitcnt lgkmcnt(13)
	v_mfma_f32_32x32x16_bf16 v[64:79], v[164:167], v[148:151], v[64:79]
	ds_read_b64_tr_b16 v[48:49], v168 offset:47104
	ds_read_b64_tr_b16 v[50:51], v168 offset:47616
	v_add_f32_e32 v108, v54, v108
	v_add_f32_e32 v108, v55, v108
	v_add_f32_e32 v108, v56, v108
	v_add_f32_e32 v121, v57, v108
	v_cvt_pk_bf16_f32 v134, v52, v53
	v_cvt_pk_bf16_f32 v135, v54, v55
	s_waitcnt lgkmcnt(14)
	v_mfma_f32_32x32x16_bf16 v[80:95], v[170:173], v[148:151], v[80:95]
	ds_read_b64_tr_b16 v[108:109], v168 offset:44032
	ds_read_b64_tr_b16 v[110:111], v168 offset:44544
	v_add_f32_e32 v52, v58, v121
	v_add_f32_e32 v52, v59, v52
	v_add_f32_e32 v52, v60, v52
	v_add_f32_e32 v121, v61, v52
	v_cvt_pk_bf16_f32 v128, v56, v57
	v_cvt_pk_bf16_f32 v129, v58, v59
	s_waitcnt lgkmcnt(14)
	v_mfma_f32_32x32x16_bf16 v[64:79], v[184:187], v[144:147], v[64:79]
	ds_read_b64_tr_b16 v[52:53], v168 offset:48128
	ds_read_b64_tr_b16 v[54:55], v168 offset:48640
	v_add_f32_e32 v56, v62, v121
	v_add_f32_e32 v56, v63, v56
	v_add_f32_e32 v56, 0, v56
	v_cvt_pk_bf16_f32 v130, v60, v61
	v_cvt_pk_bf16_f32 v131, v62, v63
	v_mfma_f32_32x32x16_bf16 v[80:95], v[188:191], v[144:147], v[80:95]
	s_nop 3
	v_exp_f32_e32 v64, v64
	v_exp_f32_e32 v65, v65
	v_exp_f32_e32 v66, v66
	v_exp_f32_e32 v67, v67
	s_nop 0
	v_exp_f32_e32 v68, v68
	v_exp_f32_e32 v69, v69
	v_exp_f32_e32 v70, v70
	v_exp_f32_e32 v71, v71
	s_nop 0
	v_exp_f32_e32 v72, v72
	v_exp_f32_e32 v73, v73
	v_exp_f32_e32 v74, v74
	v_exp_f32_e32 v75, v75
	s_nop 0
	v_exp_f32_e32 v76, v76
	v_exp_f32_e32 v77, v77
	v_exp_f32_e32 v78, v78
	v_exp_f32_e32 v79, v79
	v_exp_f32_e32 v80, v80
	v_exp_f32_e32 v81, v81
	v_exp_f32_e32 v82, v82
	v_exp_f32_e32 v83, v83
	s_nop 0
	v_exp_f32_e32 v84, v84
	v_exp_f32_e32 v85, v85
	v_exp_f32_e32 v86, v86
	v_exp_f32_e32 v87, v87
	s_nop 0
	v_exp_f32_e32 v88, v88
	v_exp_f32_e32 v89, v89
	v_exp_f32_e32 v90, v90
	v_exp_f32_e32 v91, v91
	s_nop 0
	v_exp_f32_e32 v92, v92
	v_exp_f32_e32 v93, v93
	v_exp_f32_e32 v94, v94
	v_exp_f32_e32 v95, v95
	s_waitcnt lgkmcnt(14)
; #define SBAR() __builtin_amdgcn_sched_barrier(0)
; __device__ __forceinline__ void pv(f32x16*o,int vb,bf16x8 pa0,bf16x8 pa1,bf16x8 pa2,bf16x8 pa3){
;   #pragma unroll
;   for(int d0=0;d0<2;++d0){s16x4 lo[4],hi[4];
;     #pragma unroll
;     for(int ks=0;ks<4;++ks){
;       asm volatile("ds_read_b64_tr_b16 %0,%1 offset:%c2":"=&v"(lo[ks]):"v"(vb),"i"(d0*4096+ks*1024):"memory");
;       asm volatile("ds_read_b64_tr_b16 %0,%1 offset:%c2":"=&v"(hi[ks]):"v"(vb),"i"(d0*4096+ks*1024+512):"memory");}
;     asm volatile("s_waitcnt lgkmcnt(0)":::"memory");SBAR();
;     ...
;     o[d0]=__builtin_amdgcn_mfma_f32_32x32x16_bf16(pa0,PK(0),o[d0],0,0,0);
;     o[d0]=__builtin_amdgcn_mfma_f32_32x32x16_bf16(pa1,PK(1),o[d0],0,0,0);
;     o[d0]=__builtin_amdgcn_mfma_f32_32x32x16_bf16(pa2,PK(2),o[d0],0,0,0);
;     o[d0]=__builtin_amdgcn_mfma_f32_32x32x16_bf16(pa3,PK(3),o[d0],0,0,0);
;     ...
;   }
; }
; template<int THRL,int VM,bool NOMAX> __device__ __forceinline__ void attn_unit(const bf16*Qb,const bf16*__restrict__ Kh,const bf16*__restrict__ Vh,bf16*Ob,const int NT,const int sp,float*wscr,char*shm){
;     ...
;   int t=1;
;   for(;t+5<NT;t+=2){
;     STEP(pB0,pB1,pA0,pA1,t,true,true,true);     if constexpr(VM==2){WAIT_BAR(3);}else{WAIT_BAR(2);} RESC(); ROT();
;     STEP(pA0,pA1,pB0,pB1,t+1,true,true,true);   if constexpr(VM==2){WAIT_BAR(3);}else{WAIT_BAR(2);} RESC(); ROT();
;   }
;     ...
;   for(;t+1<NT;t+=2){
;     STEP(pB0,pB1,pA0,pA1,t,(t+3<NT),(t+1<NT),(t+1<NT));       ENDW(t);   RESC(); ROT();
;     STEP(pA0,pA1,pB0,pB1,t+1,(t+4<NT),(t+2<NT),(t+2<NT));     ENDW(t+1); RESC(); ROT();
;   }
;   STEP(pB0,pB1,pA0,pA1,NT-1,false,false,false); RESC();
;   { float sacc=pB0[0]+pB0[1]; _Pragma("unroll") for(int r=2;r<16;++r)sacc+=pB0[r]; _Pragma("unroll") for(int r=0;r<16;++r)sacc+=pB1[r]; l_reg+=sacc;
;     pw0=(u32x4){PKW(pB0,0),PKW(pB0,2),PKW(pB0,4),PKW(pB0,6)};pw1=(u32x4){PKW(pB0,8),PKW(pB0,10),PKW(pB0,12),PKW(pB0,14)};pw2=(u32x4){PKW(pB1,0),PKW(pB1,2),PKW(pB1,4),PKW(pB1,6)};pw3=(u32x4){PKW(pB1,8),PKW(pB1,10),PKW(pB1,12),PKW(pB1,14)};
;     SBAR(); pv(o,vb0+VM*sl_cur,PAF(0),PAF(1),PAF(2),PAF(3)); if constexpr(VM==2) pv(o+2,vb0+VM*sl_cur+8192,PAF(0),PAF(1),PAF(2),PAF(3)); }
;     ...
;   {auto rr=__builtin_amdgcn_permlane32_swap(__float_as_uint(l_reg),__float_as_uint(l_reg),false,false);l_reg=__uint_as_float(rr[0])+__uint_as_float(rr[1]);}
;   if(hi==0)wsf[32+r32]=l_reg;asm volatile("s_waitcnt lgkmcnt(0)":::"memory");
	v_mfma_f32_32x32x16_bf16 v[16:31], v[140:143], v[112:115], v[16:31]
	v_add_f32_e32 v57, v64, v65
	v_add_f32_e32 v57, v66, v57
	v_add_f32_e32 v57, v67, v57
	v_add_f32_e32 v57, v68, v57
	v_add_f32_e32 v57, v69, v57
	v_add_f32_e32 v57, v70, v57
	v_add_f32_e32 v57, v71, v57
	s_waitcnt lgkmcnt(12)
	v_mfma_f32_32x32x16_bf16 v[32:47], v[140:143], v[96:99], v[32:47]
	v_add_f32_e32 v57, v72, v57
	v_add_f32_e32 v57, v73, v57
	v_add_f32_e32 v57, v74, v57
	v_add_f32_e32 v57, v75, v57
	v_add_f32_e32 v57, v76, v57
	v_add_f32_e32 v57, v77, v57
	v_add_f32_e32 v57, v78, v57
	s_waitcnt lgkmcnt(10)
	v_mfma_f32_32x32x16_bf16 v[16:31], v[136:139], v[116:119], v[16:31]
	v_add_f32_e32 v57, v79, v57
	v_add_f32_e32 v57, v80, v57
	v_add_f32_e32 v57, v81, v57
	v_add_f32_e32 v57, v82, v57
	v_add_f32_e32 v57, v83, v57
	v_add_f32_e32 v57, v84, v57
	v_add_f32_e32 v57, v85, v57
	s_waitcnt lgkmcnt(8)
	v_mfma_f32_32x32x16_bf16 v[32:47], v[136:139], v[100:103], v[32:47]
	v_add_f32_e32 v57, v86, v57
	v_add_f32_e32 v57, v87, v57
	v_add_f32_e32 v57, v88, v57
	v_add_f32_e32 v57, v89, v57
	v_add_f32_e32 v57, v90, v57
	v_add_f32_e32 v57, v91, v57
	v_add_f32_e32 v57, v92, v57
	s_waitcnt lgkmcnt(6)
	v_mfma_f32_32x32x16_bf16 v[16:31], v[132:135], v[104:107], v[16:31]
	v_add_f32_e32 v57, v93, v57
	v_add_f32_e32 v57, v94, v57
	v_add_f32_e32 v57, v95, v57
	v_add_f32_e32 v56, v120, v56
	v_add_f32_e32 v56, v56, v57
	v_cvt_pk_bf16_f32 v58, v64, v65
	v_cvt_pk_bf16_f32 v59, v66, v67
	s_waitcnt lgkmcnt(4)
	v_mfma_f32_32x32x16_bf16 v[32:47], v[132:135], v[48:51], v[32:47]
	v_cvt_pk_bf16_f32 v48, v80, v81
	v_cvt_pk_bf16_f32 v60, v68, v69
	v_cvt_pk_bf16_f32 v61, v70, v71
	v_cvt_pk_bf16_f32 v62, v72, v73
	v_cvt_pk_bf16_f32 v63, v74, v75
	v_cvt_pk_bf16_f32 v64, v76, v77
	v_cvt_pk_bf16_f32 v65, v78, v79
	s_waitcnt lgkmcnt(2)
	v_mfma_f32_32x32x16_bf16 v[16:31], v[128:131], v[108:111], v[16:31]
	v_cvt_pk_bf16_f32 v49, v82, v83
	v_cvt_pk_bf16_f32 v50, v84, v85
	v_cvt_pk_bf16_f32 v51, v86, v87
	v_cvt_pk_bf16_f32 v66, v88, v89
	v_cvt_pk_bf16_f32 v67, v90, v91
	v_cvt_pk_bf16_f32 v68, v92, v93
	v_cvt_pk_bf16_f32 v69, v94, v95
	s_waitcnt lgkmcnt(0)
	v_mfma_f32_32x32x16_bf16 v[32:47], v[128:131], v[52:55], v[32:47]
	ds_read_b64_tr_b16 v[52:53],v174 offset:0
	ds_read_b64_tr_b16 v[54:55],v174 offset:512
	ds_read_b64_tr_b16 v[70:71],v174 offset:1024
	ds_read_b64_tr_b16 v[72:73],v174 offset:1536
	ds_read_b64_tr_b16 v[74:75],v174 offset:2048
	ds_read_b64_tr_b16 v[76:77],v174 offset:2560
	ds_read_b64_tr_b16 v[78:79],v174 offset:3072
	ds_read_b64_tr_b16 v[80:81],v174 offset:3584
	s_waitcnt lgkmcnt(0)
	s_nop 0
	v_mfma_f32_32x32x16_bf16 v[16:31], v[58:61], v[52:55], v[16:31]
	ds_read_b64_tr_b16 v[52:53],v174 offset:4096
	ds_read_b64_tr_b16 v[54:55],v174 offset:4608
	v_mfma_f32_32x32x16_bf16 v[16:31], v[62:65], v[70:73], v[16:31]
	ds_read_b64_tr_b16 v[70:71],v174 offset:5120
	ds_read_b64_tr_b16 v[72:73],v174 offset:5632
	v_mfma_f32_32x32x16_bf16 v[16:31], v[48:51], v[74:77], v[16:31]
	ds_read_b64_tr_b16 v[74:75],v174 offset:6144
	ds_read_b64_tr_b16 v[76:77],v174 offset:6656
	ds_read_b64_tr_b16 v[82:83],v174 offset:7168
	ds_read_b64_tr_b16 v[84:85],v174 offset:7680
	s_waitcnt lgkmcnt(0)
	v_mfma_f32_32x32x16_bf16 v[16:31], v[66:69], v[78:81], v[16:31]
	v_mfma_f32_32x32x16_bf16 v[32:47], v[58:61], v[52:55], v[32:47]
	v_cmp_gt_u32_e32 vcc, 32, v178
	v_mfma_f32_32x32x16_bf16 v[32:47], v[62:65], v[70:73], v[32:47]
	v_mfma_f32_32x32x16_bf16 v[32:47], v[48:51], v[74:77], v[32:47]
	v_mov_b32_e32 v48, v56
	s_nop 1
	v_permlane32_swap_b32_e32 v56, v48
	v_mfma_f32_32x32x16_bf16 v[32:47], v[66:69], v[82:85], v[32:47]
	s_and_saveexec_b64 s[16:17], vcc
	s_cbranch_execz .LBB0_887
	v_add_f32_e32 v48, v56, v48
	v_lshl_add_u32 v49, v180, 2, s19
	ds_write_b32 v49, v48 offset:49280
	s_branch .LBB0_887
